# dsa_sparse: hand-written P.V fast path for nsel==256 (4 double-buffered batches of 16 row gathers in flight)
# speedup vs baseline: 1.0362x; 1.0075x over previous
.LBB0_1532:
	v_lshl_add_u32 v26, v86, 4, s67
	ds_read_b128 v[0:3], v26 offset:46336
	ds_read_b128 v[4:7], v26 offset:45312
	ds_read_b128 v[12:15], v26 offset:43264
	ds_read_b128 v[8:11], v26 offset:44288
	s_cmp_lt_i32 s79, 1
	s_waitcnt lgkmcnt(3)
	v_max_f32_e32 v16, v0, v0
	s_waitcnt lgkmcnt(2)
	v_max_f32_e32 v17, v4, v4
	v_max_f32_e32 v16, v17, v16
	s_waitcnt lgkmcnt(0)
	v_max3_f32 v16, v12, v8, v16
	ds_bpermute_b32 v17, v204, v16
	v_max_f32_e32 v18, v1, v1
	v_max_f32_e32 v19, v5, v5
	v_max_f32_e32 v18, v19, v18
	v_max3_f32 v18, v13, v9, v18
	s_waitcnt lgkmcnt(0)
	v_max_f32_e32 v17, v17, v17
	ds_bpermute_b32 v19, v204, v18
	v_max_f32_e32 v16, v16, v17
	ds_bpermute_b32 v17, v205, v16
	v_max_f32_e32 v20, v2, v2
	v_max_f32_e32 v21, v6, v6
	s_waitcnt lgkmcnt(1)
	v_max_f32_e32 v19, v19, v19
	v_max_f32_e32 v18, v18, v19
	s_waitcnt lgkmcnt(0)
	v_max_f32_e32 v17, v17, v17
	ds_bpermute_b32 v19, v205, v18
	v_max_f32_e32 v16, v16, v17
	ds_bpermute_b32 v17, v206, v16
	v_max_f32_e32 v20, v21, v20
	v_max3_f32 v20, v14, v10, v20
	s_waitcnt lgkmcnt(1)
	v_max_f32_e32 v19, v19, v19
	v_max_f32_e32 v18, v18, v19
	s_waitcnt lgkmcnt(0)
	v_max_f32_e32 v17, v17, v17
	ds_bpermute_b32 v19, v206, v18
	v_max_f32_e32 v16, v16, v17
	ds_bpermute_b32 v17, v207, v16
	ds_bpermute_b32 v21, v204, v20
	v_max_f32_e32 v22, v7, v7
	s_waitcnt lgkmcnt(2)
	v_max_f32_e32 v19, v19, v19
	v_max_f32_e32 v18, v18, v19
	s_waitcnt lgkmcnt(1)
	v_max_f32_e32 v17, v17, v17
	ds_bpermute_b32 v19, v207, v18
	v_max_f32_e32 v16, v16, v17
	ds_bpermute_b32 v17, v208, v16
	s_waitcnt lgkmcnt(2)
	v_max_f32_e32 v21, v21, v21
	v_max_f32_e32 v20, v20, v21
	s_waitcnt lgkmcnt(1)
	v_max_f32_e32 v19, v19, v19
	v_max_f32_e32 v18, v18, v19
	s_waitcnt lgkmcnt(0)
	v_max_f32_e32 v17, v17, v17
	ds_bpermute_b32 v19, v208, v18
	v_max_f32_e32 v16, v16, v17
	ds_bpermute_b32 v17, v209, v16
	ds_bpermute_b32 v21, v205, v20
	s_waitcnt lgkmcnt(2)
	v_max_f32_e32 v19, v19, v19
	v_max_f32_e32 v18, v18, v19
	s_waitcnt lgkmcnt(1)
	v_max_f32_e32 v17, v17, v17
	v_max_f32_e32 v16, v16, v17
	ds_bpermute_b32 v17, v209, v18
	v_sub_f32_e32 v12, v12, v16
	v_sub_f32_e32 v8, v8, v16
	v_sub_f32_e32 v4, v4, v16
	v_sub_f32_e32 v0, v0, v16
	s_waitcnt lgkmcnt(0)
	v_max_f32_e32 v16, v17, v17
	v_max_f32_e32 v16, v18, v16
	v_sub_f32_e32 v13, v13, v16
	v_mul_f32_e32 v12, 0x3fb8aa3b, v12
	v_mul_f32_e32 v13, 0x3fb8aa3b, v13
	v_sub_f32_e32 v9, v9, v16
	v_mul_f32_e32 v8, 0x3fb8aa3b, v8
	v_exp_f32_e32 v12, v12
	v_exp_f32_e32 v13, v13
	v_mul_f32_e32 v9, 0x3fb8aa3b, v9
	v_sub_f32_e32 v5, v5, v16
	v_mul_f32_e32 v4, 0x3fb8aa3b, v4
	v_exp_f32_e32 v8, v8
	v_exp_f32_e32 v9, v9
	v_mul_f32_e32 v5, 0x3fb8aa3b, v5
	v_sub_f32_e32 v1, v1, v16
	v_exp_f32_e32 v4, v4
	v_mul_f32_e32 v0, 0x3fb8aa3b, v0
	v_exp_f32_e32 v5, v5
	v_mul_f32_e32 v1, 0x3fb8aa3b, v1
	v_exp_f32_e32 v0, v0
	v_exp_f32_e32 v1, v1
	v_pk_add_f32 v[16:17], v[12:13], 0 op_sel_hi:[1,0]
	v_max_f32_e32 v21, v21, v21
	v_pk_add_f32 v[16:17], v[8:9], v[16:17]
	v_max_f32_e32 v20, v20, v21
	v_pk_add_f32 v[16:17], v[4:5], v[16:17]
	ds_bpermute_b32 v21, v206, v20
	v_pk_add_f32 v[16:17], v[0:1], v[16:17]
	ds_bpermute_b32 v18, v204, v16
	ds_bpermute_b32 v19, v204, v17
	s_waitcnt lgkmcnt(0)
	v_pk_add_f32 v[16:17], v[16:17], v[18:19]
	ds_bpermute_b32 v18, v205, v16
	ds_bpermute_b32 v19, v205, v17
	s_waitcnt lgkmcnt(0)
	v_pk_add_f32 v[16:17], v[16:17], v[18:19]
	ds_bpermute_b32 v18, v206, v16
	ds_bpermute_b32 v19, v206, v17
	s_waitcnt lgkmcnt(0)
	v_pk_add_f32 v[16:17], v[16:17], v[18:19]
	ds_bpermute_b32 v18, v207, v16
	ds_bpermute_b32 v19, v207, v17
	s_waitcnt lgkmcnt(0)
	v_pk_add_f32 v[16:17], v[16:17], v[18:19]
	ds_bpermute_b32 v18, v208, v16
	ds_bpermute_b32 v19, v208, v17
	s_waitcnt lgkmcnt(0)
	v_pk_add_f32 v[16:17], v[16:17], v[18:19]
	v_max_f32_e32 v19, v21, v21
	v_max_f32_e32 v20, v20, v19
	v_max_f32_e32 v19, v3, v3
	v_max_f32_e32 v19, v22, v19
	ds_bpermute_b32 v21, v207, v20
	v_max3_f32 v22, v15, v11, v19
	ds_bpermute_b32 v23, v204, v22
	ds_bpermute_b32 v18, v209, v16
	ds_bpermute_b32 v19, v209, v17
	s_waitcnt lgkmcnt(3)
	v_max_f32_e32 v21, v21, v21
	v_max_f32_e32 v20, v20, v21
	s_waitcnt lgkmcnt(2)
	v_max_f32_e32 v23, v23, v23
	ds_bpermute_b32 v21, v208, v20
	v_max_f32_e32 v22, v22, v23
	ds_bpermute_b32 v23, v205, v22
	s_waitcnt lgkmcnt(2)
	v_pk_add_f32 v[16:17], v[16:17], v[18:19]
	s_waitcnt lgkmcnt(1)
	v_max_f32_e32 v18, v21, v21
	v_max_f32_e32 v18, v20, v18
	s_waitcnt lgkmcnt(0)
	v_max_f32_e32 v20, v23, v23
	ds_bpermute_b32 v19, v209, v18
	v_max_f32_e32 v20, v22, v20
	ds_bpermute_b32 v21, v206, v20
	v_div_scale_f32 v24, s[0:1], v17, v17, 1.0
	s_waitcnt lgkmcnt(1)
	v_max_f32_e32 v19, v19, v19
	v_max_f32_e32 v19, v18, v19
	s_waitcnt lgkmcnt(0)
	v_max_f32_e32 v18, v21, v21
	v_max_f32_e32 v18, v20, v18
	ds_bpermute_b32 v20, v207, v18
	v_sub_f32_e32 v10, v10, v19
	v_mul_f32_e32 v10, 0x3fb8aa3b, v10
	v_sub_f32_e32 v2, v2, v19
	v_mul_f32_e32 v2, 0x3fb8aa3b, v2
	s_waitcnt lgkmcnt(0)
	v_max_f32_e32 v20, v20, v20
	v_max_f32_e32 v20, v18, v20
	ds_bpermute_b32 v21, v208, v20
	v_exp_f32_e32 v18, v10
	v_sub_f32_e32 v6, v6, v19
	v_exp_f32_e32 v22, v2
	v_mul_f32_e32 v6, 0x3fb8aa3b, v6
	s_waitcnt lgkmcnt(0)
	v_max_f32_e32 v10, v21, v21
	v_max_f32_e32 v10, v20, v10
	ds_bpermute_b32 v21, v209, v10
	v_exp_f32_e32 v20, v6
	v_sub_f32_e32 v14, v14, v19
	v_mul_f32_e32 v14, 0x3fb8aa3b, v14
	v_exp_f32_e32 v14, v14
	s_waitcnt lgkmcnt(0)
	v_max_f32_e32 v2, v21, v21
	v_max_f32_e32 v2, v10, v2
	v_sub_f32_e32 v6, v15, v2
	v_mul_f32_e32 v6, 0x3fb8aa3b, v6
	v_exp_f32_e32 v15, v6
	v_sub_f32_e32 v6, v11, v2
	v_mul_f32_e32 v6, 0x3fb8aa3b, v6
	v_exp_f32_e32 v19, v6
	v_sub_f32_e32 v6, v7, v2
	v_mul_f32_e32 v6, 0x3fb8aa3b, v6
	v_sub_f32_e32 v2, v3, v2
	v_exp_f32_e32 v21, v6
	v_mul_f32_e32 v2, 0x3fb8aa3b, v2
	v_exp_f32_e32 v23, v2
	v_pk_add_f32 v[2:3], v[14:15], 0 op_sel_hi:[1,0]
	v_rcp_f32_e32 v25, v24
	v_pk_add_f32 v[2:3], v[18:19], v[2:3]
	v_fma_f32 v10, -v24, v25, 1.0
	v_pk_add_f32 v[2:3], v[20:21], v[2:3]
	v_fmac_f32_e32 v25, v10, v25
	v_pk_add_f32 v[2:3], v[22:23], v[2:3]
	ds_bpermute_b32 v6, v204, v2
	ds_bpermute_b32 v7, v204, v3
	v_div_scale_f32 v10, vcc, 1.0, v17, 1.0
	v_mul_f32_e32 v11, v10, v25
	v_fma_f32 v27, -v24, v11, v10
	s_waitcnt lgkmcnt(0)
	v_pk_add_f32 v[2:3], v[2:3], v[6:7]
	ds_bpermute_b32 v6, v205, v2
	ds_bpermute_b32 v7, v205, v3
	v_fmac_f32_e32 v11, v27, v25
	v_fma_f32 v10, -v24, v11, v10
	v_div_fmas_f32 v10, v10, v25, v11
	v_div_fixup_f32 v17, v10, v17, 1.0
	s_waitcnt lgkmcnt(0)
	v_pk_add_f32 v[2:3], v[2:3], v[6:7]
	ds_bpermute_b32 v6, v206, v2
	ds_bpermute_b32 v7, v206, v3
	v_div_scale_f32 v10, s[0:1], v16, v16, 1.0
	v_rcp_f32_e32 v11, v10
	s_waitcnt lgkmcnt(0)
	v_pk_add_f32 v[2:3], v[2:3], v[6:7]
	ds_bpermute_b32 v6, v207, v2
	ds_bpermute_b32 v7, v207, v3
	v_fma_f32 v24, -v10, v11, 1.0
	v_fmac_f32_e32 v11, v24, v11
	v_div_scale_f32 v24, vcc, 1.0, v16, 1.0
	s_waitcnt lgkmcnt(0)
	v_pk_add_f32 v[2:3], v[2:3], v[6:7]
	ds_bpermute_b32 v6, v208, v2
	ds_bpermute_b32 v7, v208, v3
	v_mul_f32_e32 v25, v24, v11
	v_fma_f32 v27, -v10, v25, v24
	v_fmac_f32_e32 v25, v27, v11
	v_fma_f32 v10, -v10, v25, v24
	s_waitcnt lgkmcnt(0)
	v_pk_add_f32 v[2:3], v[2:3], v[6:7]
	ds_bpermute_b32 v6, v209, v2
	ds_bpermute_b32 v7, v209, v3
	v_div_fmas_f32 v10, v10, v11, v25
	v_div_fixup_f32 v16, v10, v16, 1.0
	v_pk_mul_f32 v[0:1], v[0:1], v[16:17]
	s_waitcnt lgkmcnt(0)
	v_pk_add_f32 v[2:3], v[2:3], v[6:7]
	s_nop 0
	v_div_scale_f32 v6, s[0:1], v3, v3, 1.0
	v_rcp_f32_e32 v7, v6
	s_nop 0
	v_fma_f32 v10, -v6, v7, 1.0
	v_fmac_f32_e32 v7, v10, v7
	v_div_scale_f32 v10, vcc, 1.0, v3, 1.0
	v_mul_f32_e32 v11, v10, v7
	v_fma_f32 v24, -v6, v11, v10
	v_fmac_f32_e32 v11, v24, v7
	v_fma_f32 v6, -v6, v11, v10
	v_div_scale_f32 v10, s[0:1], v2, v2, 1.0
	v_rcp_f32_e32 v24, v10
	v_div_fmas_f32 v6, v6, v7, v11
	v_div_fixup_f32 v25, v6, v3, 1.0
	v_fma_f32 v3, -v10, v24, 1.0
	v_fmac_f32_e32 v24, v3, v24
	v_div_scale_f32 v3, vcc, 1.0, v2, 1.0
	v_mul_f32_e32 v6, v3, v24
	v_fma_f32 v7, -v10, v6, v3
	v_fmac_f32_e32 v6, v7, v24
	v_fma_f32 v3, -v10, v6, v3
	v_div_fmas_f32 v3, v3, v24, v6
	v_div_fixup_f32 v24, v3, v2, 1.0
	v_pk_mul_f32 v[2:3], v[4:5], v[16:17]
	v_pk_mul_f32 v[4:5], v[20:21], v[24:25]
	ds_write_b128 v26, v[2:5] offset:45312
	v_pk_mul_f32 v[2:3], v[22:23], v[24:25]
	ds_write_b128 v26, v[0:3] offset:46336
	v_lshlrev_b32_e32 v0, 3, v56
	v_pk_mul_f32 v[10:11], v[12:13], v[16:17]
	v_pk_mul_f32 v[12:13], v[14:15], v[24:25]
	v_pk_mul_f32 v[6:7], v[8:9], v[16:17]
	v_pk_mul_f32 v[8:9], v[18:19], v[24:25]
	v_lshlrev_b32_e32 v102, 1, v0
	ds_write_b128 v26, v[10:13] offset:43264
	ds_write_b128 v26, v[6:9] offset:44288
	s_cbranch_scc1 .LBB0_1535
	s_lshl_b64 s[0:1], s[42:43], 9
	s_add_u32 s0, s69, s0
	s_addc_u32 s1, s70, s1
	v_mov_b32_e32 v15, 0
	v_lshl_add_u64 v[28:29], s[0:1], 0, v[102:103]
	s_mov_b32 s21, 0
	v_mov_b32_e32 v14, v15
	v_mov_b32_e32 v19, v15
	v_mov_b32_e32 v18, v15
	v_mov_b32_e32 v21, v15
	v_mov_b32_e32 v20, v15
	v_mov_b32_e32 v23, v15
	v_mov_b32_e32 v22, v15
	v_mov_b32_e32 v25, v15
	v_mov_b32_e32 v24, v15
	v_mov_b32_e32 v27, v15
	v_mov_b32_e32 v26, v15
	v_mov_b32_e32 v31, v15
	v_mov_b32_e32 v30, v15
	v_mov_b32_e32 v33, v15
	v_mov_b32_e32 v32, v15
	v_mov_b32_e32 v16, v15
	v_mov_b32_e32 v17, v15
	v_mov_b32_e32 v12, v15
	v_mov_b32_e32 v13, v15
	v_mov_b32_e32 v10, v15
	v_mov_b32_e32 v11, v15
	v_mov_b32_e32 v6, v15
	v_mov_b32_e32 v7, v15
	v_mov_b32_e32 v8, v15
	v_mov_b32_e32 v9, v15
	v_mov_b32_e32 v4, v15
	v_mov_b32_e32 v5, v15
	v_mov_b32_e32 v2, v15
	v_mov_b32_e32 v3, v15
	v_mov_b32_e32 v0, v15
	v_mov_b32_e32 v1, v15
	s_cmpk_eq_i32 s78, 0x100
	s_cbranch_scc1 .Lpv_fast

.Lpv_fast:
	v_lshl_add_u32 v56, v55, 2, s66
	v_lshl_add_u32 v112, v55, 4, s67
	ds_read_b32 v34, v56 offset:6400
	ds_read_b32 v35, v56 offset:6416
	ds_read_b32 v36, v56 offset:6432
	ds_read_b32 v37, v56 offset:6448
	ds_read_b32 v38, v56 offset:6464
	ds_read_b32 v39, v56 offset:6480
	ds_read_b32 v40, v56 offset:6496
	ds_read_b32 v41, v56 offset:6512
	ds_read_b32 v42, v56 offset:6528
	ds_read_b32 v43, v56 offset:6544
	ds_read_b32 v44, v56 offset:6560
	ds_read_b32 v45, v56 offset:6576
	ds_read_b32 v46, v56 offset:6592
	ds_read_b32 v47, v56 offset:6608
	ds_read_b32 v48, v56 offset:6624
	ds_read_b32 v49, v56 offset:6640
	s_waitcnt lgkmcnt(15)
	v_lshl_add_u32 v34, v34, 9, v102
	global_load_dwordx4 v[130:133], v34, s[0:1]
	s_waitcnt lgkmcnt(14)
	v_lshl_add_u32 v35, v35, 9, v102
	global_load_dwordx4 v[134:137], v35, s[0:1]
	s_waitcnt lgkmcnt(13)
	v_lshl_add_u32 v36, v36, 9, v102
	global_load_dwordx4 v[138:141], v36, s[0:1]
	s_waitcnt lgkmcnt(12)
	v_lshl_add_u32 v37, v37, 9, v102
	global_load_dwordx4 v[142:145], v37, s[0:1]
	s_waitcnt lgkmcnt(11)
	v_lshl_add_u32 v38, v38, 9, v102
	global_load_dwordx4 v[146:149], v38, s[0:1]
	s_waitcnt lgkmcnt(10)
	v_lshl_add_u32 v39, v39, 9, v102
	global_load_dwordx4 v[150:153], v39, s[0:1]
	s_waitcnt lgkmcnt(9)
	v_lshl_add_u32 v40, v40, 9, v102
	global_load_dwordx4 v[154:157], v40, s[0:1]
	s_waitcnt lgkmcnt(8)
	v_lshl_add_u32 v41, v41, 9, v102
	global_load_dwordx4 v[158:161], v41, s[0:1]
	s_waitcnt lgkmcnt(7)
	v_lshl_add_u32 v42, v42, 9, v102
	global_load_dwordx4 v[162:165], v42, s[0:1]
	s_waitcnt lgkmcnt(6)
	v_lshl_add_u32 v43, v43, 9, v102
	global_load_dwordx4 v[166:169], v43, s[0:1]
	s_waitcnt lgkmcnt(5)
	v_lshl_add_u32 v44, v44, 9, v102
	global_load_dwordx4 v[170:173], v44, s[0:1]
	s_waitcnt lgkmcnt(4)
	v_lshl_add_u32 v45, v45, 9, v102
	global_load_dwordx4 v[174:177], v45, s[0:1]
	s_waitcnt lgkmcnt(3)
	v_lshl_add_u32 v46, v46, 9, v102
	global_load_dwordx4 v[178:181], v46, s[0:1]
	s_waitcnt lgkmcnt(2)
	v_lshl_add_u32 v47, v47, 9, v102
	global_load_dwordx4 v[182:185], v47, s[0:1]
	s_waitcnt lgkmcnt(1)
	v_lshl_add_u32 v48, v48, 9, v102
	global_load_dwordx4 v[186:189], v48, s[0:1]
	s_waitcnt lgkmcnt(0)
	v_lshl_add_u32 v49, v49, 9, v102
	global_load_dwordx4 v[190:193], v49, s[0:1]
	ds_read_b32 v34, v56 offset:6656
	ds_read_b32 v35, v56 offset:6672
	ds_read_b32 v36, v56 offset:6688
	ds_read_b32 v37, v56 offset:6704
	ds_read_b32 v38, v56 offset:6720
	ds_read_b32 v39, v56 offset:6736
	ds_read_b32 v40, v56 offset:6752
	ds_read_b32 v41, v56 offset:6768
	ds_read_b32 v42, v56 offset:6784
	ds_read_b32 v43, v56 offset:6800
	ds_read_b32 v44, v56 offset:6816
	ds_read_b32 v45, v56 offset:6832
	ds_read_b32 v46, v56 offset:6848
	ds_read_b32 v47, v56 offset:6864
	ds_read_b32 v48, v56 offset:6880
	ds_read_b32 v49, v56 offset:6896
	s_waitcnt lgkmcnt(15)
	v_lshl_add_u32 v34, v34, 9, v102
	global_load_dwordx4 v[210:213], v34, s[0:1]
	s_waitcnt lgkmcnt(14)
	v_lshl_add_u32 v35, v35, 9, v102
	global_load_dwordx4 v[214:217], v35, s[0:1]
	s_waitcnt lgkmcnt(13)
	v_lshl_add_u32 v36, v36, 9, v102
	global_load_dwordx4 v[218:221], v36, s[0:1]
	s_waitcnt lgkmcnt(12)
	v_lshl_add_u32 v37, v37, 9, v102
	global_load_dwordx4 v[222:225], v37, s[0:1]
	s_waitcnt lgkmcnt(11)
	v_lshl_add_u32 v38, v38, 9, v102
	global_load_dwordx4 v[226:229], v38, s[0:1]
	s_waitcnt lgkmcnt(10)
	v_lshl_add_u32 v39, v39, 9, v102
	global_load_dwordx4 v[230:233], v39, s[0:1]
	s_waitcnt lgkmcnt(9)
	v_lshl_add_u32 v40, v40, 9, v102
	global_load_dwordx4 v[234:237], v40, s[0:1]
	s_waitcnt lgkmcnt(8)
	v_lshl_add_u32 v41, v41, 9, v102
	global_load_dwordx4 v[238:241], v41, s[0:1]
	s_waitcnt lgkmcnt(7)
	v_lshl_add_u32 v42, v42, 9, v102
	global_load_dwordx4 v[70:73], v42, s[0:1]
	s_waitcnt lgkmcnt(6)
	v_lshl_add_u32 v43, v43, 9, v102
	global_load_dwordx4 v[74:77], v43, s[0:1]
	s_waitcnt lgkmcnt(5)
	v_lshl_add_u32 v44, v44, 9, v102
	global_load_dwordx4 v[78:81], v44, s[0:1]
	s_waitcnt lgkmcnt(4)
	v_lshl_add_u32 v45, v45, 9, v102
	global_load_dwordx4 v[82:85], v45, s[0:1]
	s_waitcnt lgkmcnt(3)
	v_lshl_add_u32 v46, v46, 9, v102
	global_load_dwordx4 v[86:89], v46, s[0:1]
	s_waitcnt lgkmcnt(2)
	v_lshl_add_u32 v47, v47, 9, v102
	global_load_dwordx4 v[90:93], v47, s[0:1]
	s_waitcnt lgkmcnt(1)
	v_lshl_add_u32 v48, v48, 9, v102
	global_load_dwordx4 v[94:97], v48, s[0:1]
	s_waitcnt lgkmcnt(0)
	v_lshl_add_u32 v49, v49, 9, v102
	global_load_dwordx4 v[98:101], v49, s[0:1]
	ds_read_b128 v[248:251], v112 offset:43264
	ds_read_b128 v[252:255], v112 offset:43328
	s_waitcnt vmcnt(31)
	v_lshlrev_b32_e32 v108, 16, v130
	v_and_b32_e32 v109, 0xffff0000, v130
	v_lshlrev_b32_e32 v246, 16, v131
	v_and_b32_e32 v247, 0xffff0000, v131
	v_lshlrev_b32_e32 v130, 16, v132
	v_and_b32_e32 v131, 0xffff0000, v132
	v_lshlrev_b32_e32 v132, 16, v133
	v_and_b32_e32 v133, 0xffff0000, v133
	s_waitcnt lgkmcnt(1)
	v_pk_fma_f32 v[8:9], v[250:251], v[108:109], v[8:9] op_sel:[1,0,0] op_sel_hi:[1,1,1]
	v_pk_fma_f32 v[32:33], v[248:249], v[108:109], v[32:33] op_sel_hi:[0,1,1]
	v_pk_fma_f32 v[22:23], v[248:249], v[108:109], v[22:23] op_sel:[1,0,0] op_sel_hi:[1,1,1]
	v_pk_fma_f32 v[16:17], v[250:251], v[108:109], v[16:17] op_sel_hi:[0,1,1]
	v_pk_fma_f32 v[4:5], v[250:251], v[246:247], v[4:5] op_sel:[1,0,0] op_sel_hi:[1,1,1]
	v_pk_fma_f32 v[30:31], v[248:249], v[246:247], v[30:31] op_sel_hi:[0,1,1]
	v_pk_fma_f32 v[20:21], v[248:249], v[246:247], v[20:21] op_sel:[1,0,0] op_sel_hi:[1,1,1]
	v_pk_fma_f32 v[12:13], v[250:251], v[246:247], v[12:13] op_sel_hi:[0,1,1]
	v_pk_fma_f32 v[2:3], v[250:251], v[130:131], v[2:3] op_sel:[1,0,0] op_sel_hi:[1,1,1]
	v_pk_fma_f32 v[26:27], v[248:249], v[130:131], v[26:27] op_sel_hi:[0,1,1]
	v_pk_fma_f32 v[18:19], v[248:249], v[130:131], v[18:19] op_sel:[1,0,0] op_sel_hi:[1,1,1]
	v_pk_fma_f32 v[10:11], v[250:251], v[130:131], v[10:11] op_sel_hi:[0,1,1]
	v_pk_fma_f32 v[0:1], v[250:251], v[132:133], v[0:1] op_sel:[1,0,0] op_sel_hi:[1,1,1]
	v_pk_fma_f32 v[24:25], v[248:249], v[132:133], v[24:25] op_sel_hi:[0,1,1]
	v_pk_fma_f32 v[14:15], v[248:249], v[132:133], v[14:15] op_sel:[1,0,0] op_sel_hi:[1,1,1]
	v_pk_fma_f32 v[6:7], v[250:251], v[132:133], v[6:7] op_sel_hi:[0,1,1]
	ds_read_b128 v[248:251], v112 offset:43392
	s_waitcnt vmcnt(30)
	v_lshlrev_b32_e32 v108, 16, v134
	v_and_b32_e32 v109, 0xffff0000, v134
	v_lshlrev_b32_e32 v246, 16, v135
	v_and_b32_e32 v247, 0xffff0000, v135
	v_lshlrev_b32_e32 v134, 16, v136
	v_and_b32_e32 v135, 0xffff0000, v136
	v_lshlrev_b32_e32 v136, 16, v137
	v_and_b32_e32 v137, 0xffff0000, v137
	s_waitcnt lgkmcnt(1)
	v_pk_fma_f32 v[8:9], v[254:255], v[108:109], v[8:9] op_sel:[1,0,0] op_sel_hi:[1,1,1]
	v_pk_fma_f32 v[32:33], v[252:253], v[108:109], v[32:33] op_sel_hi:[0,1,1]
	v_pk_fma_f32 v[22:23], v[252:253], v[108:109], v[22:23] op_sel:[1,0,0] op_sel_hi:[1,1,1]
	v_pk_fma_f32 v[16:17], v[254:255], v[108:109], v[16:17] op_sel_hi:[0,1,1]
	v_pk_fma_f32 v[4:5], v[254:255], v[246:247], v[4:5] op_sel:[1,0,0] op_sel_hi:[1,1,1]
	v_pk_fma_f32 v[30:31], v[252:253], v[246:247], v[30:31] op_sel_hi:[0,1,1]
	v_pk_fma_f32 v[20:21], v[252:253], v[246:247], v[20:21] op_sel:[1,0,0] op_sel_hi:[1,1,1]
	v_pk_fma_f32 v[12:13], v[254:255], v[246:247], v[12:13] op_sel_hi:[0,1,1]
	v_pk_fma_f32 v[2:3], v[254:255], v[134:135], v[2:3] op_sel:[1,0,0] op_sel_hi:[1,1,1]
	v_pk_fma_f32 v[26:27], v[252:253], v[134:135], v[26:27] op_sel_hi:[0,1,1]
	v_pk_fma_f32 v[18:19], v[252:253], v[134:135], v[18:19] op_sel:[1,0,0] op_sel_hi:[1,1,1]
	v_pk_fma_f32 v[10:11], v[254:255], v[134:135], v[10:11] op_sel_hi:[0,1,1]
	v_pk_fma_f32 v[0:1], v[254:255], v[136:137], v[0:1] op_sel:[1,0,0] op_sel_hi:[1,1,1]
	v_pk_fma_f32 v[24:25], v[252:253], v[136:137], v[24:25] op_sel_hi:[0,1,1]
	v_pk_fma_f32 v[14:15], v[252:253], v[136:137], v[14:15] op_sel:[1,0,0] op_sel_hi:[1,1,1]
	v_pk_fma_f32 v[6:7], v[254:255], v[136:137], v[6:7] op_sel_hi:[0,1,1]
	ds_read_b128 v[252:255], v112 offset:43456
	s_waitcnt vmcnt(29)
	v_lshlrev_b32_e32 v108, 16, v138
	v_and_b32_e32 v109, 0xffff0000, v138
	v_lshlrev_b32_e32 v246, 16, v139
	v_and_b32_e32 v247, 0xffff0000, v139
	v_lshlrev_b32_e32 v138, 16, v140
	v_and_b32_e32 v139, 0xffff0000, v140
	v_lshlrev_b32_e32 v140, 16, v141
	v_and_b32_e32 v141, 0xffff0000, v141
	s_waitcnt lgkmcnt(1)
	v_pk_fma_f32 v[8:9], v[250:251], v[108:109], v[8:9] op_sel:[1,0,0] op_sel_hi:[1,1,1]
	v_pk_fma_f32 v[32:33], v[248:249], v[108:109], v[32:33] op_sel_hi:[0,1,1]
	v_pk_fma_f32 v[22:23], v[248:249], v[108:109], v[22:23] op_sel:[1,0,0] op_sel_hi:[1,1,1]
	v_pk_fma_f32 v[16:17], v[250:251], v[108:109], v[16:17] op_sel_hi:[0,1,1]
	v_pk_fma_f32 v[4:5], v[250:251], v[246:247], v[4:5] op_sel:[1,0,0] op_sel_hi:[1,1,1]
	v_pk_fma_f32 v[30:31], v[248:249], v[246:247], v[30:31] op_sel_hi:[0,1,1]
	v_pk_fma_f32 v[20:21], v[248:249], v[246:247], v[20:21] op_sel:[1,0,0] op_sel_hi:[1,1,1]
	v_pk_fma_f32 v[12:13], v[250:251], v[246:247], v[12:13] op_sel_hi:[0,1,1]
	v_pk_fma_f32 v[2:3], v[250:251], v[138:139], v[2:3] op_sel:[1,0,0] op_sel_hi:[1,1,1]
	v_pk_fma_f32 v[26:27], v[248:249], v[138:139], v[26:27] op_sel_hi:[0,1,1]
	v_pk_fma_f32 v[18:19], v[248:249], v[138:139], v[18:19] op_sel:[1,0,0] op_sel_hi:[1,1,1]
	v_pk_fma_f32 v[10:11], v[250:251], v[138:139], v[10:11] op_sel_hi:[0,1,1]
	v_pk_fma_f32 v[0:1], v[250:251], v[140:141], v[0:1] op_sel:[1,0,0] op_sel_hi:[1,1,1]
	v_pk_fma_f32 v[24:25], v[248:249], v[140:141], v[24:25] op_sel_hi:[0,1,1]
	v_pk_fma_f32 v[14:15], v[248:249], v[140:141], v[14:15] op_sel:[1,0,0] op_sel_hi:[1,1,1]
	v_pk_fma_f32 v[6:7], v[250:251], v[140:141], v[6:7] op_sel_hi:[0,1,1]
	ds_read_b128 v[248:251], v112 offset:43520
	s_waitcnt vmcnt(28)
	v_lshlrev_b32_e32 v108, 16, v142
	v_and_b32_e32 v109, 0xffff0000, v142
	v_lshlrev_b32_e32 v246, 16, v143
	v_and_b32_e32 v247, 0xffff0000, v143
	v_lshlrev_b32_e32 v142, 16, v144
	v_and_b32_e32 v143, 0xffff0000, v144
	v_lshlrev_b32_e32 v144, 16, v145
	v_and_b32_e32 v145, 0xffff0000, v145
	s_waitcnt lgkmcnt(1)
	v_pk_fma_f32 v[8:9], v[254:255], v[108:109], v[8:9] op_sel:[1,0,0] op_sel_hi:[1,1,1]
	v_pk_fma_f32 v[32:33], v[252:253], v[108:109], v[32:33] op_sel_hi:[0,1,1]
	v_pk_fma_f32 v[22:23], v[252:253], v[108:109], v[22:23] op_sel:[1,0,0] op_sel_hi:[1,1,1]
	v_pk_fma_f32 v[16:17], v[254:255], v[108:109], v[16:17] op_sel_hi:[0,1,1]
	v_pk_fma_f32 v[4:5], v[254:255], v[246:247], v[4:5] op_sel:[1,0,0] op_sel_hi:[1,1,1]
	v_pk_fma_f32 v[30:31], v[252:253], v[246:247], v[30:31] op_sel_hi:[0,1,1]
	v_pk_fma_f32 v[20:21], v[252:253], v[246:247], v[20:21] op_sel:[1,0,0] op_sel_hi:[1,1,1]
	v_pk_fma_f32 v[12:13], v[254:255], v[246:247], v[12:13] op_sel_hi:[0,1,1]
	v_pk_fma_f32 v[2:3], v[254:255], v[142:143], v[2:3] op_sel:[1,0,0] op_sel_hi:[1,1,1]
	v_pk_fma_f32 v[26:27], v[252:253], v[142:143], v[26:27] op_sel_hi:[0,1,1]
	v_pk_fma_f32 v[18:19], v[252:253], v[142:143], v[18:19] op_sel:[1,0,0] op_sel_hi:[1,1,1]
	v_pk_fma_f32 v[10:11], v[254:255], v[142:143], v[10:11] op_sel_hi:[0,1,1]
	v_pk_fma_f32 v[0:1], v[254:255], v[144:145], v[0:1] op_sel:[1,0,0] op_sel_hi:[1,1,1]
	v_pk_fma_f32 v[24:25], v[252:253], v[144:145], v[24:25] op_sel_hi:[0,1,1]
	v_pk_fma_f32 v[14:15], v[252:253], v[144:145], v[14:15] op_sel:[1,0,0] op_sel_hi:[1,1,1]
	v_pk_fma_f32 v[6:7], v[254:255], v[144:145], v[6:7] op_sel_hi:[0,1,1]
	ds_read_b128 v[252:255], v112 offset:43584
	s_waitcnt vmcnt(27)
	v_lshlrev_b32_e32 v108, 16, v146
	v_and_b32_e32 v109, 0xffff0000, v146
	v_lshlrev_b32_e32 v246, 16, v147
	v_and_b32_e32 v247, 0xffff0000, v147
	v_lshlrev_b32_e32 v146, 16, v148
	v_and_b32_e32 v147, 0xffff0000, v148
	v_lshlrev_b32_e32 v148, 16, v149
	v_and_b32_e32 v149, 0xffff0000, v149
	s_waitcnt lgkmcnt(1)
	v_pk_fma_f32 v[8:9], v[250:251], v[108:109], v[8:9] op_sel:[1,0,0] op_sel_hi:[1,1,1]
	v_pk_fma_f32 v[32:33], v[248:249], v[108:109], v[32:33] op_sel_hi:[0,1,1]
	v_pk_fma_f32 v[22:23], v[248:249], v[108:109], v[22:23] op_sel:[1,0,0] op_sel_hi:[1,1,1]
	v_pk_fma_f32 v[16:17], v[250:251], v[108:109], v[16:17] op_sel_hi:[0,1,1]
	v_pk_fma_f32 v[4:5], v[250:251], v[246:247], v[4:5] op_sel:[1,0,0] op_sel_hi:[1,1,1]
	v_pk_fma_f32 v[30:31], v[248:249], v[246:247], v[30:31] op_sel_hi:[0,1,1]
	v_pk_fma_f32 v[20:21], v[248:249], v[246:247], v[20:21] op_sel:[1,0,0] op_sel_hi:[1,1,1]
	v_pk_fma_f32 v[12:13], v[250:251], v[246:247], v[12:13] op_sel_hi:[0,1,1]
	v_pk_fma_f32 v[2:3], v[250:251], v[146:147], v[2:3] op_sel:[1,0,0] op_sel_hi:[1,1,1]
	v_pk_fma_f32 v[26:27], v[248:249], v[146:147], v[26:27] op_sel_hi:[0,1,1]
	v_pk_fma_f32 v[18:19], v[248:249], v[146:147], v[18:19] op_sel:[1,0,0] op_sel_hi:[1,1,1]
	v_pk_fma_f32 v[10:11], v[250:251], v[146:147], v[10:11] op_sel_hi:[0,1,1]
	v_pk_fma_f32 v[0:1], v[250:251], v[148:149], v[0:1] op_sel:[1,0,0] op_sel_hi:[1,1,1]
	v_pk_fma_f32 v[24:25], v[248:249], v[148:149], v[24:25] op_sel_hi:[0,1,1]
	v_pk_fma_f32 v[14:15], v[248:249], v[148:149], v[14:15] op_sel:[1,0,0] op_sel_hi:[1,1,1]
	v_pk_fma_f32 v[6:7], v[250:251], v[148:149], v[6:7] op_sel_hi:[0,1,1]
	ds_read_b128 v[248:251], v112 offset:43648
	s_waitcnt vmcnt(26)
	v_lshlrev_b32_e32 v108, 16, v150
	v_and_b32_e32 v109, 0xffff0000, v150
	v_lshlrev_b32_e32 v246, 16, v151
	v_and_b32_e32 v247, 0xffff0000, v151
	v_lshlrev_b32_e32 v150, 16, v152
	v_and_b32_e32 v151, 0xffff0000, v152
	v_lshlrev_b32_e32 v152, 16, v153
	v_and_b32_e32 v153, 0xffff0000, v153
	s_waitcnt lgkmcnt(1)
	v_pk_fma_f32 v[8:9], v[254:255], v[108:109], v[8:9] op_sel:[1,0,0] op_sel_hi:[1,1,1]
	v_pk_fma_f32 v[32:33], v[252:253], v[108:109], v[32:33] op_sel_hi:[0,1,1]
	v_pk_fma_f32 v[22:23], v[252:253], v[108:109], v[22:23] op_sel:[1,0,0] op_sel_hi:[1,1,1]
	v_pk_fma_f32 v[16:17], v[254:255], v[108:109], v[16:17] op_sel_hi:[0,1,1]
	v_pk_fma_f32 v[4:5], v[254:255], v[246:247], v[4:5] op_sel:[1,0,0] op_sel_hi:[1,1,1]
	v_pk_fma_f32 v[30:31], v[252:253], v[246:247], v[30:31] op_sel_hi:[0,1,1]
	v_pk_fma_f32 v[20:21], v[252:253], v[246:247], v[20:21] op_sel:[1,0,0] op_sel_hi:[1,1,1]
	v_pk_fma_f32 v[12:13], v[254:255], v[246:247], v[12:13] op_sel_hi:[0,1,1]
	v_pk_fma_f32 v[2:3], v[254:255], v[150:151], v[2:3] op_sel:[1,0,0] op_sel_hi:[1,1,1]
	v_pk_fma_f32 v[26:27], v[252:253], v[150:151], v[26:27] op_sel_hi:[0,1,1]
	v_pk_fma_f32 v[18:19], v[252:253], v[150:151], v[18:19] op_sel:[1,0,0] op_sel_hi:[1,1,1]
	v_pk_fma_f32 v[10:11], v[254:255], v[150:151], v[10:11] op_sel_hi:[0,1,1]
	v_pk_fma_f32 v[0:1], v[254:255], v[152:153], v[0:1] op_sel:[1,0,0] op_sel_hi:[1,1,1]
	v_pk_fma_f32 v[24:25], v[252:253], v[152:153], v[24:25] op_sel_hi:[0,1,1]
	v_pk_fma_f32 v[14:15], v[252:253], v[152:153], v[14:15] op_sel:[1,0,0] op_sel_hi:[1,1,1]
	v_pk_fma_f32 v[6:7], v[254:255], v[152:153], v[6:7] op_sel_hi:[0,1,1]
	ds_read_b128 v[252:255], v112 offset:43712
	s_waitcnt vmcnt(25)
	v_lshlrev_b32_e32 v108, 16, v154
	v_and_b32_e32 v109, 0xffff0000, v154
	v_lshlrev_b32_e32 v246, 16, v155
	v_and_b32_e32 v247, 0xffff0000, v155
	v_lshlrev_b32_e32 v154, 16, v156
	v_and_b32_e32 v155, 0xffff0000, v156
	v_lshlrev_b32_e32 v156, 16, v157
	v_and_b32_e32 v157, 0xffff0000, v157
	s_waitcnt lgkmcnt(1)
	v_pk_fma_f32 v[8:9], v[250:251], v[108:109], v[8:9] op_sel:[1,0,0] op_sel_hi:[1,1,1]
	v_pk_fma_f32 v[32:33], v[248:249], v[108:109], v[32:33] op_sel_hi:[0,1,1]
	v_pk_fma_f32 v[22:23], v[248:249], v[108:109], v[22:23] op_sel:[1,0,0] op_sel_hi:[1,1,1]
	v_pk_fma_f32 v[16:17], v[250:251], v[108:109], v[16:17] op_sel_hi:[0,1,1]
	v_pk_fma_f32 v[4:5], v[250:251], v[246:247], v[4:5] op_sel:[1,0,0] op_sel_hi:[1,1,1]
	v_pk_fma_f32 v[30:31], v[248:249], v[246:247], v[30:31] op_sel_hi:[0,1,1]
	v_pk_fma_f32 v[20:21], v[248:249], v[246:247], v[20:21] op_sel:[1,0,0] op_sel_hi:[1,1,1]
	v_pk_fma_f32 v[12:13], v[250:251], v[246:247], v[12:13] op_sel_hi:[0,1,1]
	v_pk_fma_f32 v[2:3], v[250:251], v[154:155], v[2:3] op_sel:[1,0,0] op_sel_hi:[1,1,1]
	v_pk_fma_f32 v[26:27], v[248:249], v[154:155], v[26:27] op_sel_hi:[0,1,1]
	v_pk_fma_f32 v[18:19], v[248:249], v[154:155], v[18:19] op_sel:[1,0,0] op_sel_hi:[1,1,1]
	v_pk_fma_f32 v[10:11], v[250:251], v[154:155], v[10:11] op_sel_hi:[0,1,1]
	v_pk_fma_f32 v[0:1], v[250:251], v[156:157], v[0:1] op_sel:[1,0,0] op_sel_hi:[1,1,1]
	v_pk_fma_f32 v[24:25], v[248:249], v[156:157], v[24:25] op_sel_hi:[0,1,1]
	v_pk_fma_f32 v[14:15], v[248:249], v[156:157], v[14:15] op_sel:[1,0,0] op_sel_hi:[1,1,1]
	v_pk_fma_f32 v[6:7], v[250:251], v[156:157], v[6:7] op_sel_hi:[0,1,1]
	ds_read_b128 v[248:251], v112 offset:43776
	s_waitcnt vmcnt(24)
	v_lshlrev_b32_e32 v108, 16, v158
	v_and_b32_e32 v109, 0xffff0000, v158
	v_lshlrev_b32_e32 v246, 16, v159
	v_and_b32_e32 v247, 0xffff0000, v159
	v_lshlrev_b32_e32 v158, 16, v160
	v_and_b32_e32 v159, 0xffff0000, v160
	v_lshlrev_b32_e32 v160, 16, v161
	v_and_b32_e32 v161, 0xffff0000, v161
	s_waitcnt lgkmcnt(1)
	v_pk_fma_f32 v[8:9], v[254:255], v[108:109], v[8:9] op_sel:[1,0,0] op_sel_hi:[1,1,1]
	v_pk_fma_f32 v[32:33], v[252:253], v[108:109], v[32:33] op_sel_hi:[0,1,1]
	v_pk_fma_f32 v[22:23], v[252:253], v[108:109], v[22:23] op_sel:[1,0,0] op_sel_hi:[1,1,1]
	v_pk_fma_f32 v[16:17], v[254:255], v[108:109], v[16:17] op_sel_hi:[0,1,1]
	v_pk_fma_f32 v[4:5], v[254:255], v[246:247], v[4:5] op_sel:[1,0,0] op_sel_hi:[1,1,1]
	v_pk_fma_f32 v[30:31], v[252:253], v[246:247], v[30:31] op_sel_hi:[0,1,1]
	v_pk_fma_f32 v[20:21], v[252:253], v[246:247], v[20:21] op_sel:[1,0,0] op_sel_hi:[1,1,1]
	v_pk_fma_f32 v[12:13], v[254:255], v[246:247], v[12:13] op_sel_hi:[0,1,1]
	v_pk_fma_f32 v[2:3], v[254:255], v[158:159], v[2:3] op_sel:[1,0,0] op_sel_hi:[1,1,1]
	v_pk_fma_f32 v[26:27], v[252:253], v[158:159], v[26:27] op_sel_hi:[0,1,1]
	v_pk_fma_f32 v[18:19], v[252:253], v[158:159], v[18:19] op_sel:[1,0,0] op_sel_hi:[1,1,1]
	v_pk_fma_f32 v[10:11], v[254:255], v[158:159], v[10:11] op_sel_hi:[0,1,1]
	v_pk_fma_f32 v[0:1], v[254:255], v[160:161], v[0:1] op_sel:[1,0,0] op_sel_hi:[1,1,1]
	v_pk_fma_f32 v[24:25], v[252:253], v[160:161], v[24:25] op_sel_hi:[0,1,1]
	v_pk_fma_f32 v[14:15], v[252:253], v[160:161], v[14:15] op_sel:[1,0,0] op_sel_hi:[1,1,1]
	v_pk_fma_f32 v[6:7], v[254:255], v[160:161], v[6:7] op_sel_hi:[0,1,1]
	ds_read_b128 v[252:255], v112 offset:43840
	s_waitcnt vmcnt(23)
	v_lshlrev_b32_e32 v108, 16, v162
	v_and_b32_e32 v109, 0xffff0000, v162
	v_lshlrev_b32_e32 v246, 16, v163
	v_and_b32_e32 v247, 0xffff0000, v163
	v_lshlrev_b32_e32 v162, 16, v164
	v_and_b32_e32 v163, 0xffff0000, v164
	v_lshlrev_b32_e32 v164, 16, v165
	v_and_b32_e32 v165, 0xffff0000, v165
	s_waitcnt lgkmcnt(1)
	v_pk_fma_f32 v[8:9], v[250:251], v[108:109], v[8:9] op_sel:[1,0,0] op_sel_hi:[1,1,1]
	v_pk_fma_f32 v[32:33], v[248:249], v[108:109], v[32:33] op_sel_hi:[0,1,1]
	v_pk_fma_f32 v[22:23], v[248:249], v[108:109], v[22:23] op_sel:[1,0,0] op_sel_hi:[1,1,1]
	v_pk_fma_f32 v[16:17], v[250:251], v[108:109], v[16:17] op_sel_hi:[0,1,1]
	v_pk_fma_f32 v[4:5], v[250:251], v[246:247], v[4:5] op_sel:[1,0,0] op_sel_hi:[1,1,1]
	v_pk_fma_f32 v[30:31], v[248:249], v[246:247], v[30:31] op_sel_hi:[0,1,1]
	v_pk_fma_f32 v[20:21], v[248:249], v[246:247], v[20:21] op_sel:[1,0,0] op_sel_hi:[1,1,1]
	v_pk_fma_f32 v[12:13], v[250:251], v[246:247], v[12:13] op_sel_hi:[0,1,1]
	v_pk_fma_f32 v[2:3], v[250:251], v[162:163], v[2:3] op_sel:[1,0,0] op_sel_hi:[1,1,1]
	v_pk_fma_f32 v[26:27], v[248:249], v[162:163], v[26:27] op_sel_hi:[0,1,1]
	v_pk_fma_f32 v[18:19], v[248:249], v[162:163], v[18:19] op_sel:[1,0,0] op_sel_hi:[1,1,1]
	v_pk_fma_f32 v[10:11], v[250:251], v[162:163], v[10:11] op_sel_hi:[0,1,1]
	v_pk_fma_f32 v[0:1], v[250:251], v[164:165], v[0:1] op_sel:[1,0,0] op_sel_hi:[1,1,1]
	v_pk_fma_f32 v[24:25], v[248:249], v[164:165], v[24:25] op_sel_hi:[0,1,1]
	v_pk_fma_f32 v[14:15], v[248:249], v[164:165], v[14:15] op_sel:[1,0,0] op_sel_hi:[1,1,1]
	v_pk_fma_f32 v[6:7], v[250:251], v[164:165], v[6:7] op_sel_hi:[0,1,1]
	ds_read_b128 v[248:251], v112 offset:43904
	s_waitcnt vmcnt(22)
	v_lshlrev_b32_e32 v108, 16, v166
	v_and_b32_e32 v109, 0xffff0000, v166
	v_lshlrev_b32_e32 v246, 16, v167
	v_and_b32_e32 v247, 0xffff0000, v167
	v_lshlrev_b32_e32 v166, 16, v168
	v_and_b32_e32 v167, 0xffff0000, v168
	v_lshlrev_b32_e32 v168, 16, v169
	v_and_b32_e32 v169, 0xffff0000, v169
	s_waitcnt lgkmcnt(1)
	v_pk_fma_f32 v[8:9], v[254:255], v[108:109], v[8:9] op_sel:[1,0,0] op_sel_hi:[1,1,1]
	v_pk_fma_f32 v[32:33], v[252:253], v[108:109], v[32:33] op_sel_hi:[0,1,1]
	v_pk_fma_f32 v[22:23], v[252:253], v[108:109], v[22:23] op_sel:[1,0,0] op_sel_hi:[1,1,1]
	v_pk_fma_f32 v[16:17], v[254:255], v[108:109], v[16:17] op_sel_hi:[0,1,1]
	v_pk_fma_f32 v[4:5], v[254:255], v[246:247], v[4:5] op_sel:[1,0,0] op_sel_hi:[1,1,1]
	v_pk_fma_f32 v[30:31], v[252:253], v[246:247], v[30:31] op_sel_hi:[0,1,1]
	v_pk_fma_f32 v[20:21], v[252:253], v[246:247], v[20:21] op_sel:[1,0,0] op_sel_hi:[1,1,1]
	v_pk_fma_f32 v[12:13], v[254:255], v[246:247], v[12:13] op_sel_hi:[0,1,1]
	v_pk_fma_f32 v[2:3], v[254:255], v[166:167], v[2:3] op_sel:[1,0,0] op_sel_hi:[1,1,1]
	v_pk_fma_f32 v[26:27], v[252:253], v[166:167], v[26:27] op_sel_hi:[0,1,1]
	v_pk_fma_f32 v[18:19], v[252:253], v[166:167], v[18:19] op_sel:[1,0,0] op_sel_hi:[1,1,1]
	v_pk_fma_f32 v[10:11], v[254:255], v[166:167], v[10:11] op_sel_hi:[0,1,1]
	v_pk_fma_f32 v[0:1], v[254:255], v[168:169], v[0:1] op_sel:[1,0,0] op_sel_hi:[1,1,1]
	v_pk_fma_f32 v[24:25], v[252:253], v[168:169], v[24:25] op_sel_hi:[0,1,1]
	v_pk_fma_f32 v[14:15], v[252:253], v[168:169], v[14:15] op_sel:[1,0,0] op_sel_hi:[1,1,1]
	v_pk_fma_f32 v[6:7], v[254:255], v[168:169], v[6:7] op_sel_hi:[0,1,1]
	ds_read_b128 v[252:255], v112 offset:43968
	s_waitcnt vmcnt(21)
	v_lshlrev_b32_e32 v108, 16, v170
	v_and_b32_e32 v109, 0xffff0000, v170
	v_lshlrev_b32_e32 v246, 16, v171
	v_and_b32_e32 v247, 0xffff0000, v171
	v_lshlrev_b32_e32 v170, 16, v172
	v_and_b32_e32 v171, 0xffff0000, v172
	v_lshlrev_b32_e32 v172, 16, v173
	v_and_b32_e32 v173, 0xffff0000, v173
	s_waitcnt lgkmcnt(1)
	v_pk_fma_f32 v[8:9], v[250:251], v[108:109], v[8:9] op_sel:[1,0,0] op_sel_hi:[1,1,1]
	v_pk_fma_f32 v[32:33], v[248:249], v[108:109], v[32:33] op_sel_hi:[0,1,1]
	v_pk_fma_f32 v[22:23], v[248:249], v[108:109], v[22:23] op_sel:[1,0,0] op_sel_hi:[1,1,1]
	v_pk_fma_f32 v[16:17], v[250:251], v[108:109], v[16:17] op_sel_hi:[0,1,1]
	v_pk_fma_f32 v[4:5], v[250:251], v[246:247], v[4:5] op_sel:[1,0,0] op_sel_hi:[1,1,1]
	v_pk_fma_f32 v[30:31], v[248:249], v[246:247], v[30:31] op_sel_hi:[0,1,1]
	v_pk_fma_f32 v[20:21], v[248:249], v[246:247], v[20:21] op_sel:[1,0,0] op_sel_hi:[1,1,1]
	v_pk_fma_f32 v[12:13], v[250:251], v[246:247], v[12:13] op_sel_hi:[0,1,1]
	v_pk_fma_f32 v[2:3], v[250:251], v[170:171], v[2:3] op_sel:[1,0,0] op_sel_hi:[1,1,1]
	v_pk_fma_f32 v[26:27], v[248:249], v[170:171], v[26:27] op_sel_hi:[0,1,1]
	v_pk_fma_f32 v[18:19], v[248:249], v[170:171], v[18:19] op_sel:[1,0,0] op_sel_hi:[1,1,1]
	v_pk_fma_f32 v[10:11], v[250:251], v[170:171], v[10:11] op_sel_hi:[0,1,1]
	v_pk_fma_f32 v[0:1], v[250:251], v[172:173], v[0:1] op_sel:[1,0,0] op_sel_hi:[1,1,1]
	v_pk_fma_f32 v[24:25], v[248:249], v[172:173], v[24:25] op_sel_hi:[0,1,1]
	v_pk_fma_f32 v[14:15], v[248:249], v[172:173], v[14:15] op_sel:[1,0,0] op_sel_hi:[1,1,1]
	v_pk_fma_f32 v[6:7], v[250:251], v[172:173], v[6:7] op_sel_hi:[0,1,1]
	ds_read_b128 v[248:251], v112 offset:44032
	s_waitcnt vmcnt(20)
	v_lshlrev_b32_e32 v108, 16, v174
	v_and_b32_e32 v109, 0xffff0000, v174
	v_lshlrev_b32_e32 v246, 16, v175
	v_and_b32_e32 v247, 0xffff0000, v175
	v_lshlrev_b32_e32 v174, 16, v176
	v_and_b32_e32 v175, 0xffff0000, v176
	v_lshlrev_b32_e32 v176, 16, v177
	v_and_b32_e32 v177, 0xffff0000, v177
	s_waitcnt lgkmcnt(1)
	v_pk_fma_f32 v[8:9], v[254:255], v[108:109], v[8:9] op_sel:[1,0,0] op_sel_hi:[1,1,1]
	v_pk_fma_f32 v[32:33], v[252:253], v[108:109], v[32:33] op_sel_hi:[0,1,1]
	v_pk_fma_f32 v[22:23], v[252:253], v[108:109], v[22:23] op_sel:[1,0,0] op_sel_hi:[1,1,1]
	v_pk_fma_f32 v[16:17], v[254:255], v[108:109], v[16:17] op_sel_hi:[0,1,1]
	v_pk_fma_f32 v[4:5], v[254:255], v[246:247], v[4:5] op_sel:[1,0,0] op_sel_hi:[1,1,1]
	v_pk_fma_f32 v[30:31], v[252:253], v[246:247], v[30:31] op_sel_hi:[0,1,1]
	v_pk_fma_f32 v[20:21], v[252:253], v[246:247], v[20:21] op_sel:[1,0,0] op_sel_hi:[1,1,1]
	v_pk_fma_f32 v[12:13], v[254:255], v[246:247], v[12:13] op_sel_hi:[0,1,1]
	v_pk_fma_f32 v[2:3], v[254:255], v[174:175], v[2:3] op_sel:[1,0,0] op_sel_hi:[1,1,1]
	v_pk_fma_f32 v[26:27], v[252:253], v[174:175], v[26:27] op_sel_hi:[0,1,1]
	v_pk_fma_f32 v[18:19], v[252:253], v[174:175], v[18:19] op_sel:[1,0,0] op_sel_hi:[1,1,1]
	v_pk_fma_f32 v[10:11], v[254:255], v[174:175], v[10:11] op_sel_hi:[0,1,1]
	v_pk_fma_f32 v[0:1], v[254:255], v[176:177], v[0:1] op_sel:[1,0,0] op_sel_hi:[1,1,1]
	v_pk_fma_f32 v[24:25], v[252:253], v[176:177], v[24:25] op_sel_hi:[0,1,1]
	v_pk_fma_f32 v[14:15], v[252:253], v[176:177], v[14:15] op_sel:[1,0,0] op_sel_hi:[1,1,1]
	v_pk_fma_f32 v[6:7], v[254:255], v[176:177], v[6:7] op_sel_hi:[0,1,1]
	ds_read_b128 v[252:255], v112 offset:44096
	s_waitcnt vmcnt(19)
	v_lshlrev_b32_e32 v108, 16, v178
	v_and_b32_e32 v109, 0xffff0000, v178
	v_lshlrev_b32_e32 v246, 16, v179
	v_and_b32_e32 v247, 0xffff0000, v179
	v_lshlrev_b32_e32 v178, 16, v180
	v_and_b32_e32 v179, 0xffff0000, v180
	v_lshlrev_b32_e32 v180, 16, v181
	v_and_b32_e32 v181, 0xffff0000, v181
	s_waitcnt lgkmcnt(1)
	v_pk_fma_f32 v[8:9], v[250:251], v[108:109], v[8:9] op_sel:[1,0,0] op_sel_hi:[1,1,1]
	v_pk_fma_f32 v[32:33], v[248:249], v[108:109], v[32:33] op_sel_hi:[0,1,1]
	v_pk_fma_f32 v[22:23], v[248:249], v[108:109], v[22:23] op_sel:[1,0,0] op_sel_hi:[1,1,1]
	v_pk_fma_f32 v[16:17], v[250:251], v[108:109], v[16:17] op_sel_hi:[0,1,1]
	v_pk_fma_f32 v[4:5], v[250:251], v[246:247], v[4:5] op_sel:[1,0,0] op_sel_hi:[1,1,1]
	v_pk_fma_f32 v[30:31], v[248:249], v[246:247], v[30:31] op_sel_hi:[0,1,1]
	v_pk_fma_f32 v[20:21], v[248:249], v[246:247], v[20:21] op_sel:[1,0,0] op_sel_hi:[1,1,1]
	v_pk_fma_f32 v[12:13], v[250:251], v[246:247], v[12:13] op_sel_hi:[0,1,1]
	v_pk_fma_f32 v[2:3], v[250:251], v[178:179], v[2:3] op_sel:[1,0,0] op_sel_hi:[1,1,1]
	v_pk_fma_f32 v[26:27], v[248:249], v[178:179], v[26:27] op_sel_hi:[0,1,1]
	v_pk_fma_f32 v[18:19], v[248:249], v[178:179], v[18:19] op_sel:[1,0,0] op_sel_hi:[1,1,1]
	v_pk_fma_f32 v[10:11], v[250:251], v[178:179], v[10:11] op_sel_hi:[0,1,1]
	v_pk_fma_f32 v[0:1], v[250:251], v[180:181], v[0:1] op_sel:[1,0,0] op_sel_hi:[1,1,1]
	v_pk_fma_f32 v[24:25], v[248:249], v[180:181], v[24:25] op_sel_hi:[0,1,1]
	v_pk_fma_f32 v[14:15], v[248:249], v[180:181], v[14:15] op_sel:[1,0,0] op_sel_hi:[1,1,1]
	v_pk_fma_f32 v[6:7], v[250:251], v[180:181], v[6:7] op_sel_hi:[0,1,1]
	ds_read_b128 v[248:251], v112 offset:44160
	s_waitcnt vmcnt(18)
	v_lshlrev_b32_e32 v108, 16, v182
	v_and_b32_e32 v109, 0xffff0000, v182
	v_lshlrev_b32_e32 v246, 16, v183
	v_and_b32_e32 v247, 0xffff0000, v183
	v_lshlrev_b32_e32 v182, 16, v184
	v_and_b32_e32 v183, 0xffff0000, v184
	v_lshlrev_b32_e32 v184, 16, v185
	v_and_b32_e32 v185, 0xffff0000, v185
	s_waitcnt lgkmcnt(1)
	v_pk_fma_f32 v[8:9], v[254:255], v[108:109], v[8:9] op_sel:[1,0,0] op_sel_hi:[1,1,1]
	v_pk_fma_f32 v[32:33], v[252:253], v[108:109], v[32:33] op_sel_hi:[0,1,1]
	v_pk_fma_f32 v[22:23], v[252:253], v[108:109], v[22:23] op_sel:[1,0,0] op_sel_hi:[1,1,1]
	v_pk_fma_f32 v[16:17], v[254:255], v[108:109], v[16:17] op_sel_hi:[0,1,1]
	v_pk_fma_f32 v[4:5], v[254:255], v[246:247], v[4:5] op_sel:[1,0,0] op_sel_hi:[1,1,1]
	v_pk_fma_f32 v[30:31], v[252:253], v[246:247], v[30:31] op_sel_hi:[0,1,1]
	v_pk_fma_f32 v[20:21], v[252:253], v[246:247], v[20:21] op_sel:[1,0,0] op_sel_hi:[1,1,1]
	v_pk_fma_f32 v[12:13], v[254:255], v[246:247], v[12:13] op_sel_hi:[0,1,1]
	v_pk_fma_f32 v[2:3], v[254:255], v[182:183], v[2:3] op_sel:[1,0,0] op_sel_hi:[1,1,1]
	v_pk_fma_f32 v[26:27], v[252:253], v[182:183], v[26:27] op_sel_hi:[0,1,1]
	v_pk_fma_f32 v[18:19], v[252:253], v[182:183], v[18:19] op_sel:[1,0,0] op_sel_hi:[1,1,1]
	v_pk_fma_f32 v[10:11], v[254:255], v[182:183], v[10:11] op_sel_hi:[0,1,1]
	v_pk_fma_f32 v[0:1], v[254:255], v[184:185], v[0:1] op_sel:[1,0,0] op_sel_hi:[1,1,1]
	v_pk_fma_f32 v[24:25], v[252:253], v[184:185], v[24:25] op_sel_hi:[0,1,1]
	v_pk_fma_f32 v[14:15], v[252:253], v[184:185], v[14:15] op_sel:[1,0,0] op_sel_hi:[1,1,1]
	v_pk_fma_f32 v[6:7], v[254:255], v[184:185], v[6:7] op_sel_hi:[0,1,1]
	ds_read_b128 v[252:255], v112 offset:44224
	s_waitcnt vmcnt(17)
	v_lshlrev_b32_e32 v108, 16, v186
	v_and_b32_e32 v109, 0xffff0000, v186
	v_lshlrev_b32_e32 v246, 16, v187
	v_and_b32_e32 v247, 0xffff0000, v187
	v_lshlrev_b32_e32 v186, 16, v188
	v_and_b32_e32 v187, 0xffff0000, v188
	v_lshlrev_b32_e32 v188, 16, v189
	v_and_b32_e32 v189, 0xffff0000, v189
	s_waitcnt lgkmcnt(1)
	v_pk_fma_f32 v[8:9], v[250:251], v[108:109], v[8:9] op_sel:[1,0,0] op_sel_hi:[1,1,1]
	v_pk_fma_f32 v[32:33], v[248:249], v[108:109], v[32:33] op_sel_hi:[0,1,1]
	v_pk_fma_f32 v[22:23], v[248:249], v[108:109], v[22:23] op_sel:[1,0,0] op_sel_hi:[1,1,1]
	v_pk_fma_f32 v[16:17], v[250:251], v[108:109], v[16:17] op_sel_hi:[0,1,1]
	v_pk_fma_f32 v[4:5], v[250:251], v[246:247], v[4:5] op_sel:[1,0,0] op_sel_hi:[1,1,1]
	v_pk_fma_f32 v[30:31], v[248:249], v[246:247], v[30:31] op_sel_hi:[0,1,1]
	v_pk_fma_f32 v[20:21], v[248:249], v[246:247], v[20:21] op_sel:[1,0,0] op_sel_hi:[1,1,1]
	v_pk_fma_f32 v[12:13], v[250:251], v[246:247], v[12:13] op_sel_hi:[0,1,1]
	v_pk_fma_f32 v[2:3], v[250:251], v[186:187], v[2:3] op_sel:[1,0,0] op_sel_hi:[1,1,1]
	v_pk_fma_f32 v[26:27], v[248:249], v[186:187], v[26:27] op_sel_hi:[0,1,1]
	v_pk_fma_f32 v[18:19], v[248:249], v[186:187], v[18:19] op_sel:[1,0,0] op_sel_hi:[1,1,1]
	v_pk_fma_f32 v[10:11], v[250:251], v[186:187], v[10:11] op_sel_hi:[0,1,1]
	v_pk_fma_f32 v[0:1], v[250:251], v[188:189], v[0:1] op_sel:[1,0,0] op_sel_hi:[1,1,1]
	v_pk_fma_f32 v[24:25], v[248:249], v[188:189], v[24:25] op_sel_hi:[0,1,1]
	v_pk_fma_f32 v[14:15], v[248:249], v[188:189], v[14:15] op_sel:[1,0,0] op_sel_hi:[1,1,1]
	v_pk_fma_f32 v[6:7], v[250:251], v[188:189], v[6:7] op_sel_hi:[0,1,1]
	s_waitcnt vmcnt(16)
	v_lshlrev_b32_e32 v108, 16, v190
	v_and_b32_e32 v109, 0xffff0000, v190
	v_lshlrev_b32_e32 v246, 16, v191
	v_and_b32_e32 v247, 0xffff0000, v191
	v_lshlrev_b32_e32 v190, 16, v192
	v_and_b32_e32 v191, 0xffff0000, v192
	v_lshlrev_b32_e32 v192, 16, v193
	v_and_b32_e32 v193, 0xffff0000, v193
	s_waitcnt lgkmcnt(0)
	v_pk_fma_f32 v[8:9], v[254:255], v[108:109], v[8:9] op_sel:[1,0,0] op_sel_hi:[1,1,1]
	v_pk_fma_f32 v[32:33], v[252:253], v[108:109], v[32:33] op_sel_hi:[0,1,1]
	v_pk_fma_f32 v[22:23], v[252:253], v[108:109], v[22:23] op_sel:[1,0,0] op_sel_hi:[1,1,1]
	v_pk_fma_f32 v[16:17], v[254:255], v[108:109], v[16:17] op_sel_hi:[0,1,1]
	v_pk_fma_f32 v[4:5], v[254:255], v[246:247], v[4:5] op_sel:[1,0,0] op_sel_hi:[1,1,1]
	v_pk_fma_f32 v[30:31], v[252:253], v[246:247], v[30:31] op_sel_hi:[0,1,1]
	v_pk_fma_f32 v[20:21], v[252:253], v[246:247], v[20:21] op_sel:[1,0,0] op_sel_hi:[1,1,1]
	v_pk_fma_f32 v[12:13], v[254:255], v[246:247], v[12:13] op_sel_hi:[0,1,1]
	v_pk_fma_f32 v[2:3], v[254:255], v[190:191], v[2:3] op_sel:[1,0,0] op_sel_hi:[1,1,1]
	v_pk_fma_f32 v[26:27], v[252:253], v[190:191], v[26:27] op_sel_hi:[0,1,1]
	v_pk_fma_f32 v[18:19], v[252:253], v[190:191], v[18:19] op_sel:[1,0,0] op_sel_hi:[1,1,1]
	v_pk_fma_f32 v[10:11], v[254:255], v[190:191], v[10:11] op_sel_hi:[0,1,1]
	v_pk_fma_f32 v[0:1], v[254:255], v[192:193], v[0:1] op_sel:[1,0,0] op_sel_hi:[1,1,1]
	v_pk_fma_f32 v[24:25], v[252:253], v[192:193], v[24:25] op_sel_hi:[0,1,1]
	v_pk_fma_f32 v[14:15], v[252:253], v[192:193], v[14:15] op_sel:[1,0,0] op_sel_hi:[1,1,1]
	v_pk_fma_f32 v[6:7], v[254:255], v[192:193], v[6:7] op_sel_hi:[0,1,1]
	ds_read_b32 v34, v56 offset:6912
	ds_read_b32 v35, v56 offset:6928
	ds_read_b32 v36, v56 offset:6944
	ds_read_b32 v37, v56 offset:6960
	ds_read_b32 v38, v56 offset:6976
	ds_read_b32 v39, v56 offset:6992
	ds_read_b32 v40, v56 offset:7008
	ds_read_b32 v41, v56 offset:7024
	ds_read_b32 v42, v56 offset:7040
	ds_read_b32 v43, v56 offset:7056
	ds_read_b32 v44, v56 offset:7072
	ds_read_b32 v45, v56 offset:7088
	ds_read_b32 v46, v56 offset:7104
	ds_read_b32 v47, v56 offset:7120
	ds_read_b32 v48, v56 offset:7136
	ds_read_b32 v49, v56 offset:7152
	s_waitcnt lgkmcnt(15)
	v_lshl_add_u32 v34, v34, 9, v102
	global_load_dwordx4 v[130:133], v34, s[0:1]
	s_waitcnt lgkmcnt(14)
	v_lshl_add_u32 v35, v35, 9, v102
	global_load_dwordx4 v[134:137], v35, s[0:1]
	s_waitcnt lgkmcnt(13)
	v_lshl_add_u32 v36, v36, 9, v102
	global_load_dwordx4 v[138:141], v36, s[0:1]
	s_waitcnt lgkmcnt(12)
	v_lshl_add_u32 v37, v37, 9, v102
	global_load_dwordx4 v[142:145], v37, s[0:1]
	s_waitcnt lgkmcnt(11)
	v_lshl_add_u32 v38, v38, 9, v102
	global_load_dwordx4 v[146:149], v38, s[0:1]
	s_waitcnt lgkmcnt(10)
	v_lshl_add_u32 v39, v39, 9, v102
	global_load_dwordx4 v[150:153], v39, s[0:1]
	s_waitcnt lgkmcnt(9)
	v_lshl_add_u32 v40, v40, 9, v102
	global_load_dwordx4 v[154:157], v40, s[0:1]
	s_waitcnt lgkmcnt(8)
	v_lshl_add_u32 v41, v41, 9, v102
	global_load_dwordx4 v[158:161], v41, s[0:1]
	s_waitcnt lgkmcnt(7)
	v_lshl_add_u32 v42, v42, 9, v102
	global_load_dwordx4 v[162:165], v42, s[0:1]
	s_waitcnt lgkmcnt(6)
	v_lshl_add_u32 v43, v43, 9, v102
	global_load_dwordx4 v[166:169], v43, s[0:1]
	s_waitcnt lgkmcnt(5)
	v_lshl_add_u32 v44, v44, 9, v102
	global_load_dwordx4 v[170:173], v44, s[0:1]
	s_waitcnt lgkmcnt(4)
	v_lshl_add_u32 v45, v45, 9, v102
	global_load_dwordx4 v[174:177], v45, s[0:1]
	s_waitcnt lgkmcnt(3)
	v_lshl_add_u32 v46, v46, 9, v102
	global_load_dwordx4 v[178:181], v46, s[0:1]
	s_waitcnt lgkmcnt(2)
	v_lshl_add_u32 v47, v47, 9, v102
	global_load_dwordx4 v[182:185], v47, s[0:1]
	s_waitcnt lgkmcnt(1)
	v_lshl_add_u32 v48, v48, 9, v102
	global_load_dwordx4 v[186:189], v48, s[0:1]
	s_waitcnt lgkmcnt(0)
	v_lshl_add_u32 v49, v49, 9, v102
	global_load_dwordx4 v[190:193], v49, s[0:1]
	ds_read_b128 v[248:251], v112 offset:44288
	ds_read_b128 v[252:255], v112 offset:44352
	s_waitcnt vmcnt(31)
	v_lshlrev_b32_e32 v108, 16, v210
	v_and_b32_e32 v109, 0xffff0000, v210
	v_lshlrev_b32_e32 v246, 16, v211
	v_and_b32_e32 v247, 0xffff0000, v211
	v_lshlrev_b32_e32 v210, 16, v212
	v_and_b32_e32 v211, 0xffff0000, v212
	v_lshlrev_b32_e32 v212, 16, v213
	v_and_b32_e32 v213, 0xffff0000, v213
	s_waitcnt lgkmcnt(1)
	v_pk_fma_f32 v[8:9], v[250:251], v[108:109], v[8:9] op_sel:[1,0,0] op_sel_hi:[1,1,1]
	v_pk_fma_f32 v[32:33], v[248:249], v[108:109], v[32:33] op_sel_hi:[0,1,1]
	v_pk_fma_f32 v[22:23], v[248:249], v[108:109], v[22:23] op_sel:[1,0,0] op_sel_hi:[1,1,1]
	v_pk_fma_f32 v[16:17], v[250:251], v[108:109], v[16:17] op_sel_hi:[0,1,1]
	v_pk_fma_f32 v[4:5], v[250:251], v[246:247], v[4:5] op_sel:[1,0,0] op_sel_hi:[1,1,1]
	v_pk_fma_f32 v[30:31], v[248:249], v[246:247], v[30:31] op_sel_hi:[0,1,1]
	v_pk_fma_f32 v[20:21], v[248:249], v[246:247], v[20:21] op_sel:[1,0,0] op_sel_hi:[1,1,1]
	v_pk_fma_f32 v[12:13], v[250:251], v[246:247], v[12:13] op_sel_hi:[0,1,1]
	v_pk_fma_f32 v[2:3], v[250:251], v[210:211], v[2:3] op_sel:[1,0,0] op_sel_hi:[1,1,1]
	v_pk_fma_f32 v[26:27], v[248:249], v[210:211], v[26:27] op_sel_hi:[0,1,1]
	v_pk_fma_f32 v[18:19], v[248:249], v[210:211], v[18:19] op_sel:[1,0,0] op_sel_hi:[1,1,1]
	v_pk_fma_f32 v[10:11], v[250:251], v[210:211], v[10:11] op_sel_hi:[0,1,1]
	v_pk_fma_f32 v[0:1], v[250:251], v[212:213], v[0:1] op_sel:[1,0,0] op_sel_hi:[1,1,1]
	v_pk_fma_f32 v[24:25], v[248:249], v[212:213], v[24:25] op_sel_hi:[0,1,1]
	v_pk_fma_f32 v[14:15], v[248:249], v[212:213], v[14:15] op_sel:[1,0,0] op_sel_hi:[1,1,1]
	v_pk_fma_f32 v[6:7], v[250:251], v[212:213], v[6:7] op_sel_hi:[0,1,1]
	ds_read_b128 v[248:251], v112 offset:44416
	s_waitcnt vmcnt(30)
	v_lshlrev_b32_e32 v108, 16, v214
	v_and_b32_e32 v109, 0xffff0000, v214
	v_lshlrev_b32_e32 v246, 16, v215
	v_and_b32_e32 v247, 0xffff0000, v215
	v_lshlrev_b32_e32 v214, 16, v216
	v_and_b32_e32 v215, 0xffff0000, v216
	v_lshlrev_b32_e32 v216, 16, v217
	v_and_b32_e32 v217, 0xffff0000, v217
	s_waitcnt lgkmcnt(1)
	v_pk_fma_f32 v[8:9], v[254:255], v[108:109], v[8:9] op_sel:[1,0,0] op_sel_hi:[1,1,1]
	v_pk_fma_f32 v[32:33], v[252:253], v[108:109], v[32:33] op_sel_hi:[0,1,1]
	v_pk_fma_f32 v[22:23], v[252:253], v[108:109], v[22:23] op_sel:[1,0,0] op_sel_hi:[1,1,1]
	v_pk_fma_f32 v[16:17], v[254:255], v[108:109], v[16:17] op_sel_hi:[0,1,1]
	v_pk_fma_f32 v[4:5], v[254:255], v[246:247], v[4:5] op_sel:[1,0,0] op_sel_hi:[1,1,1]
	v_pk_fma_f32 v[30:31], v[252:253], v[246:247], v[30:31] op_sel_hi:[0,1,1]
	v_pk_fma_f32 v[20:21], v[252:253], v[246:247], v[20:21] op_sel:[1,0,0] op_sel_hi:[1,1,1]
	v_pk_fma_f32 v[12:13], v[254:255], v[246:247], v[12:13] op_sel_hi:[0,1,1]
	v_pk_fma_f32 v[2:3], v[254:255], v[214:215], v[2:3] op_sel:[1,0,0] op_sel_hi:[1,1,1]
	v_pk_fma_f32 v[26:27], v[252:253], v[214:215], v[26:27] op_sel_hi:[0,1,1]
	v_pk_fma_f32 v[18:19], v[252:253], v[214:215], v[18:19] op_sel:[1,0,0] op_sel_hi:[1,1,1]
	v_pk_fma_f32 v[10:11], v[254:255], v[214:215], v[10:11] op_sel_hi:[0,1,1]
	v_pk_fma_f32 v[0:1], v[254:255], v[216:217], v[0:1] op_sel:[1,0,0] op_sel_hi:[1,1,1]
	v_pk_fma_f32 v[24:25], v[252:253], v[216:217], v[24:25] op_sel_hi:[0,1,1]
	v_pk_fma_f32 v[14:15], v[252:253], v[216:217], v[14:15] op_sel:[1,0,0] op_sel_hi:[1,1,1]
	v_pk_fma_f32 v[6:7], v[254:255], v[216:217], v[6:7] op_sel_hi:[0,1,1]
	ds_read_b128 v[252:255], v112 offset:44480
	s_waitcnt vmcnt(29)
	v_lshlrev_b32_e32 v108, 16, v218
	v_and_b32_e32 v109, 0xffff0000, v218
	v_lshlrev_b32_e32 v246, 16, v219
	v_and_b32_e32 v247, 0xffff0000, v219
	v_lshlrev_b32_e32 v218, 16, v220
	v_and_b32_e32 v219, 0xffff0000, v220
	v_lshlrev_b32_e32 v220, 16, v221
	v_and_b32_e32 v221, 0xffff0000, v221
	s_waitcnt lgkmcnt(1)
	v_pk_fma_f32 v[8:9], v[250:251], v[108:109], v[8:9] op_sel:[1,0,0] op_sel_hi:[1,1,1]
	v_pk_fma_f32 v[32:33], v[248:249], v[108:109], v[32:33] op_sel_hi:[0,1,1]
	v_pk_fma_f32 v[22:23], v[248:249], v[108:109], v[22:23] op_sel:[1,0,0] op_sel_hi:[1,1,1]
	v_pk_fma_f32 v[16:17], v[250:251], v[108:109], v[16:17] op_sel_hi:[0,1,1]
	v_pk_fma_f32 v[4:5], v[250:251], v[246:247], v[4:5] op_sel:[1,0,0] op_sel_hi:[1,1,1]
	v_pk_fma_f32 v[30:31], v[248:249], v[246:247], v[30:31] op_sel_hi:[0,1,1]
	v_pk_fma_f32 v[20:21], v[248:249], v[246:247], v[20:21] op_sel:[1,0,0] op_sel_hi:[1,1,1]
	v_pk_fma_f32 v[12:13], v[250:251], v[246:247], v[12:13] op_sel_hi:[0,1,1]
	v_pk_fma_f32 v[2:3], v[250:251], v[218:219], v[2:3] op_sel:[1,0,0] op_sel_hi:[1,1,1]
	v_pk_fma_f32 v[26:27], v[248:249], v[218:219], v[26:27] op_sel_hi:[0,1,1]
	v_pk_fma_f32 v[18:19], v[248:249], v[218:219], v[18:19] op_sel:[1,0,0] op_sel_hi:[1,1,1]
	v_pk_fma_f32 v[10:11], v[250:251], v[218:219], v[10:11] op_sel_hi:[0,1,1]
	v_pk_fma_f32 v[0:1], v[250:251], v[220:221], v[0:1] op_sel:[1,0,0] op_sel_hi:[1,1,1]
	v_pk_fma_f32 v[24:25], v[248:249], v[220:221], v[24:25] op_sel_hi:[0,1,1]
	v_pk_fma_f32 v[14:15], v[248:249], v[220:221], v[14:15] op_sel:[1,0,0] op_sel_hi:[1,1,1]
	v_pk_fma_f32 v[6:7], v[250:251], v[220:221], v[6:7] op_sel_hi:[0,1,1]
	ds_read_b128 v[248:251], v112 offset:44544
	s_waitcnt vmcnt(28)
	v_lshlrev_b32_e32 v108, 16, v222
	v_and_b32_e32 v109, 0xffff0000, v222
	v_lshlrev_b32_e32 v246, 16, v223
	v_and_b32_e32 v247, 0xffff0000, v223
	v_lshlrev_b32_e32 v222, 16, v224
	v_and_b32_e32 v223, 0xffff0000, v224
	v_lshlrev_b32_e32 v224, 16, v225
	v_and_b32_e32 v225, 0xffff0000, v225
	s_waitcnt lgkmcnt(1)
	v_pk_fma_f32 v[8:9], v[254:255], v[108:109], v[8:9] op_sel:[1,0,0] op_sel_hi:[1,1,1]
	v_pk_fma_f32 v[32:33], v[252:253], v[108:109], v[32:33] op_sel_hi:[0,1,1]
	v_pk_fma_f32 v[22:23], v[252:253], v[108:109], v[22:23] op_sel:[1,0,0] op_sel_hi:[1,1,1]
	v_pk_fma_f32 v[16:17], v[254:255], v[108:109], v[16:17] op_sel_hi:[0,1,1]
	v_pk_fma_f32 v[4:5], v[254:255], v[246:247], v[4:5] op_sel:[1,0,0] op_sel_hi:[1,1,1]
	v_pk_fma_f32 v[30:31], v[252:253], v[246:247], v[30:31] op_sel_hi:[0,1,1]
	v_pk_fma_f32 v[20:21], v[252:253], v[246:247], v[20:21] op_sel:[1,0,0] op_sel_hi:[1,1,1]
	v_pk_fma_f32 v[12:13], v[254:255], v[246:247], v[12:13] op_sel_hi:[0,1,1]
	v_pk_fma_f32 v[2:3], v[254:255], v[222:223], v[2:3] op_sel:[1,0,0] op_sel_hi:[1,1,1]
	v_pk_fma_f32 v[26:27], v[252:253], v[222:223], v[26:27] op_sel_hi:[0,1,1]
	v_pk_fma_f32 v[18:19], v[252:253], v[222:223], v[18:19] op_sel:[1,0,0] op_sel_hi:[1,1,1]
	v_pk_fma_f32 v[10:11], v[254:255], v[222:223], v[10:11] op_sel_hi:[0,1,1]
	v_pk_fma_f32 v[0:1], v[254:255], v[224:225], v[0:1] op_sel:[1,0,0] op_sel_hi:[1,1,1]
	v_pk_fma_f32 v[24:25], v[252:253], v[224:225], v[24:25] op_sel_hi:[0,1,1]
	v_pk_fma_f32 v[14:15], v[252:253], v[224:225], v[14:15] op_sel:[1,0,0] op_sel_hi:[1,1,1]
	v_pk_fma_f32 v[6:7], v[254:255], v[224:225], v[6:7] op_sel_hi:[0,1,1]
	ds_read_b128 v[252:255], v112 offset:44608
	s_waitcnt vmcnt(27)
	v_lshlrev_b32_e32 v108, 16, v226
	v_and_b32_e32 v109, 0xffff0000, v226
	v_lshlrev_b32_e32 v246, 16, v227
	v_and_b32_e32 v247, 0xffff0000, v227
	v_lshlrev_b32_e32 v226, 16, v228
	v_and_b32_e32 v227, 0xffff0000, v228
	v_lshlrev_b32_e32 v228, 16, v229
	v_and_b32_e32 v229, 0xffff0000, v229
	s_waitcnt lgkmcnt(1)
	v_pk_fma_f32 v[8:9], v[250:251], v[108:109], v[8:9] op_sel:[1,0,0] op_sel_hi:[1,1,1]
	v_pk_fma_f32 v[32:33], v[248:249], v[108:109], v[32:33] op_sel_hi:[0,1,1]
	v_pk_fma_f32 v[22:23], v[248:249], v[108:109], v[22:23] op_sel:[1,0,0] op_sel_hi:[1,1,1]
	v_pk_fma_f32 v[16:17], v[250:251], v[108:109], v[16:17] op_sel_hi:[0,1,1]
	v_pk_fma_f32 v[4:5], v[250:251], v[246:247], v[4:5] op_sel:[1,0,0] op_sel_hi:[1,1,1]
	v_pk_fma_f32 v[30:31], v[248:249], v[246:247], v[30:31] op_sel_hi:[0,1,1]
	v_pk_fma_f32 v[20:21], v[248:249], v[246:247], v[20:21] op_sel:[1,0,0] op_sel_hi:[1,1,1]
	v_pk_fma_f32 v[12:13], v[250:251], v[246:247], v[12:13] op_sel_hi:[0,1,1]
	v_pk_fma_f32 v[2:3], v[250:251], v[226:227], v[2:3] op_sel:[1,0,0] op_sel_hi:[1,1,1]
	v_pk_fma_f32 v[26:27], v[248:249], v[226:227], v[26:27] op_sel_hi:[0,1,1]
	v_pk_fma_f32 v[18:19], v[248:249], v[226:227], v[18:19] op_sel:[1,0,0] op_sel_hi:[1,1,1]
	v_pk_fma_f32 v[10:11], v[250:251], v[226:227], v[10:11] op_sel_hi:[0,1,1]
	v_pk_fma_f32 v[0:1], v[250:251], v[228:229], v[0:1] op_sel:[1,0,0] op_sel_hi:[1,1,1]
	v_pk_fma_f32 v[24:25], v[248:249], v[228:229], v[24:25] op_sel_hi:[0,1,1]
	v_pk_fma_f32 v[14:15], v[248:249], v[228:229], v[14:15] op_sel:[1,0,0] op_sel_hi:[1,1,1]
	v_pk_fma_f32 v[6:7], v[250:251], v[228:229], v[6:7] op_sel_hi:[0,1,1]
	ds_read_b128 v[248:251], v112 offset:44672
	s_waitcnt vmcnt(26)
	v_lshlrev_b32_e32 v108, 16, v230
	v_and_b32_e32 v109, 0xffff0000, v230
	v_lshlrev_b32_e32 v246, 16, v231
	v_and_b32_e32 v247, 0xffff0000, v231
	v_lshlrev_b32_e32 v230, 16, v232
	v_and_b32_e32 v231, 0xffff0000, v232
	v_lshlrev_b32_e32 v232, 16, v233
	v_and_b32_e32 v233, 0xffff0000, v233
	s_waitcnt lgkmcnt(1)
	v_pk_fma_f32 v[8:9], v[254:255], v[108:109], v[8:9] op_sel:[1,0,0] op_sel_hi:[1,1,1]
	v_pk_fma_f32 v[32:33], v[252:253], v[108:109], v[32:33] op_sel_hi:[0,1,1]
	v_pk_fma_f32 v[22:23], v[252:253], v[108:109], v[22:23] op_sel:[1,0,0] op_sel_hi:[1,1,1]
	v_pk_fma_f32 v[16:17], v[254:255], v[108:109], v[16:17] op_sel_hi:[0,1,1]
	v_pk_fma_f32 v[4:5], v[254:255], v[246:247], v[4:5] op_sel:[1,0,0] op_sel_hi:[1,1,1]
	v_pk_fma_f32 v[30:31], v[252:253], v[246:247], v[30:31] op_sel_hi:[0,1,1]
	v_pk_fma_f32 v[20:21], v[252:253], v[246:247], v[20:21] op_sel:[1,0,0] op_sel_hi:[1,1,1]
	v_pk_fma_f32 v[12:13], v[254:255], v[246:247], v[12:13] op_sel_hi:[0,1,1]
	v_pk_fma_f32 v[2:3], v[254:255], v[230:231], v[2:3] op_sel:[1,0,0] op_sel_hi:[1,1,1]
	v_pk_fma_f32 v[26:27], v[252:253], v[230:231], v[26:27] op_sel_hi:[0,1,1]
	v_pk_fma_f32 v[18:19], v[252:253], v[230:231], v[18:19] op_sel:[1,0,0] op_sel_hi:[1,1,1]
	v_pk_fma_f32 v[10:11], v[254:255], v[230:231], v[10:11] op_sel_hi:[0,1,1]
	v_pk_fma_f32 v[0:1], v[254:255], v[232:233], v[0:1] op_sel:[1,0,0] op_sel_hi:[1,1,1]
	v_pk_fma_f32 v[24:25], v[252:253], v[232:233], v[24:25] op_sel_hi:[0,1,1]
	v_pk_fma_f32 v[14:15], v[252:253], v[232:233], v[14:15] op_sel:[1,0,0] op_sel_hi:[1,1,1]
	v_pk_fma_f32 v[6:7], v[254:255], v[232:233], v[6:7] op_sel_hi:[0,1,1]
	ds_read_b128 v[252:255], v112 offset:44736
	s_waitcnt vmcnt(25)
	v_lshlrev_b32_e32 v108, 16, v234
	v_and_b32_e32 v109, 0xffff0000, v234
	v_lshlrev_b32_e32 v246, 16, v235
	v_and_b32_e32 v247, 0xffff0000, v235
	v_lshlrev_b32_e32 v234, 16, v236
	v_and_b32_e32 v235, 0xffff0000, v236
	v_lshlrev_b32_e32 v236, 16, v237
	v_and_b32_e32 v237, 0xffff0000, v237
	s_waitcnt lgkmcnt(1)
	v_pk_fma_f32 v[8:9], v[250:251], v[108:109], v[8:9] op_sel:[1,0,0] op_sel_hi:[1,1,1]
	v_pk_fma_f32 v[32:33], v[248:249], v[108:109], v[32:33] op_sel_hi:[0,1,1]
	v_pk_fma_f32 v[22:23], v[248:249], v[108:109], v[22:23] op_sel:[1,0,0] op_sel_hi:[1,1,1]
	v_pk_fma_f32 v[16:17], v[250:251], v[108:109], v[16:17] op_sel_hi:[0,1,1]
	v_pk_fma_f32 v[4:5], v[250:251], v[246:247], v[4:5] op_sel:[1,0,0] op_sel_hi:[1,1,1]
	v_pk_fma_f32 v[30:31], v[248:249], v[246:247], v[30:31] op_sel_hi:[0,1,1]
	v_pk_fma_f32 v[20:21], v[248:249], v[246:247], v[20:21] op_sel:[1,0,0] op_sel_hi:[1,1,1]
	v_pk_fma_f32 v[12:13], v[250:251], v[246:247], v[12:13] op_sel_hi:[0,1,1]
	v_pk_fma_f32 v[2:3], v[250:251], v[234:235], v[2:3] op_sel:[1,0,0] op_sel_hi:[1,1,1]
	v_pk_fma_f32 v[26:27], v[248:249], v[234:235], v[26:27] op_sel_hi:[0,1,1]
	v_pk_fma_f32 v[18:19], v[248:249], v[234:235], v[18:19] op_sel:[1,0,0] op_sel_hi:[1,1,1]
	v_pk_fma_f32 v[10:11], v[250:251], v[234:235], v[10:11] op_sel_hi:[0,1,1]
	v_pk_fma_f32 v[0:1], v[250:251], v[236:237], v[0:1] op_sel:[1,0,0] op_sel_hi:[1,1,1]
	v_pk_fma_f32 v[24:25], v[248:249], v[236:237], v[24:25] op_sel_hi:[0,1,1]
	v_pk_fma_f32 v[14:15], v[248:249], v[236:237], v[14:15] op_sel:[1,0,0] op_sel_hi:[1,1,1]
	v_pk_fma_f32 v[6:7], v[250:251], v[236:237], v[6:7] op_sel_hi:[0,1,1]
	ds_read_b128 v[248:251], v112 offset:44800
	s_waitcnt vmcnt(24)
	v_lshlrev_b32_e32 v108, 16, v238
	v_and_b32_e32 v109, 0xffff0000, v238
	v_lshlrev_b32_e32 v246, 16, v239
	v_and_b32_e32 v247, 0xffff0000, v239
	v_lshlrev_b32_e32 v238, 16, v240
	v_and_b32_e32 v239, 0xffff0000, v240
	v_lshlrev_b32_e32 v240, 16, v241
	v_and_b32_e32 v241, 0xffff0000, v241
	s_waitcnt lgkmcnt(1)
	v_pk_fma_f32 v[8:9], v[254:255], v[108:109], v[8:9] op_sel:[1,0,0] op_sel_hi:[1,1,1]
	v_pk_fma_f32 v[32:33], v[252:253], v[108:109], v[32:33] op_sel_hi:[0,1,1]
	v_pk_fma_f32 v[22:23], v[252:253], v[108:109], v[22:23] op_sel:[1,0,0] op_sel_hi:[1,1,1]
	v_pk_fma_f32 v[16:17], v[254:255], v[108:109], v[16:17] op_sel_hi:[0,1,1]
	v_pk_fma_f32 v[4:5], v[254:255], v[246:247], v[4:5] op_sel:[1,0,0] op_sel_hi:[1,1,1]
	v_pk_fma_f32 v[30:31], v[252:253], v[246:247], v[30:31] op_sel_hi:[0,1,1]
	v_pk_fma_f32 v[20:21], v[252:253], v[246:247], v[20:21] op_sel:[1,0,0] op_sel_hi:[1,1,1]
	v_pk_fma_f32 v[12:13], v[254:255], v[246:247], v[12:13] op_sel_hi:[0,1,1]
	v_pk_fma_f32 v[2:3], v[254:255], v[238:239], v[2:3] op_sel:[1,0,0] op_sel_hi:[1,1,1]
	v_pk_fma_f32 v[26:27], v[252:253], v[238:239], v[26:27] op_sel_hi:[0,1,1]
	v_pk_fma_f32 v[18:19], v[252:253], v[238:239], v[18:19] op_sel:[1,0,0] op_sel_hi:[1,1,1]
	v_pk_fma_f32 v[10:11], v[254:255], v[238:239], v[10:11] op_sel_hi:[0,1,1]
	v_pk_fma_f32 v[0:1], v[254:255], v[240:241], v[0:1] op_sel:[1,0,0] op_sel_hi:[1,1,1]
	v_pk_fma_f32 v[24:25], v[252:253], v[240:241], v[24:25] op_sel_hi:[0,1,1]
	v_pk_fma_f32 v[14:15], v[252:253], v[240:241], v[14:15] op_sel:[1,0,0] op_sel_hi:[1,1,1]
	v_pk_fma_f32 v[6:7], v[254:255], v[240:241], v[6:7] op_sel_hi:[0,1,1]
	ds_read_b128 v[252:255], v112 offset:44864
	s_waitcnt vmcnt(23)
	v_lshlrev_b32_e32 v108, 16, v70
	v_and_b32_e32 v109, 0xffff0000, v70
	v_lshlrev_b32_e32 v246, 16, v71
	v_and_b32_e32 v247, 0xffff0000, v71
	v_lshlrev_b32_e32 v70, 16, v72
	v_and_b32_e32 v71, 0xffff0000, v72
	v_lshlrev_b32_e32 v72, 16, v73
	v_and_b32_e32 v73, 0xffff0000, v73
	s_waitcnt lgkmcnt(1)
	v_pk_fma_f32 v[8:9], v[250:251], v[108:109], v[8:9] op_sel:[1,0,0] op_sel_hi:[1,1,1]
	v_pk_fma_f32 v[32:33], v[248:249], v[108:109], v[32:33] op_sel_hi:[0,1,1]
	v_pk_fma_f32 v[22:23], v[248:249], v[108:109], v[22:23] op_sel:[1,0,0] op_sel_hi:[1,1,1]
	v_pk_fma_f32 v[16:17], v[250:251], v[108:109], v[16:17] op_sel_hi:[0,1,1]
	v_pk_fma_f32 v[4:5], v[250:251], v[246:247], v[4:5] op_sel:[1,0,0] op_sel_hi:[1,1,1]
	v_pk_fma_f32 v[30:31], v[248:249], v[246:247], v[30:31] op_sel_hi:[0,1,1]
	v_pk_fma_f32 v[20:21], v[248:249], v[246:247], v[20:21] op_sel:[1,0,0] op_sel_hi:[1,1,1]
	v_pk_fma_f32 v[12:13], v[250:251], v[246:247], v[12:13] op_sel_hi:[0,1,1]
	v_pk_fma_f32 v[2:3], v[250:251], v[70:71], v[2:3] op_sel:[1,0,0] op_sel_hi:[1,1,1]
	v_pk_fma_f32 v[26:27], v[248:249], v[70:71], v[26:27] op_sel_hi:[0,1,1]
	v_pk_fma_f32 v[18:19], v[248:249], v[70:71], v[18:19] op_sel:[1,0,0] op_sel_hi:[1,1,1]
	v_pk_fma_f32 v[10:11], v[250:251], v[70:71], v[10:11] op_sel_hi:[0,1,1]
	v_pk_fma_f32 v[0:1], v[250:251], v[72:73], v[0:1] op_sel:[1,0,0] op_sel_hi:[1,1,1]
	v_pk_fma_f32 v[24:25], v[248:249], v[72:73], v[24:25] op_sel_hi:[0,1,1]
	v_pk_fma_f32 v[14:15], v[248:249], v[72:73], v[14:15] op_sel:[1,0,0] op_sel_hi:[1,1,1]
	v_pk_fma_f32 v[6:7], v[250:251], v[72:73], v[6:7] op_sel_hi:[0,1,1]
	ds_read_b128 v[248:251], v112 offset:44928
	s_waitcnt vmcnt(22)
	v_lshlrev_b32_e32 v108, 16, v74
	v_and_b32_e32 v109, 0xffff0000, v74
	v_lshlrev_b32_e32 v246, 16, v75
	v_and_b32_e32 v247, 0xffff0000, v75
	v_lshlrev_b32_e32 v74, 16, v76
	v_and_b32_e32 v75, 0xffff0000, v76
	v_lshlrev_b32_e32 v76, 16, v77
	v_and_b32_e32 v77, 0xffff0000, v77
	s_waitcnt lgkmcnt(1)
	v_pk_fma_f32 v[8:9], v[254:255], v[108:109], v[8:9] op_sel:[1,0,0] op_sel_hi:[1,1,1]
	v_pk_fma_f32 v[32:33], v[252:253], v[108:109], v[32:33] op_sel_hi:[0,1,1]
	v_pk_fma_f32 v[22:23], v[252:253], v[108:109], v[22:23] op_sel:[1,0,0] op_sel_hi:[1,1,1]
	v_pk_fma_f32 v[16:17], v[254:255], v[108:109], v[16:17] op_sel_hi:[0,1,1]
	v_pk_fma_f32 v[4:5], v[254:255], v[246:247], v[4:5] op_sel:[1,0,0] op_sel_hi:[1,1,1]
	v_pk_fma_f32 v[30:31], v[252:253], v[246:247], v[30:31] op_sel_hi:[0,1,1]
	v_pk_fma_f32 v[20:21], v[252:253], v[246:247], v[20:21] op_sel:[1,0,0] op_sel_hi:[1,1,1]
	v_pk_fma_f32 v[12:13], v[254:255], v[246:247], v[12:13] op_sel_hi:[0,1,1]
	v_pk_fma_f32 v[2:3], v[254:255], v[74:75], v[2:3] op_sel:[1,0,0] op_sel_hi:[1,1,1]
	v_pk_fma_f32 v[26:27], v[252:253], v[74:75], v[26:27] op_sel_hi:[0,1,1]
	v_pk_fma_f32 v[18:19], v[252:253], v[74:75], v[18:19] op_sel:[1,0,0] op_sel_hi:[1,1,1]
	v_pk_fma_f32 v[10:11], v[254:255], v[74:75], v[10:11] op_sel_hi:[0,1,1]
	v_pk_fma_f32 v[0:1], v[254:255], v[76:77], v[0:1] op_sel:[1,0,0] op_sel_hi:[1,1,1]
	v_pk_fma_f32 v[24:25], v[252:253], v[76:77], v[24:25] op_sel_hi:[0,1,1]
	v_pk_fma_f32 v[14:15], v[252:253], v[76:77], v[14:15] op_sel:[1,0,0] op_sel_hi:[1,1,1]
	v_pk_fma_f32 v[6:7], v[254:255], v[76:77], v[6:7] op_sel_hi:[0,1,1]
	ds_read_b128 v[252:255], v112 offset:44992
	s_waitcnt vmcnt(21)
	v_lshlrev_b32_e32 v108, 16, v78
	v_and_b32_e32 v109, 0xffff0000, v78
	v_lshlrev_b32_e32 v246, 16, v79
	v_and_b32_e32 v247, 0xffff0000, v79
	v_lshlrev_b32_e32 v78, 16, v80
	v_and_b32_e32 v79, 0xffff0000, v80
	v_lshlrev_b32_e32 v80, 16, v81
	v_and_b32_e32 v81, 0xffff0000, v81
	s_waitcnt lgkmcnt(1)
	v_pk_fma_f32 v[8:9], v[250:251], v[108:109], v[8:9] op_sel:[1,0,0] op_sel_hi:[1,1,1]
	v_pk_fma_f32 v[32:33], v[248:249], v[108:109], v[32:33] op_sel_hi:[0,1,1]
	v_pk_fma_f32 v[22:23], v[248:249], v[108:109], v[22:23] op_sel:[1,0,0] op_sel_hi:[1,1,1]
	v_pk_fma_f32 v[16:17], v[250:251], v[108:109], v[16:17] op_sel_hi:[0,1,1]
	v_pk_fma_f32 v[4:5], v[250:251], v[246:247], v[4:5] op_sel:[1,0,0] op_sel_hi:[1,1,1]
	v_pk_fma_f32 v[30:31], v[248:249], v[246:247], v[30:31] op_sel_hi:[0,1,1]
	v_pk_fma_f32 v[20:21], v[248:249], v[246:247], v[20:21] op_sel:[1,0,0] op_sel_hi:[1,1,1]
	v_pk_fma_f32 v[12:13], v[250:251], v[246:247], v[12:13] op_sel_hi:[0,1,1]
	v_pk_fma_f32 v[2:3], v[250:251], v[78:79], v[2:3] op_sel:[1,0,0] op_sel_hi:[1,1,1]
	v_pk_fma_f32 v[26:27], v[248:249], v[78:79], v[26:27] op_sel_hi:[0,1,1]
	v_pk_fma_f32 v[18:19], v[248:249], v[78:79], v[18:19] op_sel:[1,0,0] op_sel_hi:[1,1,1]
	v_pk_fma_f32 v[10:11], v[250:251], v[78:79], v[10:11] op_sel_hi:[0,1,1]
	v_pk_fma_f32 v[0:1], v[250:251], v[80:81], v[0:1] op_sel:[1,0,0] op_sel_hi:[1,1,1]
	v_pk_fma_f32 v[24:25], v[248:249], v[80:81], v[24:25] op_sel_hi:[0,1,1]
	v_pk_fma_f32 v[14:15], v[248:249], v[80:81], v[14:15] op_sel:[1,0,0] op_sel_hi:[1,1,1]
	v_pk_fma_f32 v[6:7], v[250:251], v[80:81], v[6:7] op_sel_hi:[0,1,1]
	ds_read_b128 v[248:251], v112 offset:45056
	s_waitcnt vmcnt(20)
	v_lshlrev_b32_e32 v108, 16, v82
	v_and_b32_e32 v109, 0xffff0000, v82
	v_lshlrev_b32_e32 v246, 16, v83
	v_and_b32_e32 v247, 0xffff0000, v83
	v_lshlrev_b32_e32 v82, 16, v84
	v_and_b32_e32 v83, 0xffff0000, v84
	v_lshlrev_b32_e32 v84, 16, v85
	v_and_b32_e32 v85, 0xffff0000, v85
	s_waitcnt lgkmcnt(1)
	v_pk_fma_f32 v[8:9], v[254:255], v[108:109], v[8:9] op_sel:[1,0,0] op_sel_hi:[1,1,1]
	v_pk_fma_f32 v[32:33], v[252:253], v[108:109], v[32:33] op_sel_hi:[0,1,1]
	v_pk_fma_f32 v[22:23], v[252:253], v[108:109], v[22:23] op_sel:[1,0,0] op_sel_hi:[1,1,1]
	v_pk_fma_f32 v[16:17], v[254:255], v[108:109], v[16:17] op_sel_hi:[0,1,1]
	v_pk_fma_f32 v[4:5], v[254:255], v[246:247], v[4:5] op_sel:[1,0,0] op_sel_hi:[1,1,1]
	v_pk_fma_f32 v[30:31], v[252:253], v[246:247], v[30:31] op_sel_hi:[0,1,1]
	v_pk_fma_f32 v[20:21], v[252:253], v[246:247], v[20:21] op_sel:[1,0,0] op_sel_hi:[1,1,1]
	v_pk_fma_f32 v[12:13], v[254:255], v[246:247], v[12:13] op_sel_hi:[0,1,1]
	v_pk_fma_f32 v[2:3], v[254:255], v[82:83], v[2:3] op_sel:[1,0,0] op_sel_hi:[1,1,1]
	v_pk_fma_f32 v[26:27], v[252:253], v[82:83], v[26:27] op_sel_hi:[0,1,1]
	v_pk_fma_f32 v[18:19], v[252:253], v[82:83], v[18:19] op_sel:[1,0,0] op_sel_hi:[1,1,1]
	v_pk_fma_f32 v[10:11], v[254:255], v[82:83], v[10:11] op_sel_hi:[0,1,1]
	v_pk_fma_f32 v[0:1], v[254:255], v[84:85], v[0:1] op_sel:[1,0,0] op_sel_hi:[1,1,1]
	v_pk_fma_f32 v[24:25], v[252:253], v[84:85], v[24:25] op_sel_hi:[0,1,1]
	v_pk_fma_f32 v[14:15], v[252:253], v[84:85], v[14:15] op_sel:[1,0,0] op_sel_hi:[1,1,1]
	v_pk_fma_f32 v[6:7], v[254:255], v[84:85], v[6:7] op_sel_hi:[0,1,1]
	ds_read_b128 v[252:255], v112 offset:45120
	s_waitcnt vmcnt(19)
	v_lshlrev_b32_e32 v108, 16, v86
	v_and_b32_e32 v109, 0xffff0000, v86
	v_lshlrev_b32_e32 v246, 16, v87
	v_and_b32_e32 v247, 0xffff0000, v87
	v_lshlrev_b32_e32 v86, 16, v88
	v_and_b32_e32 v87, 0xffff0000, v88
	v_lshlrev_b32_e32 v88, 16, v89
	v_and_b32_e32 v89, 0xffff0000, v89
	s_waitcnt lgkmcnt(1)
	v_pk_fma_f32 v[8:9], v[250:251], v[108:109], v[8:9] op_sel:[1,0,0] op_sel_hi:[1,1,1]
	v_pk_fma_f32 v[32:33], v[248:249], v[108:109], v[32:33] op_sel_hi:[0,1,1]
	v_pk_fma_f32 v[22:23], v[248:249], v[108:109], v[22:23] op_sel:[1,0,0] op_sel_hi:[1,1,1]
	v_pk_fma_f32 v[16:17], v[250:251], v[108:109], v[16:17] op_sel_hi:[0,1,1]
	v_pk_fma_f32 v[4:5], v[250:251], v[246:247], v[4:5] op_sel:[1,0,0] op_sel_hi:[1,1,1]
	v_pk_fma_f32 v[30:31], v[248:249], v[246:247], v[30:31] op_sel_hi:[0,1,1]
	v_pk_fma_f32 v[20:21], v[248:249], v[246:247], v[20:21] op_sel:[1,0,0] op_sel_hi:[1,1,1]
	v_pk_fma_f32 v[12:13], v[250:251], v[246:247], v[12:13] op_sel_hi:[0,1,1]
	v_pk_fma_f32 v[2:3], v[250:251], v[86:87], v[2:3] op_sel:[1,0,0] op_sel_hi:[1,1,1]
	v_pk_fma_f32 v[26:27], v[248:249], v[86:87], v[26:27] op_sel_hi:[0,1,1]
	v_pk_fma_f32 v[18:19], v[248:249], v[86:87], v[18:19] op_sel:[1,0,0] op_sel_hi:[1,1,1]
	v_pk_fma_f32 v[10:11], v[250:251], v[86:87], v[10:11] op_sel_hi:[0,1,1]
	v_pk_fma_f32 v[0:1], v[250:251], v[88:89], v[0:1] op_sel:[1,0,0] op_sel_hi:[1,1,1]
	v_pk_fma_f32 v[24:25], v[248:249], v[88:89], v[24:25] op_sel_hi:[0,1,1]
	v_pk_fma_f32 v[14:15], v[248:249], v[88:89], v[14:15] op_sel:[1,0,0] op_sel_hi:[1,1,1]
	v_pk_fma_f32 v[6:7], v[250:251], v[88:89], v[6:7] op_sel_hi:[0,1,1]
	ds_read_b128 v[248:251], v112 offset:45184
	s_waitcnt vmcnt(18)
	v_lshlrev_b32_e32 v108, 16, v90
	v_and_b32_e32 v109, 0xffff0000, v90
	v_lshlrev_b32_e32 v246, 16, v91
	v_and_b32_e32 v247, 0xffff0000, v91
	v_lshlrev_b32_e32 v90, 16, v92
	v_and_b32_e32 v91, 0xffff0000, v92
	v_lshlrev_b32_e32 v92, 16, v93
	v_and_b32_e32 v93, 0xffff0000, v93
	s_waitcnt lgkmcnt(1)
	v_pk_fma_f32 v[8:9], v[254:255], v[108:109], v[8:9] op_sel:[1,0,0] op_sel_hi:[1,1,1]
	v_pk_fma_f32 v[32:33], v[252:253], v[108:109], v[32:33] op_sel_hi:[0,1,1]
	v_pk_fma_f32 v[22:23], v[252:253], v[108:109], v[22:23] op_sel:[1,0,0] op_sel_hi:[1,1,1]
	v_pk_fma_f32 v[16:17], v[254:255], v[108:109], v[16:17] op_sel_hi:[0,1,1]
	v_pk_fma_f32 v[4:5], v[254:255], v[246:247], v[4:5] op_sel:[1,0,0] op_sel_hi:[1,1,1]
	v_pk_fma_f32 v[30:31], v[252:253], v[246:247], v[30:31] op_sel_hi:[0,1,1]
	v_pk_fma_f32 v[20:21], v[252:253], v[246:247], v[20:21] op_sel:[1,0,0] op_sel_hi:[1,1,1]
	v_pk_fma_f32 v[12:13], v[254:255], v[246:247], v[12:13] op_sel_hi:[0,1,1]
	v_pk_fma_f32 v[2:3], v[254:255], v[90:91], v[2:3] op_sel:[1,0,0] op_sel_hi:[1,1,1]
	v_pk_fma_f32 v[26:27], v[252:253], v[90:91], v[26:27] op_sel_hi:[0,1,1]
	v_pk_fma_f32 v[18:19], v[252:253], v[90:91], v[18:19] op_sel:[1,0,0] op_sel_hi:[1,1,1]
	v_pk_fma_f32 v[10:11], v[254:255], v[90:91], v[10:11] op_sel_hi:[0,1,1]
	v_pk_fma_f32 v[0:1], v[254:255], v[92:93], v[0:1] op_sel:[1,0,0] op_sel_hi:[1,1,1]
	v_pk_fma_f32 v[24:25], v[252:253], v[92:93], v[24:25] op_sel_hi:[0,1,1]
	v_pk_fma_f32 v[14:15], v[252:253], v[92:93], v[14:15] op_sel:[1,0,0] op_sel_hi:[1,1,1]
	v_pk_fma_f32 v[6:7], v[254:255], v[92:93], v[6:7] op_sel_hi:[0,1,1]
	ds_read_b128 v[252:255], v112 offset:45248
	s_waitcnt vmcnt(17)
	v_lshlrev_b32_e32 v108, 16, v94
	v_and_b32_e32 v109, 0xffff0000, v94
	v_lshlrev_b32_e32 v246, 16, v95
	v_and_b32_e32 v247, 0xffff0000, v95
	v_lshlrev_b32_e32 v94, 16, v96
	v_and_b32_e32 v95, 0xffff0000, v96
	v_lshlrev_b32_e32 v96, 16, v97
	v_and_b32_e32 v97, 0xffff0000, v97
	s_waitcnt lgkmcnt(1)
	v_pk_fma_f32 v[8:9], v[250:251], v[108:109], v[8:9] op_sel:[1,0,0] op_sel_hi:[1,1,1]
	v_pk_fma_f32 v[32:33], v[248:249], v[108:109], v[32:33] op_sel_hi:[0,1,1]
	v_pk_fma_f32 v[22:23], v[248:249], v[108:109], v[22:23] op_sel:[1,0,0] op_sel_hi:[1,1,1]
	v_pk_fma_f32 v[16:17], v[250:251], v[108:109], v[16:17] op_sel_hi:[0,1,1]
	v_pk_fma_f32 v[4:5], v[250:251], v[246:247], v[4:5] op_sel:[1,0,0] op_sel_hi:[1,1,1]
	v_pk_fma_f32 v[30:31], v[248:249], v[246:247], v[30:31] op_sel_hi:[0,1,1]
	v_pk_fma_f32 v[20:21], v[248:249], v[246:247], v[20:21] op_sel:[1,0,0] op_sel_hi:[1,1,1]
	v_pk_fma_f32 v[12:13], v[250:251], v[246:247], v[12:13] op_sel_hi:[0,1,1]
	v_pk_fma_f32 v[2:3], v[250:251], v[94:95], v[2:3] op_sel:[1,0,0] op_sel_hi:[1,1,1]
	v_pk_fma_f32 v[26:27], v[248:249], v[94:95], v[26:27] op_sel_hi:[0,1,1]
	v_pk_fma_f32 v[18:19], v[248:249], v[94:95], v[18:19] op_sel:[1,0,0] op_sel_hi:[1,1,1]
	v_pk_fma_f32 v[10:11], v[250:251], v[94:95], v[10:11] op_sel_hi:[0,1,1]
	v_pk_fma_f32 v[0:1], v[250:251], v[96:97], v[0:1] op_sel:[1,0,0] op_sel_hi:[1,1,1]
	v_pk_fma_f32 v[24:25], v[248:249], v[96:97], v[24:25] op_sel_hi:[0,1,1]
	v_pk_fma_f32 v[14:15], v[248:249], v[96:97], v[14:15] op_sel:[1,0,0] op_sel_hi:[1,1,1]
	v_pk_fma_f32 v[6:7], v[250:251], v[96:97], v[6:7] op_sel_hi:[0,1,1]
	s_waitcnt vmcnt(16)
	v_lshlrev_b32_e32 v108, 16, v98
	v_and_b32_e32 v109, 0xffff0000, v98
	v_lshlrev_b32_e32 v246, 16, v99
	v_and_b32_e32 v247, 0xffff0000, v99
	v_lshlrev_b32_e32 v98, 16, v100
	v_and_b32_e32 v99, 0xffff0000, v100
	v_lshlrev_b32_e32 v100, 16, v101
	v_and_b32_e32 v101, 0xffff0000, v101
	s_waitcnt lgkmcnt(0)
	v_pk_fma_f32 v[8:9], v[254:255], v[108:109], v[8:9] op_sel:[1,0,0] op_sel_hi:[1,1,1]
	v_pk_fma_f32 v[32:33], v[252:253], v[108:109], v[32:33] op_sel_hi:[0,1,1]
	v_pk_fma_f32 v[22:23], v[252:253], v[108:109], v[22:23] op_sel:[1,0,0] op_sel_hi:[1,1,1]
	v_pk_fma_f32 v[16:17], v[254:255], v[108:109], v[16:17] op_sel_hi:[0,1,1]
	v_pk_fma_f32 v[4:5], v[254:255], v[246:247], v[4:5] op_sel:[1,0,0] op_sel_hi:[1,1,1]
	v_pk_fma_f32 v[30:31], v[252:253], v[246:247], v[30:31] op_sel_hi:[0,1,1]
	v_pk_fma_f32 v[20:21], v[252:253], v[246:247], v[20:21] op_sel:[1,0,0] op_sel_hi:[1,1,1]
	v_pk_fma_f32 v[12:13], v[254:255], v[246:247], v[12:13] op_sel_hi:[0,1,1]
	v_pk_fma_f32 v[2:3], v[254:255], v[98:99], v[2:3] op_sel:[1,0,0] op_sel_hi:[1,1,1]
	v_pk_fma_f32 v[26:27], v[252:253], v[98:99], v[26:27] op_sel_hi:[0,1,1]
	v_pk_fma_f32 v[18:19], v[252:253], v[98:99], v[18:19] op_sel:[1,0,0] op_sel_hi:[1,1,1]
	v_pk_fma_f32 v[10:11], v[254:255], v[98:99], v[10:11] op_sel_hi:[0,1,1]
	v_pk_fma_f32 v[0:1], v[254:255], v[100:101], v[0:1] op_sel:[1,0,0] op_sel_hi:[1,1,1]
	v_pk_fma_f32 v[24:25], v[252:253], v[100:101], v[24:25] op_sel_hi:[0,1,1]
	v_pk_fma_f32 v[14:15], v[252:253], v[100:101], v[14:15] op_sel:[1,0,0] op_sel_hi:[1,1,1]
	v_pk_fma_f32 v[6:7], v[254:255], v[100:101], v[6:7] op_sel_hi:[0,1,1]
	ds_read_b32 v34, v56 offset:7168
	ds_read_b32 v35, v56 offset:7184
	ds_read_b32 v36, v56 offset:7200
	ds_read_b32 v37, v56 offset:7216
	ds_read_b32 v38, v56 offset:7232
	ds_read_b32 v39, v56 offset:7248
	ds_read_b32 v40, v56 offset:7264
	ds_read_b32 v41, v56 offset:7280
	ds_read_b32 v42, v56 offset:7296
	ds_read_b32 v43, v56 offset:7312
	ds_read_b32 v44, v56 offset:7328
	ds_read_b32 v45, v56 offset:7344
	ds_read_b32 v46, v56 offset:7360
	ds_read_b32 v47, v56 offset:7376
	ds_read_b32 v48, v56 offset:7392
	ds_read_b32 v49, v56 offset:7408
	s_waitcnt lgkmcnt(15)
	v_lshl_add_u32 v34, v34, 9, v102
	global_load_dwordx4 v[210:213], v34, s[0:1]
	s_waitcnt lgkmcnt(14)
	v_lshl_add_u32 v35, v35, 9, v102
	global_load_dwordx4 v[214:217], v35, s[0:1]
	s_waitcnt lgkmcnt(13)
	v_lshl_add_u32 v36, v36, 9, v102
	global_load_dwordx4 v[218:221], v36, s[0:1]
	s_waitcnt lgkmcnt(12)
	v_lshl_add_u32 v37, v37, 9, v102
	global_load_dwordx4 v[222:225], v37, s[0:1]
	s_waitcnt lgkmcnt(11)
	v_lshl_add_u32 v38, v38, 9, v102
	global_load_dwordx4 v[226:229], v38, s[0:1]
	s_waitcnt lgkmcnt(10)
	v_lshl_add_u32 v39, v39, 9, v102
	global_load_dwordx4 v[230:233], v39, s[0:1]
	s_waitcnt lgkmcnt(9)
	v_lshl_add_u32 v40, v40, 9, v102
	global_load_dwordx4 v[234:237], v40, s[0:1]
	s_waitcnt lgkmcnt(8)
	v_lshl_add_u32 v41, v41, 9, v102
	global_load_dwordx4 v[238:241], v41, s[0:1]
	s_waitcnt lgkmcnt(7)
	v_lshl_add_u32 v42, v42, 9, v102
	global_load_dwordx4 v[70:73], v42, s[0:1]
	s_waitcnt lgkmcnt(6)
	v_lshl_add_u32 v43, v43, 9, v102
	global_load_dwordx4 v[74:77], v43, s[0:1]
	s_waitcnt lgkmcnt(5)
	v_lshl_add_u32 v44, v44, 9, v102
	global_load_dwordx4 v[78:81], v44, s[0:1]
	s_waitcnt lgkmcnt(4)
	v_lshl_add_u32 v45, v45, 9, v102
	global_load_dwordx4 v[82:85], v45, s[0:1]
	s_waitcnt lgkmcnt(3)
	v_lshl_add_u32 v46, v46, 9, v102
	global_load_dwordx4 v[86:89], v46, s[0:1]
	s_waitcnt lgkmcnt(2)
	v_lshl_add_u32 v47, v47, 9, v102
	global_load_dwordx4 v[90:93], v47, s[0:1]
	s_waitcnt lgkmcnt(1)
	v_lshl_add_u32 v48, v48, 9, v102
	global_load_dwordx4 v[94:97], v48, s[0:1]
	s_waitcnt lgkmcnt(0)
	v_lshl_add_u32 v49, v49, 9, v102
	global_load_dwordx4 v[98:101], v49, s[0:1]
	ds_read_b128 v[248:251], v112 offset:45312
	ds_read_b128 v[252:255], v112 offset:45376
	s_waitcnt vmcnt(31)
	v_lshlrev_b32_e32 v108, 16, v130
	v_and_b32_e32 v109, 0xffff0000, v130
	v_lshlrev_b32_e32 v246, 16, v131
	v_and_b32_e32 v247, 0xffff0000, v131
	v_lshlrev_b32_e32 v130, 16, v132
	v_and_b32_e32 v131, 0xffff0000, v132
	v_lshlrev_b32_e32 v132, 16, v133
	v_and_b32_e32 v133, 0xffff0000, v133
	s_waitcnt lgkmcnt(1)
	v_pk_fma_f32 v[8:9], v[250:251], v[108:109], v[8:9] op_sel:[1,0,0] op_sel_hi:[1,1,1]
	v_pk_fma_f32 v[32:33], v[248:249], v[108:109], v[32:33] op_sel_hi:[0,1,1]
	v_pk_fma_f32 v[22:23], v[248:249], v[108:109], v[22:23] op_sel:[1,0,0] op_sel_hi:[1,1,1]
	v_pk_fma_f32 v[16:17], v[250:251], v[108:109], v[16:17] op_sel_hi:[0,1,1]
	v_pk_fma_f32 v[4:5], v[250:251], v[246:247], v[4:5] op_sel:[1,0,0] op_sel_hi:[1,1,1]
	v_pk_fma_f32 v[30:31], v[248:249], v[246:247], v[30:31] op_sel_hi:[0,1,1]
	v_pk_fma_f32 v[20:21], v[248:249], v[246:247], v[20:21] op_sel:[1,0,0] op_sel_hi:[1,1,1]
	v_pk_fma_f32 v[12:13], v[250:251], v[246:247], v[12:13] op_sel_hi:[0,1,1]
	v_pk_fma_f32 v[2:3], v[250:251], v[130:131], v[2:3] op_sel:[1,0,0] op_sel_hi:[1,1,1]
	v_pk_fma_f32 v[26:27], v[248:249], v[130:131], v[26:27] op_sel_hi:[0,1,1]
	v_pk_fma_f32 v[18:19], v[248:249], v[130:131], v[18:19] op_sel:[1,0,0] op_sel_hi:[1,1,1]
	v_pk_fma_f32 v[10:11], v[250:251], v[130:131], v[10:11] op_sel_hi:[0,1,1]
	v_pk_fma_f32 v[0:1], v[250:251], v[132:133], v[0:1] op_sel:[1,0,0] op_sel_hi:[1,1,1]
	v_pk_fma_f32 v[24:25], v[248:249], v[132:133], v[24:25] op_sel_hi:[0,1,1]
	v_pk_fma_f32 v[14:15], v[248:249], v[132:133], v[14:15] op_sel:[1,0,0] op_sel_hi:[1,1,1]
	v_pk_fma_f32 v[6:7], v[250:251], v[132:133], v[6:7] op_sel_hi:[0,1,1]
	ds_read_b128 v[248:251], v112 offset:45440
	s_waitcnt vmcnt(30)
	v_lshlrev_b32_e32 v108, 16, v134
	v_and_b32_e32 v109, 0xffff0000, v134
	v_lshlrev_b32_e32 v246, 16, v135
	v_and_b32_e32 v247, 0xffff0000, v135
	v_lshlrev_b32_e32 v134, 16, v136
	v_and_b32_e32 v135, 0xffff0000, v136
	v_lshlrev_b32_e32 v136, 16, v137
	v_and_b32_e32 v137, 0xffff0000, v137
	s_waitcnt lgkmcnt(1)
	v_pk_fma_f32 v[8:9], v[254:255], v[108:109], v[8:9] op_sel:[1,0,0] op_sel_hi:[1,1,1]
	v_pk_fma_f32 v[32:33], v[252:253], v[108:109], v[32:33] op_sel_hi:[0,1,1]
	v_pk_fma_f32 v[22:23], v[252:253], v[108:109], v[22:23] op_sel:[1,0,0] op_sel_hi:[1,1,1]
	v_pk_fma_f32 v[16:17], v[254:255], v[108:109], v[16:17] op_sel_hi:[0,1,1]
	v_pk_fma_f32 v[4:5], v[254:255], v[246:247], v[4:5] op_sel:[1,0,0] op_sel_hi:[1,1,1]
	v_pk_fma_f32 v[30:31], v[252:253], v[246:247], v[30:31] op_sel_hi:[0,1,1]
	v_pk_fma_f32 v[20:21], v[252:253], v[246:247], v[20:21] op_sel:[1,0,0] op_sel_hi:[1,1,1]
	v_pk_fma_f32 v[12:13], v[254:255], v[246:247], v[12:13] op_sel_hi:[0,1,1]
	v_pk_fma_f32 v[2:3], v[254:255], v[134:135], v[2:3] op_sel:[1,0,0] op_sel_hi:[1,1,1]
	v_pk_fma_f32 v[26:27], v[252:253], v[134:135], v[26:27] op_sel_hi:[0,1,1]
	v_pk_fma_f32 v[18:19], v[252:253], v[134:135], v[18:19] op_sel:[1,0,0] op_sel_hi:[1,1,1]
	v_pk_fma_f32 v[10:11], v[254:255], v[134:135], v[10:11] op_sel_hi:[0,1,1]
	v_pk_fma_f32 v[0:1], v[254:255], v[136:137], v[0:1] op_sel:[1,0,0] op_sel_hi:[1,1,1]
	v_pk_fma_f32 v[24:25], v[252:253], v[136:137], v[24:25] op_sel_hi:[0,1,1]
	v_pk_fma_f32 v[14:15], v[252:253], v[136:137], v[14:15] op_sel:[1,0,0] op_sel_hi:[1,1,1]
	v_pk_fma_f32 v[6:7], v[254:255], v[136:137], v[6:7] op_sel_hi:[0,1,1]
	ds_read_b128 v[252:255], v112 offset:45504
	s_waitcnt vmcnt(29)
	v_lshlrev_b32_e32 v108, 16, v138
	v_and_b32_e32 v109, 0xffff0000, v138
	v_lshlrev_b32_e32 v246, 16, v139
	v_and_b32_e32 v247, 0xffff0000, v139
	v_lshlrev_b32_e32 v138, 16, v140
	v_and_b32_e32 v139, 0xffff0000, v140
	v_lshlrev_b32_e32 v140, 16, v141
	v_and_b32_e32 v141, 0xffff0000, v141
	s_waitcnt lgkmcnt(1)
	v_pk_fma_f32 v[8:9], v[250:251], v[108:109], v[8:9] op_sel:[1,0,0] op_sel_hi:[1,1,1]
	v_pk_fma_f32 v[32:33], v[248:249], v[108:109], v[32:33] op_sel_hi:[0,1,1]
	v_pk_fma_f32 v[22:23], v[248:249], v[108:109], v[22:23] op_sel:[1,0,0] op_sel_hi:[1,1,1]
	v_pk_fma_f32 v[16:17], v[250:251], v[108:109], v[16:17] op_sel_hi:[0,1,1]
	v_pk_fma_f32 v[4:5], v[250:251], v[246:247], v[4:5] op_sel:[1,0,0] op_sel_hi:[1,1,1]
	v_pk_fma_f32 v[30:31], v[248:249], v[246:247], v[30:31] op_sel_hi:[0,1,1]
	v_pk_fma_f32 v[20:21], v[248:249], v[246:247], v[20:21] op_sel:[1,0,0] op_sel_hi:[1,1,1]
	v_pk_fma_f32 v[12:13], v[250:251], v[246:247], v[12:13] op_sel_hi:[0,1,1]
	v_pk_fma_f32 v[2:3], v[250:251], v[138:139], v[2:3] op_sel:[1,0,0] op_sel_hi:[1,1,1]
	v_pk_fma_f32 v[26:27], v[248:249], v[138:139], v[26:27] op_sel_hi:[0,1,1]
	v_pk_fma_f32 v[18:19], v[248:249], v[138:139], v[18:19] op_sel:[1,0,0] op_sel_hi:[1,1,1]
	v_pk_fma_f32 v[10:11], v[250:251], v[138:139], v[10:11] op_sel_hi:[0,1,1]
	v_pk_fma_f32 v[0:1], v[250:251], v[140:141], v[0:1] op_sel:[1,0,0] op_sel_hi:[1,1,1]
	v_pk_fma_f32 v[24:25], v[248:249], v[140:141], v[24:25] op_sel_hi:[0,1,1]
	v_pk_fma_f32 v[14:15], v[248:249], v[140:141], v[14:15] op_sel:[1,0,0] op_sel_hi:[1,1,1]
	v_pk_fma_f32 v[6:7], v[250:251], v[140:141], v[6:7] op_sel_hi:[0,1,1]
	ds_read_b128 v[248:251], v112 offset:45568
	s_waitcnt vmcnt(28)
	v_lshlrev_b32_e32 v108, 16, v142
	v_and_b32_e32 v109, 0xffff0000, v142
	v_lshlrev_b32_e32 v246, 16, v143
	v_and_b32_e32 v247, 0xffff0000, v143
	v_lshlrev_b32_e32 v142, 16, v144
	v_and_b32_e32 v143, 0xffff0000, v144
	v_lshlrev_b32_e32 v144, 16, v145
	v_and_b32_e32 v145, 0xffff0000, v145
	s_waitcnt lgkmcnt(1)
	v_pk_fma_f32 v[8:9], v[254:255], v[108:109], v[8:9] op_sel:[1,0,0] op_sel_hi:[1,1,1]
	v_pk_fma_f32 v[32:33], v[252:253], v[108:109], v[32:33] op_sel_hi:[0,1,1]
	v_pk_fma_f32 v[22:23], v[252:253], v[108:109], v[22:23] op_sel:[1,0,0] op_sel_hi:[1,1,1]
	v_pk_fma_f32 v[16:17], v[254:255], v[108:109], v[16:17] op_sel_hi:[0,1,1]
	v_pk_fma_f32 v[4:5], v[254:255], v[246:247], v[4:5] op_sel:[1,0,0] op_sel_hi:[1,1,1]
	v_pk_fma_f32 v[30:31], v[252:253], v[246:247], v[30:31] op_sel_hi:[0,1,1]
	v_pk_fma_f32 v[20:21], v[252:253], v[246:247], v[20:21] op_sel:[1,0,0] op_sel_hi:[1,1,1]
	v_pk_fma_f32 v[12:13], v[254:255], v[246:247], v[12:13] op_sel_hi:[0,1,1]
	v_pk_fma_f32 v[2:3], v[254:255], v[142:143], v[2:3] op_sel:[1,0,0] op_sel_hi:[1,1,1]
	v_pk_fma_f32 v[26:27], v[252:253], v[142:143], v[26:27] op_sel_hi:[0,1,1]
	v_pk_fma_f32 v[18:19], v[252:253], v[142:143], v[18:19] op_sel:[1,0,0] op_sel_hi:[1,1,1]
	v_pk_fma_f32 v[10:11], v[254:255], v[142:143], v[10:11] op_sel_hi:[0,1,1]
	v_pk_fma_f32 v[0:1], v[254:255], v[144:145], v[0:1] op_sel:[1,0,0] op_sel_hi:[1,1,1]
	v_pk_fma_f32 v[24:25], v[252:253], v[144:145], v[24:25] op_sel_hi:[0,1,1]
	v_pk_fma_f32 v[14:15], v[252:253], v[144:145], v[14:15] op_sel:[1,0,0] op_sel_hi:[1,1,1]
	v_pk_fma_f32 v[6:7], v[254:255], v[144:145], v[6:7] op_sel_hi:[0,1,1]
	ds_read_b128 v[252:255], v112 offset:45632
	s_waitcnt vmcnt(27)
	v_lshlrev_b32_e32 v108, 16, v146
	v_and_b32_e32 v109, 0xffff0000, v146
	v_lshlrev_b32_e32 v246, 16, v147
	v_and_b32_e32 v247, 0xffff0000, v147
	v_lshlrev_b32_e32 v146, 16, v148
	v_and_b32_e32 v147, 0xffff0000, v148
	v_lshlrev_b32_e32 v148, 16, v149
	v_and_b32_e32 v149, 0xffff0000, v149
	s_waitcnt lgkmcnt(1)
	v_pk_fma_f32 v[8:9], v[250:251], v[108:109], v[8:9] op_sel:[1,0,0] op_sel_hi:[1,1,1]
	v_pk_fma_f32 v[32:33], v[248:249], v[108:109], v[32:33] op_sel_hi:[0,1,1]
	v_pk_fma_f32 v[22:23], v[248:249], v[108:109], v[22:23] op_sel:[1,0,0] op_sel_hi:[1,1,1]
	v_pk_fma_f32 v[16:17], v[250:251], v[108:109], v[16:17] op_sel_hi:[0,1,1]
	v_pk_fma_f32 v[4:5], v[250:251], v[246:247], v[4:5] op_sel:[1,0,0] op_sel_hi:[1,1,1]
	v_pk_fma_f32 v[30:31], v[248:249], v[246:247], v[30:31] op_sel_hi:[0,1,1]
	v_pk_fma_f32 v[20:21], v[248:249], v[246:247], v[20:21] op_sel:[1,0,0] op_sel_hi:[1,1,1]
	v_pk_fma_f32 v[12:13], v[250:251], v[246:247], v[12:13] op_sel_hi:[0,1,1]
	v_pk_fma_f32 v[2:3], v[250:251], v[146:147], v[2:3] op_sel:[1,0,0] op_sel_hi:[1,1,1]
	v_pk_fma_f32 v[26:27], v[248:249], v[146:147], v[26:27] op_sel_hi:[0,1,1]
	v_pk_fma_f32 v[18:19], v[248:249], v[146:147], v[18:19] op_sel:[1,0,0] op_sel_hi:[1,1,1]
	v_pk_fma_f32 v[10:11], v[250:251], v[146:147], v[10:11] op_sel_hi:[0,1,1]
	v_pk_fma_f32 v[0:1], v[250:251], v[148:149], v[0:1] op_sel:[1,0,0] op_sel_hi:[1,1,1]
	v_pk_fma_f32 v[24:25], v[248:249], v[148:149], v[24:25] op_sel_hi:[0,1,1]
	v_pk_fma_f32 v[14:15], v[248:249], v[148:149], v[14:15] op_sel:[1,0,0] op_sel_hi:[1,1,1]
	v_pk_fma_f32 v[6:7], v[250:251], v[148:149], v[6:7] op_sel_hi:[0,1,1]
	ds_read_b128 v[248:251], v112 offset:45696
	s_waitcnt vmcnt(26)
	v_lshlrev_b32_e32 v108, 16, v150
	v_and_b32_e32 v109, 0xffff0000, v150
	v_lshlrev_b32_e32 v246, 16, v151
	v_and_b32_e32 v247, 0xffff0000, v151
	v_lshlrev_b32_e32 v150, 16, v152
	v_and_b32_e32 v151, 0xffff0000, v152
	v_lshlrev_b32_e32 v152, 16, v153
	v_and_b32_e32 v153, 0xffff0000, v153
	s_waitcnt lgkmcnt(1)
	v_pk_fma_f32 v[8:9], v[254:255], v[108:109], v[8:9] op_sel:[1,0,0] op_sel_hi:[1,1,1]
	v_pk_fma_f32 v[32:33], v[252:253], v[108:109], v[32:33] op_sel_hi:[0,1,1]
	v_pk_fma_f32 v[22:23], v[252:253], v[108:109], v[22:23] op_sel:[1,0,0] op_sel_hi:[1,1,1]
	v_pk_fma_f32 v[16:17], v[254:255], v[108:109], v[16:17] op_sel_hi:[0,1,1]
	v_pk_fma_f32 v[4:5], v[254:255], v[246:247], v[4:5] op_sel:[1,0,0] op_sel_hi:[1,1,1]
	v_pk_fma_f32 v[30:31], v[252:253], v[246:247], v[30:31] op_sel_hi:[0,1,1]
	v_pk_fma_f32 v[20:21], v[252:253], v[246:247], v[20:21] op_sel:[1,0,0] op_sel_hi:[1,1,1]
	v_pk_fma_f32 v[12:13], v[254:255], v[246:247], v[12:13] op_sel_hi:[0,1,1]
	v_pk_fma_f32 v[2:3], v[254:255], v[150:151], v[2:3] op_sel:[1,0,0] op_sel_hi:[1,1,1]
	v_pk_fma_f32 v[26:27], v[252:253], v[150:151], v[26:27] op_sel_hi:[0,1,1]
	v_pk_fma_f32 v[18:19], v[252:253], v[150:151], v[18:19] op_sel:[1,0,0] op_sel_hi:[1,1,1]
	v_pk_fma_f32 v[10:11], v[254:255], v[150:151], v[10:11] op_sel_hi:[0,1,1]
	v_pk_fma_f32 v[0:1], v[254:255], v[152:153], v[0:1] op_sel:[1,0,0] op_sel_hi:[1,1,1]
	v_pk_fma_f32 v[24:25], v[252:253], v[152:153], v[24:25] op_sel_hi:[0,1,1]
	v_pk_fma_f32 v[14:15], v[252:253], v[152:153], v[14:15] op_sel:[1,0,0] op_sel_hi:[1,1,1]
	v_pk_fma_f32 v[6:7], v[254:255], v[152:153], v[6:7] op_sel_hi:[0,1,1]
	ds_read_b128 v[252:255], v112 offset:45760
	s_waitcnt vmcnt(25)
	v_lshlrev_b32_e32 v108, 16, v154
	v_and_b32_e32 v109, 0xffff0000, v154
	v_lshlrev_b32_e32 v246, 16, v155
	v_and_b32_e32 v247, 0xffff0000, v155
	v_lshlrev_b32_e32 v154, 16, v156
	v_and_b32_e32 v155, 0xffff0000, v156
	v_lshlrev_b32_e32 v156, 16, v157
	v_and_b32_e32 v157, 0xffff0000, v157
	s_waitcnt lgkmcnt(1)
	v_pk_fma_f32 v[8:9], v[250:251], v[108:109], v[8:9] op_sel:[1,0,0] op_sel_hi:[1,1,1]
	v_pk_fma_f32 v[32:33], v[248:249], v[108:109], v[32:33] op_sel_hi:[0,1,1]
	v_pk_fma_f32 v[22:23], v[248:249], v[108:109], v[22:23] op_sel:[1,0,0] op_sel_hi:[1,1,1]
	v_pk_fma_f32 v[16:17], v[250:251], v[108:109], v[16:17] op_sel_hi:[0,1,1]
	v_pk_fma_f32 v[4:5], v[250:251], v[246:247], v[4:5] op_sel:[1,0,0] op_sel_hi:[1,1,1]
	v_pk_fma_f32 v[30:31], v[248:249], v[246:247], v[30:31] op_sel_hi:[0,1,1]
	v_pk_fma_f32 v[20:21], v[248:249], v[246:247], v[20:21] op_sel:[1,0,0] op_sel_hi:[1,1,1]
	v_pk_fma_f32 v[12:13], v[250:251], v[246:247], v[12:13] op_sel_hi:[0,1,1]
	v_pk_fma_f32 v[2:3], v[250:251], v[154:155], v[2:3] op_sel:[1,0,0] op_sel_hi:[1,1,1]
	v_pk_fma_f32 v[26:27], v[248:249], v[154:155], v[26:27] op_sel_hi:[0,1,1]
	v_pk_fma_f32 v[18:19], v[248:249], v[154:155], v[18:19] op_sel:[1,0,0] op_sel_hi:[1,1,1]
	v_pk_fma_f32 v[10:11], v[250:251], v[154:155], v[10:11] op_sel_hi:[0,1,1]
	v_pk_fma_f32 v[0:1], v[250:251], v[156:157], v[0:1] op_sel:[1,0,0] op_sel_hi:[1,1,1]
	v_pk_fma_f32 v[24:25], v[248:249], v[156:157], v[24:25] op_sel_hi:[0,1,1]
	v_pk_fma_f32 v[14:15], v[248:249], v[156:157], v[14:15] op_sel:[1,0,0] op_sel_hi:[1,1,1]
	v_pk_fma_f32 v[6:7], v[250:251], v[156:157], v[6:7] op_sel_hi:[0,1,1]
	ds_read_b128 v[248:251], v112 offset:45824
	s_waitcnt vmcnt(24)
	v_lshlrev_b32_e32 v108, 16, v158
	v_and_b32_e32 v109, 0xffff0000, v158
	v_lshlrev_b32_e32 v246, 16, v159
	v_and_b32_e32 v247, 0xffff0000, v159
	v_lshlrev_b32_e32 v158, 16, v160
	v_and_b32_e32 v159, 0xffff0000, v160
	v_lshlrev_b32_e32 v160, 16, v161
	v_and_b32_e32 v161, 0xffff0000, v161
	s_waitcnt lgkmcnt(1)
	v_pk_fma_f32 v[8:9], v[254:255], v[108:109], v[8:9] op_sel:[1,0,0] op_sel_hi:[1,1,1]
	v_pk_fma_f32 v[32:33], v[252:253], v[108:109], v[32:33] op_sel_hi:[0,1,1]
	v_pk_fma_f32 v[22:23], v[252:253], v[108:109], v[22:23] op_sel:[1,0,0] op_sel_hi:[1,1,1]
	v_pk_fma_f32 v[16:17], v[254:255], v[108:109], v[16:17] op_sel_hi:[0,1,1]
	v_pk_fma_f32 v[4:5], v[254:255], v[246:247], v[4:5] op_sel:[1,0,0] op_sel_hi:[1,1,1]
	v_pk_fma_f32 v[30:31], v[252:253], v[246:247], v[30:31] op_sel_hi:[0,1,1]
	v_pk_fma_f32 v[20:21], v[252:253], v[246:247], v[20:21] op_sel:[1,0,0] op_sel_hi:[1,1,1]
	v_pk_fma_f32 v[12:13], v[254:255], v[246:247], v[12:13] op_sel_hi:[0,1,1]
	v_pk_fma_f32 v[2:3], v[254:255], v[158:159], v[2:3] op_sel:[1,0,0] op_sel_hi:[1,1,1]
	v_pk_fma_f32 v[26:27], v[252:253], v[158:159], v[26:27] op_sel_hi:[0,1,1]
	v_pk_fma_f32 v[18:19], v[252:253], v[158:159], v[18:19] op_sel:[1,0,0] op_sel_hi:[1,1,1]
	v_pk_fma_f32 v[10:11], v[254:255], v[158:159], v[10:11] op_sel_hi:[0,1,1]
	v_pk_fma_f32 v[0:1], v[254:255], v[160:161], v[0:1] op_sel:[1,0,0] op_sel_hi:[1,1,1]
	v_pk_fma_f32 v[24:25], v[252:253], v[160:161], v[24:25] op_sel_hi:[0,1,1]
	v_pk_fma_f32 v[14:15], v[252:253], v[160:161], v[14:15] op_sel:[1,0,0] op_sel_hi:[1,1,1]
	v_pk_fma_f32 v[6:7], v[254:255], v[160:161], v[6:7] op_sel_hi:[0,1,1]
	ds_read_b128 v[252:255], v112 offset:45888
	s_waitcnt vmcnt(23)
	v_lshlrev_b32_e32 v108, 16, v162
	v_and_b32_e32 v109, 0xffff0000, v162
	v_lshlrev_b32_e32 v246, 16, v163
	v_and_b32_e32 v247, 0xffff0000, v163
	v_lshlrev_b32_e32 v162, 16, v164
	v_and_b32_e32 v163, 0xffff0000, v164
	v_lshlrev_b32_e32 v164, 16, v165
	v_and_b32_e32 v165, 0xffff0000, v165
	s_waitcnt lgkmcnt(1)
	v_pk_fma_f32 v[8:9], v[250:251], v[108:109], v[8:9] op_sel:[1,0,0] op_sel_hi:[1,1,1]
	v_pk_fma_f32 v[32:33], v[248:249], v[108:109], v[32:33] op_sel_hi:[0,1,1]
	v_pk_fma_f32 v[22:23], v[248:249], v[108:109], v[22:23] op_sel:[1,0,0] op_sel_hi:[1,1,1]
	v_pk_fma_f32 v[16:17], v[250:251], v[108:109], v[16:17] op_sel_hi:[0,1,1]
	v_pk_fma_f32 v[4:5], v[250:251], v[246:247], v[4:5] op_sel:[1,0,0] op_sel_hi:[1,1,1]
	v_pk_fma_f32 v[30:31], v[248:249], v[246:247], v[30:31] op_sel_hi:[0,1,1]
	v_pk_fma_f32 v[20:21], v[248:249], v[246:247], v[20:21] op_sel:[1,0,0] op_sel_hi:[1,1,1]
	v_pk_fma_f32 v[12:13], v[250:251], v[246:247], v[12:13] op_sel_hi:[0,1,1]
	v_pk_fma_f32 v[2:3], v[250:251], v[162:163], v[2:3] op_sel:[1,0,0] op_sel_hi:[1,1,1]
	v_pk_fma_f32 v[26:27], v[248:249], v[162:163], v[26:27] op_sel_hi:[0,1,1]
	v_pk_fma_f32 v[18:19], v[248:249], v[162:163], v[18:19] op_sel:[1,0,0] op_sel_hi:[1,1,1]
	v_pk_fma_f32 v[10:11], v[250:251], v[162:163], v[10:11] op_sel_hi:[0,1,1]
	v_pk_fma_f32 v[0:1], v[250:251], v[164:165], v[0:1] op_sel:[1,0,0] op_sel_hi:[1,1,1]
	v_pk_fma_f32 v[24:25], v[248:249], v[164:165], v[24:25] op_sel_hi:[0,1,1]
	v_pk_fma_f32 v[14:15], v[248:249], v[164:165], v[14:15] op_sel:[1,0,0] op_sel_hi:[1,1,1]
	v_pk_fma_f32 v[6:7], v[250:251], v[164:165], v[6:7] op_sel_hi:[0,1,1]
	ds_read_b128 v[248:251], v112 offset:45952
	s_waitcnt vmcnt(22)
	v_lshlrev_b32_e32 v108, 16, v166
	v_and_b32_e32 v109, 0xffff0000, v166
	v_lshlrev_b32_e32 v246, 16, v167
	v_and_b32_e32 v247, 0xffff0000, v167
	v_lshlrev_b32_e32 v166, 16, v168
	v_and_b32_e32 v167, 0xffff0000, v168
	v_lshlrev_b32_e32 v168, 16, v169
	v_and_b32_e32 v169, 0xffff0000, v169
	s_waitcnt lgkmcnt(1)
	v_pk_fma_f32 v[8:9], v[254:255], v[108:109], v[8:9] op_sel:[1,0,0] op_sel_hi:[1,1,1]
	v_pk_fma_f32 v[32:33], v[252:253], v[108:109], v[32:33] op_sel_hi:[0,1,1]
	v_pk_fma_f32 v[22:23], v[252:253], v[108:109], v[22:23] op_sel:[1,0,0] op_sel_hi:[1,1,1]
	v_pk_fma_f32 v[16:17], v[254:255], v[108:109], v[16:17] op_sel_hi:[0,1,1]
	v_pk_fma_f32 v[4:5], v[254:255], v[246:247], v[4:5] op_sel:[1,0,0] op_sel_hi:[1,1,1]
	v_pk_fma_f32 v[30:31], v[252:253], v[246:247], v[30:31] op_sel_hi:[0,1,1]
	v_pk_fma_f32 v[20:21], v[252:253], v[246:247], v[20:21] op_sel:[1,0,0] op_sel_hi:[1,1,1]
	v_pk_fma_f32 v[12:13], v[254:255], v[246:247], v[12:13] op_sel_hi:[0,1,1]
	v_pk_fma_f32 v[2:3], v[254:255], v[166:167], v[2:3] op_sel:[1,0,0] op_sel_hi:[1,1,1]
	v_pk_fma_f32 v[26:27], v[252:253], v[166:167], v[26:27] op_sel_hi:[0,1,1]
	v_pk_fma_f32 v[18:19], v[252:253], v[166:167], v[18:19] op_sel:[1,0,0] op_sel_hi:[1,1,1]
	v_pk_fma_f32 v[10:11], v[254:255], v[166:167], v[10:11] op_sel_hi:[0,1,1]
	v_pk_fma_f32 v[0:1], v[254:255], v[168:169], v[0:1] op_sel:[1,0,0] op_sel_hi:[1,1,1]
	v_pk_fma_f32 v[24:25], v[252:253], v[168:169], v[24:25] op_sel_hi:[0,1,1]
	v_pk_fma_f32 v[14:15], v[252:253], v[168:169], v[14:15] op_sel:[1,0,0] op_sel_hi:[1,1,1]
	v_pk_fma_f32 v[6:7], v[254:255], v[168:169], v[6:7] op_sel_hi:[0,1,1]
	ds_read_b128 v[252:255], v112 offset:46016
	s_waitcnt vmcnt(21)
	v_lshlrev_b32_e32 v108, 16, v170
	v_and_b32_e32 v109, 0xffff0000, v170
	v_lshlrev_b32_e32 v246, 16, v171
	v_and_b32_e32 v247, 0xffff0000, v171
	v_lshlrev_b32_e32 v170, 16, v172
	v_and_b32_e32 v171, 0xffff0000, v172
	v_lshlrev_b32_e32 v172, 16, v173
	v_and_b32_e32 v173, 0xffff0000, v173
	s_waitcnt lgkmcnt(1)
	v_pk_fma_f32 v[8:9], v[250:251], v[108:109], v[8:9] op_sel:[1,0,0] op_sel_hi:[1,1,1]
	v_pk_fma_f32 v[32:33], v[248:249], v[108:109], v[32:33] op_sel_hi:[0,1,1]
	v_pk_fma_f32 v[22:23], v[248:249], v[108:109], v[22:23] op_sel:[1,0,0] op_sel_hi:[1,1,1]
	v_pk_fma_f32 v[16:17], v[250:251], v[108:109], v[16:17] op_sel_hi:[0,1,1]
	v_pk_fma_f32 v[4:5], v[250:251], v[246:247], v[4:5] op_sel:[1,0,0] op_sel_hi:[1,1,1]
	v_pk_fma_f32 v[30:31], v[248:249], v[246:247], v[30:31] op_sel_hi:[0,1,1]
	v_pk_fma_f32 v[20:21], v[248:249], v[246:247], v[20:21] op_sel:[1,0,0] op_sel_hi:[1,1,1]
	v_pk_fma_f32 v[12:13], v[250:251], v[246:247], v[12:13] op_sel_hi:[0,1,1]
	v_pk_fma_f32 v[2:3], v[250:251], v[170:171], v[2:3] op_sel:[1,0,0] op_sel_hi:[1,1,1]
	v_pk_fma_f32 v[26:27], v[248:249], v[170:171], v[26:27] op_sel_hi:[0,1,1]
	v_pk_fma_f32 v[18:19], v[248:249], v[170:171], v[18:19] op_sel:[1,0,0] op_sel_hi:[1,1,1]
	v_pk_fma_f32 v[10:11], v[250:251], v[170:171], v[10:11] op_sel_hi:[0,1,1]
	v_pk_fma_f32 v[0:1], v[250:251], v[172:173], v[0:1] op_sel:[1,0,0] op_sel_hi:[1,1,1]
	v_pk_fma_f32 v[24:25], v[248:249], v[172:173], v[24:25] op_sel_hi:[0,1,1]
	v_pk_fma_f32 v[14:15], v[248:249], v[172:173], v[14:15] op_sel:[1,0,0] op_sel_hi:[1,1,1]
	v_pk_fma_f32 v[6:7], v[250:251], v[172:173], v[6:7] op_sel_hi:[0,1,1]
	ds_read_b128 v[248:251], v112 offset:46080
	s_waitcnt vmcnt(20)
	v_lshlrev_b32_e32 v108, 16, v174
	v_and_b32_e32 v109, 0xffff0000, v174
	v_lshlrev_b32_e32 v246, 16, v175
	v_and_b32_e32 v247, 0xffff0000, v175
	v_lshlrev_b32_e32 v174, 16, v176
	v_and_b32_e32 v175, 0xffff0000, v176
	v_lshlrev_b32_e32 v176, 16, v177
	v_and_b32_e32 v177, 0xffff0000, v177
	s_waitcnt lgkmcnt(1)
	v_pk_fma_f32 v[8:9], v[254:255], v[108:109], v[8:9] op_sel:[1,0,0] op_sel_hi:[1,1,1]
	v_pk_fma_f32 v[32:33], v[252:253], v[108:109], v[32:33] op_sel_hi:[0,1,1]
	v_pk_fma_f32 v[22:23], v[252:253], v[108:109], v[22:23] op_sel:[1,0,0] op_sel_hi:[1,1,1]
	v_pk_fma_f32 v[16:17], v[254:255], v[108:109], v[16:17] op_sel_hi:[0,1,1]
	v_pk_fma_f32 v[4:5], v[254:255], v[246:247], v[4:5] op_sel:[1,0,0] op_sel_hi:[1,1,1]
	v_pk_fma_f32 v[30:31], v[252:253], v[246:247], v[30:31] op_sel_hi:[0,1,1]
	v_pk_fma_f32 v[20:21], v[252:253], v[246:247], v[20:21] op_sel:[1,0,0] op_sel_hi:[1,1,1]
	v_pk_fma_f32 v[12:13], v[254:255], v[246:247], v[12:13] op_sel_hi:[0,1,1]
	v_pk_fma_f32 v[2:3], v[254:255], v[174:175], v[2:3] op_sel:[1,0,0] op_sel_hi:[1,1,1]
	v_pk_fma_f32 v[26:27], v[252:253], v[174:175], v[26:27] op_sel_hi:[0,1,1]
	v_pk_fma_f32 v[18:19], v[252:253], v[174:175], v[18:19] op_sel:[1,0,0] op_sel_hi:[1,1,1]
	v_pk_fma_f32 v[10:11], v[254:255], v[174:175], v[10:11] op_sel_hi:[0,1,1]
	v_pk_fma_f32 v[0:1], v[254:255], v[176:177], v[0:1] op_sel:[1,0,0] op_sel_hi:[1,1,1]
	v_pk_fma_f32 v[24:25], v[252:253], v[176:177], v[24:25] op_sel_hi:[0,1,1]
	v_pk_fma_f32 v[14:15], v[252:253], v[176:177], v[14:15] op_sel:[1,0,0] op_sel_hi:[1,1,1]
	v_pk_fma_f32 v[6:7], v[254:255], v[176:177], v[6:7] op_sel_hi:[0,1,1]
	ds_read_b128 v[252:255], v112 offset:46144
	s_waitcnt vmcnt(19)
	v_lshlrev_b32_e32 v108, 16, v178
	v_and_b32_e32 v109, 0xffff0000, v178
	v_lshlrev_b32_e32 v246, 16, v179
	v_and_b32_e32 v247, 0xffff0000, v179
	v_lshlrev_b32_e32 v178, 16, v180
	v_and_b32_e32 v179, 0xffff0000, v180
	v_lshlrev_b32_e32 v180, 16, v181
	v_and_b32_e32 v181, 0xffff0000, v181
	s_waitcnt lgkmcnt(1)
	v_pk_fma_f32 v[8:9], v[250:251], v[108:109], v[8:9] op_sel:[1,0,0] op_sel_hi:[1,1,1]
	v_pk_fma_f32 v[32:33], v[248:249], v[108:109], v[32:33] op_sel_hi:[0,1,1]
	v_pk_fma_f32 v[22:23], v[248:249], v[108:109], v[22:23] op_sel:[1,0,0] op_sel_hi:[1,1,1]
	v_pk_fma_f32 v[16:17], v[250:251], v[108:109], v[16:17] op_sel_hi:[0,1,1]
	v_pk_fma_f32 v[4:5], v[250:251], v[246:247], v[4:5] op_sel:[1,0,0] op_sel_hi:[1,1,1]
	v_pk_fma_f32 v[30:31], v[248:249], v[246:247], v[30:31] op_sel_hi:[0,1,1]
	v_pk_fma_f32 v[20:21], v[248:249], v[246:247], v[20:21] op_sel:[1,0,0] op_sel_hi:[1,1,1]
	v_pk_fma_f32 v[12:13], v[250:251], v[246:247], v[12:13] op_sel_hi:[0,1,1]
	v_pk_fma_f32 v[2:3], v[250:251], v[178:179], v[2:3] op_sel:[1,0,0] op_sel_hi:[1,1,1]
	v_pk_fma_f32 v[26:27], v[248:249], v[178:179], v[26:27] op_sel_hi:[0,1,1]
	v_pk_fma_f32 v[18:19], v[248:249], v[178:179], v[18:19] op_sel:[1,0,0] op_sel_hi:[1,1,1]
	v_pk_fma_f32 v[10:11], v[250:251], v[178:179], v[10:11] op_sel_hi:[0,1,1]
	v_pk_fma_f32 v[0:1], v[250:251], v[180:181], v[0:1] op_sel:[1,0,0] op_sel_hi:[1,1,1]
	v_pk_fma_f32 v[24:25], v[248:249], v[180:181], v[24:25] op_sel_hi:[0,1,1]
	v_pk_fma_f32 v[14:15], v[248:249], v[180:181], v[14:15] op_sel:[1,0,0] op_sel_hi:[1,1,1]
	v_pk_fma_f32 v[6:7], v[250:251], v[180:181], v[6:7] op_sel_hi:[0,1,1]
	ds_read_b128 v[248:251], v112 offset:46208
	s_waitcnt vmcnt(18)
	v_lshlrev_b32_e32 v108, 16, v182
	v_and_b32_e32 v109, 0xffff0000, v182
	v_lshlrev_b32_e32 v246, 16, v183
	v_and_b32_e32 v247, 0xffff0000, v183
	v_lshlrev_b32_e32 v182, 16, v184
	v_and_b32_e32 v183, 0xffff0000, v184
	v_lshlrev_b32_e32 v184, 16, v185
	v_and_b32_e32 v185, 0xffff0000, v185
	s_waitcnt lgkmcnt(1)
	v_pk_fma_f32 v[8:9], v[254:255], v[108:109], v[8:9] op_sel:[1,0,0] op_sel_hi:[1,1,1]
	v_pk_fma_f32 v[32:33], v[252:253], v[108:109], v[32:33] op_sel_hi:[0,1,1]
	v_pk_fma_f32 v[22:23], v[252:253], v[108:109], v[22:23] op_sel:[1,0,0] op_sel_hi:[1,1,1]
	v_pk_fma_f32 v[16:17], v[254:255], v[108:109], v[16:17] op_sel_hi:[0,1,1]
	v_pk_fma_f32 v[4:5], v[254:255], v[246:247], v[4:5] op_sel:[1,0,0] op_sel_hi:[1,1,1]
	v_pk_fma_f32 v[30:31], v[252:253], v[246:247], v[30:31] op_sel_hi:[0,1,1]
	v_pk_fma_f32 v[20:21], v[252:253], v[246:247], v[20:21] op_sel:[1,0,0] op_sel_hi:[1,1,1]
	v_pk_fma_f32 v[12:13], v[254:255], v[246:247], v[12:13] op_sel_hi:[0,1,1]
	v_pk_fma_f32 v[2:3], v[254:255], v[182:183], v[2:3] op_sel:[1,0,0] op_sel_hi:[1,1,1]
	v_pk_fma_f32 v[26:27], v[252:253], v[182:183], v[26:27] op_sel_hi:[0,1,1]
	v_pk_fma_f32 v[18:19], v[252:253], v[182:183], v[18:19] op_sel:[1,0,0] op_sel_hi:[1,1,1]
	v_pk_fma_f32 v[10:11], v[254:255], v[182:183], v[10:11] op_sel_hi:[0,1,1]
	v_pk_fma_f32 v[0:1], v[254:255], v[184:185], v[0:1] op_sel:[1,0,0] op_sel_hi:[1,1,1]
	v_pk_fma_f32 v[24:25], v[252:253], v[184:185], v[24:25] op_sel_hi:[0,1,1]
	v_pk_fma_f32 v[14:15], v[252:253], v[184:185], v[14:15] op_sel:[1,0,0] op_sel_hi:[1,1,1]
	v_pk_fma_f32 v[6:7], v[254:255], v[184:185], v[6:7] op_sel_hi:[0,1,1]
	ds_read_b128 v[252:255], v112 offset:46272
	s_waitcnt vmcnt(17)
	v_lshlrev_b32_e32 v108, 16, v186
	v_and_b32_e32 v109, 0xffff0000, v186
	v_lshlrev_b32_e32 v246, 16, v187
	v_and_b32_e32 v247, 0xffff0000, v187
	v_lshlrev_b32_e32 v186, 16, v188
	v_and_b32_e32 v187, 0xffff0000, v188
	v_lshlrev_b32_e32 v188, 16, v189
	v_and_b32_e32 v189, 0xffff0000, v189
	s_waitcnt lgkmcnt(1)
	v_pk_fma_f32 v[8:9], v[250:251], v[108:109], v[8:9] op_sel:[1,0,0] op_sel_hi:[1,1,1]
	v_pk_fma_f32 v[32:33], v[248:249], v[108:109], v[32:33] op_sel_hi:[0,1,1]
	v_pk_fma_f32 v[22:23], v[248:249], v[108:109], v[22:23] op_sel:[1,0,0] op_sel_hi:[1,1,1]
	v_pk_fma_f32 v[16:17], v[250:251], v[108:109], v[16:17] op_sel_hi:[0,1,1]
	v_pk_fma_f32 v[4:5], v[250:251], v[246:247], v[4:5] op_sel:[1,0,0] op_sel_hi:[1,1,1]
	v_pk_fma_f32 v[30:31], v[248:249], v[246:247], v[30:31] op_sel_hi:[0,1,1]
	v_pk_fma_f32 v[20:21], v[248:249], v[246:247], v[20:21] op_sel:[1,0,0] op_sel_hi:[1,1,1]
	v_pk_fma_f32 v[12:13], v[250:251], v[246:247], v[12:13] op_sel_hi:[0,1,1]
	v_pk_fma_f32 v[2:3], v[250:251], v[186:187], v[2:3] op_sel:[1,0,0] op_sel_hi:[1,1,1]
	v_pk_fma_f32 v[26:27], v[248:249], v[186:187], v[26:27] op_sel_hi:[0,1,1]
	v_pk_fma_f32 v[18:19], v[248:249], v[186:187], v[18:19] op_sel:[1,0,0] op_sel_hi:[1,1,1]
	v_pk_fma_f32 v[10:11], v[250:251], v[186:187], v[10:11] op_sel_hi:[0,1,1]
	v_pk_fma_f32 v[0:1], v[250:251], v[188:189], v[0:1] op_sel:[1,0,0] op_sel_hi:[1,1,1]
	v_pk_fma_f32 v[24:25], v[248:249], v[188:189], v[24:25] op_sel_hi:[0,1,1]
	v_pk_fma_f32 v[14:15], v[248:249], v[188:189], v[14:15] op_sel:[1,0,0] op_sel_hi:[1,1,1]
	v_pk_fma_f32 v[6:7], v[250:251], v[188:189], v[6:7] op_sel_hi:[0,1,1]
	s_waitcnt vmcnt(16)
	v_lshlrev_b32_e32 v108, 16, v190
	v_and_b32_e32 v109, 0xffff0000, v190
	v_lshlrev_b32_e32 v246, 16, v191
	v_and_b32_e32 v247, 0xffff0000, v191
	v_lshlrev_b32_e32 v190, 16, v192
	v_and_b32_e32 v191, 0xffff0000, v192
	v_lshlrev_b32_e32 v192, 16, v193
	v_and_b32_e32 v193, 0xffff0000, v193
	s_waitcnt lgkmcnt(0)
	v_pk_fma_f32 v[8:9], v[254:255], v[108:109], v[8:9] op_sel:[1,0,0] op_sel_hi:[1,1,1]
	v_pk_fma_f32 v[32:33], v[252:253], v[108:109], v[32:33] op_sel_hi:[0,1,1]
	v_pk_fma_f32 v[22:23], v[252:253], v[108:109], v[22:23] op_sel:[1,0,0] op_sel_hi:[1,1,1]
	v_pk_fma_f32 v[16:17], v[254:255], v[108:109], v[16:17] op_sel_hi:[0,1,1]
	v_pk_fma_f32 v[4:5], v[254:255], v[246:247], v[4:5] op_sel:[1,0,0] op_sel_hi:[1,1,1]
	v_pk_fma_f32 v[30:31], v[252:253], v[246:247], v[30:31] op_sel_hi:[0,1,1]
	v_pk_fma_f32 v[20:21], v[252:253], v[246:247], v[20:21] op_sel:[1,0,0] op_sel_hi:[1,1,1]
	v_pk_fma_f32 v[12:13], v[254:255], v[246:247], v[12:13] op_sel_hi:[0,1,1]
	v_pk_fma_f32 v[2:3], v[254:255], v[190:191], v[2:3] op_sel:[1,0,0] op_sel_hi:[1,1,1]
	v_pk_fma_f32 v[26:27], v[252:253], v[190:191], v[26:27] op_sel_hi:[0,1,1]
	v_pk_fma_f32 v[18:19], v[252:253], v[190:191], v[18:19] op_sel:[1,0,0] op_sel_hi:[1,1,1]
	v_pk_fma_f32 v[10:11], v[254:255], v[190:191], v[10:11] op_sel_hi:[0,1,1]
	v_pk_fma_f32 v[0:1], v[254:255], v[192:193], v[0:1] op_sel:[1,0,0] op_sel_hi:[1,1,1]
	v_pk_fma_f32 v[24:25], v[252:253], v[192:193], v[24:25] op_sel_hi:[0,1,1]
	v_pk_fma_f32 v[14:15], v[252:253], v[192:193], v[14:15] op_sel:[1,0,0] op_sel_hi:[1,1,1]
	v_pk_fma_f32 v[6:7], v[254:255], v[192:193], v[6:7] op_sel_hi:[0,1,1]
	ds_read_b128 v[248:251], v112 offset:46336
	ds_read_b128 v[252:255], v112 offset:46400
	s_waitcnt vmcnt(15)
	v_lshlrev_b32_e32 v108, 16, v210
	v_and_b32_e32 v109, 0xffff0000, v210
	v_lshlrev_b32_e32 v246, 16, v211
	v_and_b32_e32 v247, 0xffff0000, v211
	v_lshlrev_b32_e32 v210, 16, v212
	v_and_b32_e32 v211, 0xffff0000, v212
	v_lshlrev_b32_e32 v212, 16, v213
	v_and_b32_e32 v213, 0xffff0000, v213
	s_waitcnt lgkmcnt(1)
	v_pk_fma_f32 v[8:9], v[250:251], v[108:109], v[8:9] op_sel:[1,0,0] op_sel_hi:[1,1,1]
	v_pk_fma_f32 v[32:33], v[248:249], v[108:109], v[32:33] op_sel_hi:[0,1,1]
	v_pk_fma_f32 v[22:23], v[248:249], v[108:109], v[22:23] op_sel:[1,0,0] op_sel_hi:[1,1,1]
	v_pk_fma_f32 v[16:17], v[250:251], v[108:109], v[16:17] op_sel_hi:[0,1,1]
	v_pk_fma_f32 v[4:5], v[250:251], v[246:247], v[4:5] op_sel:[1,0,0] op_sel_hi:[1,1,1]
	v_pk_fma_f32 v[30:31], v[248:249], v[246:247], v[30:31] op_sel_hi:[0,1,1]
	v_pk_fma_f32 v[20:21], v[248:249], v[246:247], v[20:21] op_sel:[1,0,0] op_sel_hi:[1,1,1]
	v_pk_fma_f32 v[12:13], v[250:251], v[246:247], v[12:13] op_sel_hi:[0,1,1]
	v_pk_fma_f32 v[2:3], v[250:251], v[210:211], v[2:3] op_sel:[1,0,0] op_sel_hi:[1,1,1]
	v_pk_fma_f32 v[26:27], v[248:249], v[210:211], v[26:27] op_sel_hi:[0,1,1]
	v_pk_fma_f32 v[18:19], v[248:249], v[210:211], v[18:19] op_sel:[1,0,0] op_sel_hi:[1,1,1]
	v_pk_fma_f32 v[10:11], v[250:251], v[210:211], v[10:11] op_sel_hi:[0,1,1]
	v_pk_fma_f32 v[0:1], v[250:251], v[212:213], v[0:1] op_sel:[1,0,0] op_sel_hi:[1,1,1]
	v_pk_fma_f32 v[24:25], v[248:249], v[212:213], v[24:25] op_sel_hi:[0,1,1]
	v_pk_fma_f32 v[14:15], v[248:249], v[212:213], v[14:15] op_sel:[1,0,0] op_sel_hi:[1,1,1]
	v_pk_fma_f32 v[6:7], v[250:251], v[212:213], v[6:7] op_sel_hi:[0,1,1]
	ds_read_b128 v[248:251], v112 offset:46464
	s_waitcnt vmcnt(14)
	v_lshlrev_b32_e32 v108, 16, v214
	v_and_b32_e32 v109, 0xffff0000, v214
	v_lshlrev_b32_e32 v246, 16, v215
	v_and_b32_e32 v247, 0xffff0000, v215
	v_lshlrev_b32_e32 v214, 16, v216
	v_and_b32_e32 v215, 0xffff0000, v216
	v_lshlrev_b32_e32 v216, 16, v217
	v_and_b32_e32 v217, 0xffff0000, v217
	s_waitcnt lgkmcnt(1)
	v_pk_fma_f32 v[8:9], v[254:255], v[108:109], v[8:9] op_sel:[1,0,0] op_sel_hi:[1,1,1]
	v_pk_fma_f32 v[32:33], v[252:253], v[108:109], v[32:33] op_sel_hi:[0,1,1]
	v_pk_fma_f32 v[22:23], v[252:253], v[108:109], v[22:23] op_sel:[1,0,0] op_sel_hi:[1,1,1]
	v_pk_fma_f32 v[16:17], v[254:255], v[108:109], v[16:17] op_sel_hi:[0,1,1]
	v_pk_fma_f32 v[4:5], v[254:255], v[246:247], v[4:5] op_sel:[1,0,0] op_sel_hi:[1,1,1]
	v_pk_fma_f32 v[30:31], v[252:253], v[246:247], v[30:31] op_sel_hi:[0,1,1]
	v_pk_fma_f32 v[20:21], v[252:253], v[246:247], v[20:21] op_sel:[1,0,0] op_sel_hi:[1,1,1]
	v_pk_fma_f32 v[12:13], v[254:255], v[246:247], v[12:13] op_sel_hi:[0,1,1]
	v_pk_fma_f32 v[2:3], v[254:255], v[214:215], v[2:3] op_sel:[1,0,0] op_sel_hi:[1,1,1]
	v_pk_fma_f32 v[26:27], v[252:253], v[214:215], v[26:27] op_sel_hi:[0,1,1]
	v_pk_fma_f32 v[18:19], v[252:253], v[214:215], v[18:19] op_sel:[1,0,0] op_sel_hi:[1,1,1]
	v_pk_fma_f32 v[10:11], v[254:255], v[214:215], v[10:11] op_sel_hi:[0,1,1]
	v_pk_fma_f32 v[0:1], v[254:255], v[216:217], v[0:1] op_sel:[1,0,0] op_sel_hi:[1,1,1]
	v_pk_fma_f32 v[24:25], v[252:253], v[216:217], v[24:25] op_sel_hi:[0,1,1]
	v_pk_fma_f32 v[14:15], v[252:253], v[216:217], v[14:15] op_sel:[1,0,0] op_sel_hi:[1,1,1]
	v_pk_fma_f32 v[6:7], v[254:255], v[216:217], v[6:7] op_sel_hi:[0,1,1]
	ds_read_b128 v[252:255], v112 offset:46528
	s_waitcnt vmcnt(13)
	v_lshlrev_b32_e32 v108, 16, v218
	v_and_b32_e32 v109, 0xffff0000, v218
	v_lshlrev_b32_e32 v246, 16, v219
	v_and_b32_e32 v247, 0xffff0000, v219
	v_lshlrev_b32_e32 v218, 16, v220
	v_and_b32_e32 v219, 0xffff0000, v220
	v_lshlrev_b32_e32 v220, 16, v221
	v_and_b32_e32 v221, 0xffff0000, v221
	s_waitcnt lgkmcnt(1)
	v_pk_fma_f32 v[8:9], v[250:251], v[108:109], v[8:9] op_sel:[1,0,0] op_sel_hi:[1,1,1]
	v_pk_fma_f32 v[32:33], v[248:249], v[108:109], v[32:33] op_sel_hi:[0,1,1]
	v_pk_fma_f32 v[22:23], v[248:249], v[108:109], v[22:23] op_sel:[1,0,0] op_sel_hi:[1,1,1]
	v_pk_fma_f32 v[16:17], v[250:251], v[108:109], v[16:17] op_sel_hi:[0,1,1]
	v_pk_fma_f32 v[4:5], v[250:251], v[246:247], v[4:5] op_sel:[1,0,0] op_sel_hi:[1,1,1]
	v_pk_fma_f32 v[30:31], v[248:249], v[246:247], v[30:31] op_sel_hi:[0,1,1]
	v_pk_fma_f32 v[20:21], v[248:249], v[246:247], v[20:21] op_sel:[1,0,0] op_sel_hi:[1,1,1]
	v_pk_fma_f32 v[12:13], v[250:251], v[246:247], v[12:13] op_sel_hi:[0,1,1]
	v_pk_fma_f32 v[2:3], v[250:251], v[218:219], v[2:3] op_sel:[1,0,0] op_sel_hi:[1,1,1]
	v_pk_fma_f32 v[26:27], v[248:249], v[218:219], v[26:27] op_sel_hi:[0,1,1]
	v_pk_fma_f32 v[18:19], v[248:249], v[218:219], v[18:19] op_sel:[1,0,0] op_sel_hi:[1,1,1]
	v_pk_fma_f32 v[10:11], v[250:251], v[218:219], v[10:11] op_sel_hi:[0,1,1]
	v_pk_fma_f32 v[0:1], v[250:251], v[220:221], v[0:1] op_sel:[1,0,0] op_sel_hi:[1,1,1]
	v_pk_fma_f32 v[24:25], v[248:249], v[220:221], v[24:25] op_sel_hi:[0,1,1]
	v_pk_fma_f32 v[14:15], v[248:249], v[220:221], v[14:15] op_sel:[1,0,0] op_sel_hi:[1,1,1]
	v_pk_fma_f32 v[6:7], v[250:251], v[220:221], v[6:7] op_sel_hi:[0,1,1]
	ds_read_b128 v[248:251], v112 offset:46592
	s_waitcnt vmcnt(12)
	v_lshlrev_b32_e32 v108, 16, v222
	v_and_b32_e32 v109, 0xffff0000, v222
	v_lshlrev_b32_e32 v246, 16, v223
	v_and_b32_e32 v247, 0xffff0000, v223
	v_lshlrev_b32_e32 v222, 16, v224
	v_and_b32_e32 v223, 0xffff0000, v224
	v_lshlrev_b32_e32 v224, 16, v225
	v_and_b32_e32 v225, 0xffff0000, v225
	s_waitcnt lgkmcnt(1)
	v_pk_fma_f32 v[8:9], v[254:255], v[108:109], v[8:9] op_sel:[1,0,0] op_sel_hi:[1,1,1]
	v_pk_fma_f32 v[32:33], v[252:253], v[108:109], v[32:33] op_sel_hi:[0,1,1]
	v_pk_fma_f32 v[22:23], v[252:253], v[108:109], v[22:23] op_sel:[1,0,0] op_sel_hi:[1,1,1]
	v_pk_fma_f32 v[16:17], v[254:255], v[108:109], v[16:17] op_sel_hi:[0,1,1]
	v_pk_fma_f32 v[4:5], v[254:255], v[246:247], v[4:5] op_sel:[1,0,0] op_sel_hi:[1,1,1]
	v_pk_fma_f32 v[30:31], v[252:253], v[246:247], v[30:31] op_sel_hi:[0,1,1]
	v_pk_fma_f32 v[20:21], v[252:253], v[246:247], v[20:21] op_sel:[1,0,0] op_sel_hi:[1,1,1]
	v_pk_fma_f32 v[12:13], v[254:255], v[246:247], v[12:13] op_sel_hi:[0,1,1]
	v_pk_fma_f32 v[2:3], v[254:255], v[222:223], v[2:3] op_sel:[1,0,0] op_sel_hi:[1,1,1]
	v_pk_fma_f32 v[26:27], v[252:253], v[222:223], v[26:27] op_sel_hi:[0,1,1]
	v_pk_fma_f32 v[18:19], v[252:253], v[222:223], v[18:19] op_sel:[1,0,0] op_sel_hi:[1,1,1]
	v_pk_fma_f32 v[10:11], v[254:255], v[222:223], v[10:11] op_sel_hi:[0,1,1]
	v_pk_fma_f32 v[0:1], v[254:255], v[224:225], v[0:1] op_sel:[1,0,0] op_sel_hi:[1,1,1]
	v_pk_fma_f32 v[24:25], v[252:253], v[224:225], v[24:25] op_sel_hi:[0,1,1]
	v_pk_fma_f32 v[14:15], v[252:253], v[224:225], v[14:15] op_sel:[1,0,0] op_sel_hi:[1,1,1]
	v_pk_fma_f32 v[6:7], v[254:255], v[224:225], v[6:7] op_sel_hi:[0,1,1]
	ds_read_b128 v[252:255], v112 offset:46656
	s_waitcnt vmcnt(11)
	v_lshlrev_b32_e32 v108, 16, v226
	v_and_b32_e32 v109, 0xffff0000, v226
	v_lshlrev_b32_e32 v246, 16, v227
	v_and_b32_e32 v247, 0xffff0000, v227
	v_lshlrev_b32_e32 v226, 16, v228
	v_and_b32_e32 v227, 0xffff0000, v228
	v_lshlrev_b32_e32 v228, 16, v229
	v_and_b32_e32 v229, 0xffff0000, v229
	s_waitcnt lgkmcnt(1)
	v_pk_fma_f32 v[8:9], v[250:251], v[108:109], v[8:9] op_sel:[1,0,0] op_sel_hi:[1,1,1]
	v_pk_fma_f32 v[32:33], v[248:249], v[108:109], v[32:33] op_sel_hi:[0,1,1]
	v_pk_fma_f32 v[22:23], v[248:249], v[108:109], v[22:23] op_sel:[1,0,0] op_sel_hi:[1,1,1]
	v_pk_fma_f32 v[16:17], v[250:251], v[108:109], v[16:17] op_sel_hi:[0,1,1]
	v_pk_fma_f32 v[4:5], v[250:251], v[246:247], v[4:5] op_sel:[1,0,0] op_sel_hi:[1,1,1]
	v_pk_fma_f32 v[30:31], v[248:249], v[246:247], v[30:31] op_sel_hi:[0,1,1]
	v_pk_fma_f32 v[20:21], v[248:249], v[246:247], v[20:21] op_sel:[1,0,0] op_sel_hi:[1,1,1]
	v_pk_fma_f32 v[12:13], v[250:251], v[246:247], v[12:13] op_sel_hi:[0,1,1]
	v_pk_fma_f32 v[2:3], v[250:251], v[226:227], v[2:3] op_sel:[1,0,0] op_sel_hi:[1,1,1]
	v_pk_fma_f32 v[26:27], v[248:249], v[226:227], v[26:27] op_sel_hi:[0,1,1]
	v_pk_fma_f32 v[18:19], v[248:249], v[226:227], v[18:19] op_sel:[1,0,0] op_sel_hi:[1,1,1]
	v_pk_fma_f32 v[10:11], v[250:251], v[226:227], v[10:11] op_sel_hi:[0,1,1]
	v_pk_fma_f32 v[0:1], v[250:251], v[228:229], v[0:1] op_sel:[1,0,0] op_sel_hi:[1,1,1]
	v_pk_fma_f32 v[24:25], v[248:249], v[228:229], v[24:25] op_sel_hi:[0,1,1]
	v_pk_fma_f32 v[14:15], v[248:249], v[228:229], v[14:15] op_sel:[1,0,0] op_sel_hi:[1,1,1]
	v_pk_fma_f32 v[6:7], v[250:251], v[228:229], v[6:7] op_sel_hi:[0,1,1]
	ds_read_b128 v[248:251], v112 offset:46720
	s_waitcnt vmcnt(10)
	v_lshlrev_b32_e32 v108, 16, v230
	v_and_b32_e32 v109, 0xffff0000, v230
	v_lshlrev_b32_e32 v246, 16, v231
	v_and_b32_e32 v247, 0xffff0000, v231
	v_lshlrev_b32_e32 v230, 16, v232
	v_and_b32_e32 v231, 0xffff0000, v232
	v_lshlrev_b32_e32 v232, 16, v233
	v_and_b32_e32 v233, 0xffff0000, v233
	s_waitcnt lgkmcnt(1)
	v_pk_fma_f32 v[8:9], v[254:255], v[108:109], v[8:9] op_sel:[1,0,0] op_sel_hi:[1,1,1]
	v_pk_fma_f32 v[32:33], v[252:253], v[108:109], v[32:33] op_sel_hi:[0,1,1]
	v_pk_fma_f32 v[22:23], v[252:253], v[108:109], v[22:23] op_sel:[1,0,0] op_sel_hi:[1,1,1]
	v_pk_fma_f32 v[16:17], v[254:255], v[108:109], v[16:17] op_sel_hi:[0,1,1]
	v_pk_fma_f32 v[4:5], v[254:255], v[246:247], v[4:5] op_sel:[1,0,0] op_sel_hi:[1,1,1]
	v_pk_fma_f32 v[30:31], v[252:253], v[246:247], v[30:31] op_sel_hi:[0,1,1]
	v_pk_fma_f32 v[20:21], v[252:253], v[246:247], v[20:21] op_sel:[1,0,0] op_sel_hi:[1,1,1]
	v_pk_fma_f32 v[12:13], v[254:255], v[246:247], v[12:13] op_sel_hi:[0,1,1]
	v_pk_fma_f32 v[2:3], v[254:255], v[230:231], v[2:3] op_sel:[1,0,0] op_sel_hi:[1,1,1]
	v_pk_fma_f32 v[26:27], v[252:253], v[230:231], v[26:27] op_sel_hi:[0,1,1]
	v_pk_fma_f32 v[18:19], v[252:253], v[230:231], v[18:19] op_sel:[1,0,0] op_sel_hi:[1,1,1]
	v_pk_fma_f32 v[10:11], v[254:255], v[230:231], v[10:11] op_sel_hi:[0,1,1]
	v_pk_fma_f32 v[0:1], v[254:255], v[232:233], v[0:1] op_sel:[1,0,0] op_sel_hi:[1,1,1]
	v_pk_fma_f32 v[24:25], v[252:253], v[232:233], v[24:25] op_sel_hi:[0,1,1]
	v_pk_fma_f32 v[14:15], v[252:253], v[232:233], v[14:15] op_sel:[1,0,0] op_sel_hi:[1,1,1]
	v_pk_fma_f32 v[6:7], v[254:255], v[232:233], v[6:7] op_sel_hi:[0,1,1]
	ds_read_b128 v[252:255], v112 offset:46784
	s_waitcnt vmcnt(9)
	v_lshlrev_b32_e32 v108, 16, v234
	v_and_b32_e32 v109, 0xffff0000, v234
	v_lshlrev_b32_e32 v246, 16, v235
	v_and_b32_e32 v247, 0xffff0000, v235
	v_lshlrev_b32_e32 v234, 16, v236
	v_and_b32_e32 v235, 0xffff0000, v236
	v_lshlrev_b32_e32 v236, 16, v237
	v_and_b32_e32 v237, 0xffff0000, v237
	s_waitcnt lgkmcnt(1)
	v_pk_fma_f32 v[8:9], v[250:251], v[108:109], v[8:9] op_sel:[1,0,0] op_sel_hi:[1,1,1]
	v_pk_fma_f32 v[32:33], v[248:249], v[108:109], v[32:33] op_sel_hi:[0,1,1]
	v_pk_fma_f32 v[22:23], v[248:249], v[108:109], v[22:23] op_sel:[1,0,0] op_sel_hi:[1,1,1]
	v_pk_fma_f32 v[16:17], v[250:251], v[108:109], v[16:17] op_sel_hi:[0,1,1]
	v_pk_fma_f32 v[4:5], v[250:251], v[246:247], v[4:5] op_sel:[1,0,0] op_sel_hi:[1,1,1]
	v_pk_fma_f32 v[30:31], v[248:249], v[246:247], v[30:31] op_sel_hi:[0,1,1]
	v_pk_fma_f32 v[20:21], v[248:249], v[246:247], v[20:21] op_sel:[1,0,0] op_sel_hi:[1,1,1]
	v_pk_fma_f32 v[12:13], v[250:251], v[246:247], v[12:13] op_sel_hi:[0,1,1]
	v_pk_fma_f32 v[2:3], v[250:251], v[234:235], v[2:3] op_sel:[1,0,0] op_sel_hi:[1,1,1]
	v_pk_fma_f32 v[26:27], v[248:249], v[234:235], v[26:27] op_sel_hi:[0,1,1]
	v_pk_fma_f32 v[18:19], v[248:249], v[234:235], v[18:19] op_sel:[1,0,0] op_sel_hi:[1,1,1]
	v_pk_fma_f32 v[10:11], v[250:251], v[234:235], v[10:11] op_sel_hi:[0,1,1]
	v_pk_fma_f32 v[0:1], v[250:251], v[236:237], v[0:1] op_sel:[1,0,0] op_sel_hi:[1,1,1]
	v_pk_fma_f32 v[24:25], v[248:249], v[236:237], v[24:25] op_sel_hi:[0,1,1]
	v_pk_fma_f32 v[14:15], v[248:249], v[236:237], v[14:15] op_sel:[1,0,0] op_sel_hi:[1,1,1]
	v_pk_fma_f32 v[6:7], v[250:251], v[236:237], v[6:7] op_sel_hi:[0,1,1]
	ds_read_b128 v[248:251], v112 offset:46848
	s_waitcnt vmcnt(8)
	v_lshlrev_b32_e32 v108, 16, v238
	v_and_b32_e32 v109, 0xffff0000, v238
	v_lshlrev_b32_e32 v246, 16, v239
	v_and_b32_e32 v247, 0xffff0000, v239
	v_lshlrev_b32_e32 v238, 16, v240
	v_and_b32_e32 v239, 0xffff0000, v240
	v_lshlrev_b32_e32 v240, 16, v241
	v_and_b32_e32 v241, 0xffff0000, v241
	s_waitcnt lgkmcnt(1)
	v_pk_fma_f32 v[8:9], v[254:255], v[108:109], v[8:9] op_sel:[1,0,0] op_sel_hi:[1,1,1]
	v_pk_fma_f32 v[32:33], v[252:253], v[108:109], v[32:33] op_sel_hi:[0,1,1]
	v_pk_fma_f32 v[22:23], v[252:253], v[108:109], v[22:23] op_sel:[1,0,0] op_sel_hi:[1,1,1]
	v_pk_fma_f32 v[16:17], v[254:255], v[108:109], v[16:17] op_sel_hi:[0,1,1]
	v_pk_fma_f32 v[4:5], v[254:255], v[246:247], v[4:5] op_sel:[1,0,0] op_sel_hi:[1,1,1]
	v_pk_fma_f32 v[30:31], v[252:253], v[246:247], v[30:31] op_sel_hi:[0,1,1]
	v_pk_fma_f32 v[20:21], v[252:253], v[246:247], v[20:21] op_sel:[1,0,0] op_sel_hi:[1,1,1]
	v_pk_fma_f32 v[12:13], v[254:255], v[246:247], v[12:13] op_sel_hi:[0,1,1]
	v_pk_fma_f32 v[2:3], v[254:255], v[238:239], v[2:3] op_sel:[1,0,0] op_sel_hi:[1,1,1]
	v_pk_fma_f32 v[26:27], v[252:253], v[238:239], v[26:27] op_sel_hi:[0,1,1]
	v_pk_fma_f32 v[18:19], v[252:253], v[238:239], v[18:19] op_sel:[1,0,0] op_sel_hi:[1,1,1]
	v_pk_fma_f32 v[10:11], v[254:255], v[238:239], v[10:11] op_sel_hi:[0,1,1]
	v_pk_fma_f32 v[0:1], v[254:255], v[240:241], v[0:1] op_sel:[1,0,0] op_sel_hi:[1,1,1]
	v_pk_fma_f32 v[24:25], v[252:253], v[240:241], v[24:25] op_sel_hi:[0,1,1]
	v_pk_fma_f32 v[14:15], v[252:253], v[240:241], v[14:15] op_sel:[1,0,0] op_sel_hi:[1,1,1]
	v_pk_fma_f32 v[6:7], v[254:255], v[240:241], v[6:7] op_sel_hi:[0,1,1]
	ds_read_b128 v[252:255], v112 offset:46912
	s_waitcnt vmcnt(7)
	v_lshlrev_b32_e32 v108, 16, v70
	v_and_b32_e32 v109, 0xffff0000, v70
	v_lshlrev_b32_e32 v246, 16, v71
	v_and_b32_e32 v247, 0xffff0000, v71
	v_lshlrev_b32_e32 v70, 16, v72
	v_and_b32_e32 v71, 0xffff0000, v72
	v_lshlrev_b32_e32 v72, 16, v73
	v_and_b32_e32 v73, 0xffff0000, v73
	s_waitcnt lgkmcnt(1)
	v_pk_fma_f32 v[8:9], v[250:251], v[108:109], v[8:9] op_sel:[1,0,0] op_sel_hi:[1,1,1]
	v_pk_fma_f32 v[32:33], v[248:249], v[108:109], v[32:33] op_sel_hi:[0,1,1]
	v_pk_fma_f32 v[22:23], v[248:249], v[108:109], v[22:23] op_sel:[1,0,0] op_sel_hi:[1,1,1]
	v_pk_fma_f32 v[16:17], v[250:251], v[108:109], v[16:17] op_sel_hi:[0,1,1]
	v_pk_fma_f32 v[4:5], v[250:251], v[246:247], v[4:5] op_sel:[1,0,0] op_sel_hi:[1,1,1]
	v_pk_fma_f32 v[30:31], v[248:249], v[246:247], v[30:31] op_sel_hi:[0,1,1]
	v_pk_fma_f32 v[20:21], v[248:249], v[246:247], v[20:21] op_sel:[1,0,0] op_sel_hi:[1,1,1]
	v_pk_fma_f32 v[12:13], v[250:251], v[246:247], v[12:13] op_sel_hi:[0,1,1]
	v_pk_fma_f32 v[2:3], v[250:251], v[70:71], v[2:3] op_sel:[1,0,0] op_sel_hi:[1,1,1]
	v_pk_fma_f32 v[26:27], v[248:249], v[70:71], v[26:27] op_sel_hi:[0,1,1]
	v_pk_fma_f32 v[18:19], v[248:249], v[70:71], v[18:19] op_sel:[1,0,0] op_sel_hi:[1,1,1]
	v_pk_fma_f32 v[10:11], v[250:251], v[70:71], v[10:11] op_sel_hi:[0,1,1]
	v_pk_fma_f32 v[0:1], v[250:251], v[72:73], v[0:1] op_sel:[1,0,0] op_sel_hi:[1,1,1]
	v_pk_fma_f32 v[24:25], v[248:249], v[72:73], v[24:25] op_sel_hi:[0,1,1]
	v_pk_fma_f32 v[14:15], v[248:249], v[72:73], v[14:15] op_sel:[1,0,0] op_sel_hi:[1,1,1]
	v_pk_fma_f32 v[6:7], v[250:251], v[72:73], v[6:7] op_sel_hi:[0,1,1]
	ds_read_b128 v[248:251], v112 offset:46976
	s_waitcnt vmcnt(6)
	v_lshlrev_b32_e32 v108, 16, v74
	v_and_b32_e32 v109, 0xffff0000, v74
	v_lshlrev_b32_e32 v246, 16, v75
	v_and_b32_e32 v247, 0xffff0000, v75
	v_lshlrev_b32_e32 v74, 16, v76
	v_and_b32_e32 v75, 0xffff0000, v76
	v_lshlrev_b32_e32 v76, 16, v77
	v_and_b32_e32 v77, 0xffff0000, v77
	s_waitcnt lgkmcnt(1)
	v_pk_fma_f32 v[8:9], v[254:255], v[108:109], v[8:9] op_sel:[1,0,0] op_sel_hi:[1,1,1]
	v_pk_fma_f32 v[32:33], v[252:253], v[108:109], v[32:33] op_sel_hi:[0,1,1]
	v_pk_fma_f32 v[22:23], v[252:253], v[108:109], v[22:23] op_sel:[1,0,0] op_sel_hi:[1,1,1]
	v_pk_fma_f32 v[16:17], v[254:255], v[108:109], v[16:17] op_sel_hi:[0,1,1]
	v_pk_fma_f32 v[4:5], v[254:255], v[246:247], v[4:5] op_sel:[1,0,0] op_sel_hi:[1,1,1]
	v_pk_fma_f32 v[30:31], v[252:253], v[246:247], v[30:31] op_sel_hi:[0,1,1]
	v_pk_fma_f32 v[20:21], v[252:253], v[246:247], v[20:21] op_sel:[1,0,0] op_sel_hi:[1,1,1]
	v_pk_fma_f32 v[12:13], v[254:255], v[246:247], v[12:13] op_sel_hi:[0,1,1]
	v_pk_fma_f32 v[2:3], v[254:255], v[74:75], v[2:3] op_sel:[1,0,0] op_sel_hi:[1,1,1]
	v_pk_fma_f32 v[26:27], v[252:253], v[74:75], v[26:27] op_sel_hi:[0,1,1]
	v_pk_fma_f32 v[18:19], v[252:253], v[74:75], v[18:19] op_sel:[1,0,0] op_sel_hi:[1,1,1]
	v_pk_fma_f32 v[10:11], v[254:255], v[74:75], v[10:11] op_sel_hi:[0,1,1]
	v_pk_fma_f32 v[0:1], v[254:255], v[76:77], v[0:1] op_sel:[1,0,0] op_sel_hi:[1,1,1]
	v_pk_fma_f32 v[24:25], v[252:253], v[76:77], v[24:25] op_sel_hi:[0,1,1]
	v_pk_fma_f32 v[14:15], v[252:253], v[76:77], v[14:15] op_sel:[1,0,0] op_sel_hi:[1,1,1]
	v_pk_fma_f32 v[6:7], v[254:255], v[76:77], v[6:7] op_sel_hi:[0,1,1]
	ds_read_b128 v[252:255], v112 offset:47040
	s_waitcnt vmcnt(5)
	v_lshlrev_b32_e32 v108, 16, v78
	v_and_b32_e32 v109, 0xffff0000, v78
	v_lshlrev_b32_e32 v246, 16, v79
	v_and_b32_e32 v247, 0xffff0000, v79
	v_lshlrev_b32_e32 v78, 16, v80
	v_and_b32_e32 v79, 0xffff0000, v80
	v_lshlrev_b32_e32 v80, 16, v81
	v_and_b32_e32 v81, 0xffff0000, v81
	s_waitcnt lgkmcnt(1)
	v_pk_fma_f32 v[8:9], v[250:251], v[108:109], v[8:9] op_sel:[1,0,0] op_sel_hi:[1,1,1]
	v_pk_fma_f32 v[32:33], v[248:249], v[108:109], v[32:33] op_sel_hi:[0,1,1]
	v_pk_fma_f32 v[22:23], v[248:249], v[108:109], v[22:23] op_sel:[1,0,0] op_sel_hi:[1,1,1]
	v_pk_fma_f32 v[16:17], v[250:251], v[108:109], v[16:17] op_sel_hi:[0,1,1]
	v_pk_fma_f32 v[4:5], v[250:251], v[246:247], v[4:5] op_sel:[1,0,0] op_sel_hi:[1,1,1]
	v_pk_fma_f32 v[30:31], v[248:249], v[246:247], v[30:31] op_sel_hi:[0,1,1]
	v_pk_fma_f32 v[20:21], v[248:249], v[246:247], v[20:21] op_sel:[1,0,0] op_sel_hi:[1,1,1]
	v_pk_fma_f32 v[12:13], v[250:251], v[246:247], v[12:13] op_sel_hi:[0,1,1]
	v_pk_fma_f32 v[2:3], v[250:251], v[78:79], v[2:3] op_sel:[1,0,0] op_sel_hi:[1,1,1]
	v_pk_fma_f32 v[26:27], v[248:249], v[78:79], v[26:27] op_sel_hi:[0,1,1]
	v_pk_fma_f32 v[18:19], v[248:249], v[78:79], v[18:19] op_sel:[1,0,0] op_sel_hi:[1,1,1]
	v_pk_fma_f32 v[10:11], v[250:251], v[78:79], v[10:11] op_sel_hi:[0,1,1]
	v_pk_fma_f32 v[0:1], v[250:251], v[80:81], v[0:1] op_sel:[1,0,0] op_sel_hi:[1,1,1]
	v_pk_fma_f32 v[24:25], v[248:249], v[80:81], v[24:25] op_sel_hi:[0,1,1]
	v_pk_fma_f32 v[14:15], v[248:249], v[80:81], v[14:15] op_sel:[1,0,0] op_sel_hi:[1,1,1]
	v_pk_fma_f32 v[6:7], v[250:251], v[80:81], v[6:7] op_sel_hi:[0,1,1]
	ds_read_b128 v[248:251], v112 offset:47104
	s_waitcnt vmcnt(4)
	v_lshlrev_b32_e32 v108, 16, v82
	v_and_b32_e32 v109, 0xffff0000, v82
	v_lshlrev_b32_e32 v246, 16, v83
	v_and_b32_e32 v247, 0xffff0000, v83
	v_lshlrev_b32_e32 v82, 16, v84
	v_and_b32_e32 v83, 0xffff0000, v84
	v_lshlrev_b32_e32 v84, 16, v85
	v_and_b32_e32 v85, 0xffff0000, v85
	s_waitcnt lgkmcnt(1)
	v_pk_fma_f32 v[8:9], v[254:255], v[108:109], v[8:9] op_sel:[1,0,0] op_sel_hi:[1,1,1]
	v_pk_fma_f32 v[32:33], v[252:253], v[108:109], v[32:33] op_sel_hi:[0,1,1]
	v_pk_fma_f32 v[22:23], v[252:253], v[108:109], v[22:23] op_sel:[1,0,0] op_sel_hi:[1,1,1]
	v_pk_fma_f32 v[16:17], v[254:255], v[108:109], v[16:17] op_sel_hi:[0,1,1]
	v_pk_fma_f32 v[4:5], v[254:255], v[246:247], v[4:5] op_sel:[1,0,0] op_sel_hi:[1,1,1]
	v_pk_fma_f32 v[30:31], v[252:253], v[246:247], v[30:31] op_sel_hi:[0,1,1]
	v_pk_fma_f32 v[20:21], v[252:253], v[246:247], v[20:21] op_sel:[1,0,0] op_sel_hi:[1,1,1]
	v_pk_fma_f32 v[12:13], v[254:255], v[246:247], v[12:13] op_sel_hi:[0,1,1]
	v_pk_fma_f32 v[2:3], v[254:255], v[82:83], v[2:3] op_sel:[1,0,0] op_sel_hi:[1,1,1]
	v_pk_fma_f32 v[26:27], v[252:253], v[82:83], v[26:27] op_sel_hi:[0,1,1]
	v_pk_fma_f32 v[18:19], v[252:253], v[82:83], v[18:19] op_sel:[1,0,0] op_sel_hi:[1,1,1]
	v_pk_fma_f32 v[10:11], v[254:255], v[82:83], v[10:11] op_sel_hi:[0,1,1]
	v_pk_fma_f32 v[0:1], v[254:255], v[84:85], v[0:1] op_sel:[1,0,0] op_sel_hi:[1,1,1]
	v_pk_fma_f32 v[24:25], v[252:253], v[84:85], v[24:25] op_sel_hi:[0,1,1]
	v_pk_fma_f32 v[14:15], v[252:253], v[84:85], v[14:15] op_sel:[1,0,0] op_sel_hi:[1,1,1]
	v_pk_fma_f32 v[6:7], v[254:255], v[84:85], v[6:7] op_sel_hi:[0,1,1]
	ds_read_b128 v[252:255], v112 offset:47168
	s_waitcnt vmcnt(3)
	v_lshlrev_b32_e32 v108, 16, v86
	v_and_b32_e32 v109, 0xffff0000, v86
	v_lshlrev_b32_e32 v246, 16, v87
	v_and_b32_e32 v247, 0xffff0000, v87
	v_lshlrev_b32_e32 v86, 16, v88
	v_and_b32_e32 v87, 0xffff0000, v88
	v_lshlrev_b32_e32 v88, 16, v89
	v_and_b32_e32 v89, 0xffff0000, v89
	s_waitcnt lgkmcnt(1)
	v_pk_fma_f32 v[8:9], v[250:251], v[108:109], v[8:9] op_sel:[1,0,0] op_sel_hi:[1,1,1]
	v_pk_fma_f32 v[32:33], v[248:249], v[108:109], v[32:33] op_sel_hi:[0,1,1]
	v_pk_fma_f32 v[22:23], v[248:249], v[108:109], v[22:23] op_sel:[1,0,0] op_sel_hi:[1,1,1]
	v_pk_fma_f32 v[16:17], v[250:251], v[108:109], v[16:17] op_sel_hi:[0,1,1]
	v_pk_fma_f32 v[4:5], v[250:251], v[246:247], v[4:5] op_sel:[1,0,0] op_sel_hi:[1,1,1]
	v_pk_fma_f32 v[30:31], v[248:249], v[246:247], v[30:31] op_sel_hi:[0,1,1]
	v_pk_fma_f32 v[20:21], v[248:249], v[246:247], v[20:21] op_sel:[1,0,0] op_sel_hi:[1,1,1]
	v_pk_fma_f32 v[12:13], v[250:251], v[246:247], v[12:13] op_sel_hi:[0,1,1]
	v_pk_fma_f32 v[2:3], v[250:251], v[86:87], v[2:3] op_sel:[1,0,0] op_sel_hi:[1,1,1]
	v_pk_fma_f32 v[26:27], v[248:249], v[86:87], v[26:27] op_sel_hi:[0,1,1]
	v_pk_fma_f32 v[18:19], v[248:249], v[86:87], v[18:19] op_sel:[1,0,0] op_sel_hi:[1,1,1]
	v_pk_fma_f32 v[10:11], v[250:251], v[86:87], v[10:11] op_sel_hi:[0,1,1]
	v_pk_fma_f32 v[0:1], v[250:251], v[88:89], v[0:1] op_sel:[1,0,0] op_sel_hi:[1,1,1]
	v_pk_fma_f32 v[24:25], v[248:249], v[88:89], v[24:25] op_sel_hi:[0,1,1]
	v_pk_fma_f32 v[14:15], v[248:249], v[88:89], v[14:15] op_sel:[1,0,0] op_sel_hi:[1,1,1]
	v_pk_fma_f32 v[6:7], v[250:251], v[88:89], v[6:7] op_sel_hi:[0,1,1]
	ds_read_b128 v[248:251], v112 offset:47232
	s_waitcnt vmcnt(2)
	v_lshlrev_b32_e32 v108, 16, v90
	v_and_b32_e32 v109, 0xffff0000, v90
	v_lshlrev_b32_e32 v246, 16, v91
	v_and_b32_e32 v247, 0xffff0000, v91
	v_lshlrev_b32_e32 v90, 16, v92
	v_and_b32_e32 v91, 0xffff0000, v92
	v_lshlrev_b32_e32 v92, 16, v93
	v_and_b32_e32 v93, 0xffff0000, v93
	s_waitcnt lgkmcnt(1)
	v_pk_fma_f32 v[8:9], v[254:255], v[108:109], v[8:9] op_sel:[1,0,0] op_sel_hi:[1,1,1]
	v_pk_fma_f32 v[32:33], v[252:253], v[108:109], v[32:33] op_sel_hi:[0,1,1]
	v_pk_fma_f32 v[22:23], v[252:253], v[108:109], v[22:23] op_sel:[1,0,0] op_sel_hi:[1,1,1]
	v_pk_fma_f32 v[16:17], v[254:255], v[108:109], v[16:17] op_sel_hi:[0,1,1]
	v_pk_fma_f32 v[4:5], v[254:255], v[246:247], v[4:5] op_sel:[1,0,0] op_sel_hi:[1,1,1]
	v_pk_fma_f32 v[30:31], v[252:253], v[246:247], v[30:31] op_sel_hi:[0,1,1]
	v_pk_fma_f32 v[20:21], v[252:253], v[246:247], v[20:21] op_sel:[1,0,0] op_sel_hi:[1,1,1]
	v_pk_fma_f32 v[12:13], v[254:255], v[246:247], v[12:13] op_sel_hi:[0,1,1]
	v_pk_fma_f32 v[2:3], v[254:255], v[90:91], v[2:3] op_sel:[1,0,0] op_sel_hi:[1,1,1]
	v_pk_fma_f32 v[26:27], v[252:253], v[90:91], v[26:27] op_sel_hi:[0,1,1]
	v_pk_fma_f32 v[18:19], v[252:253], v[90:91], v[18:19] op_sel:[1,0,0] op_sel_hi:[1,1,1]
	v_pk_fma_f32 v[10:11], v[254:255], v[90:91], v[10:11] op_sel_hi:[0,1,1]
	v_pk_fma_f32 v[0:1], v[254:255], v[92:93], v[0:1] op_sel:[1,0,0] op_sel_hi:[1,1,1]
	v_pk_fma_f32 v[24:25], v[252:253], v[92:93], v[24:25] op_sel_hi:[0,1,1]
	v_pk_fma_f32 v[14:15], v[252:253], v[92:93], v[14:15] op_sel:[1,0,0] op_sel_hi:[1,1,1]
	v_pk_fma_f32 v[6:7], v[254:255], v[92:93], v[6:7] op_sel_hi:[0,1,1]
	ds_read_b128 v[252:255], v112 offset:47296
	s_waitcnt vmcnt(1)
	v_lshlrev_b32_e32 v108, 16, v94
	v_and_b32_e32 v109, 0xffff0000, v94
	v_lshlrev_b32_e32 v246, 16, v95
	v_and_b32_e32 v247, 0xffff0000, v95
	v_lshlrev_b32_e32 v94, 16, v96
	v_and_b32_e32 v95, 0xffff0000, v96
	v_lshlrev_b32_e32 v96, 16, v97
	v_and_b32_e32 v97, 0xffff0000, v97
	s_waitcnt lgkmcnt(1)
	v_pk_fma_f32 v[8:9], v[250:251], v[108:109], v[8:9] op_sel:[1,0,0] op_sel_hi:[1,1,1]
	v_pk_fma_f32 v[32:33], v[248:249], v[108:109], v[32:33] op_sel_hi:[0,1,1]
	v_pk_fma_f32 v[22:23], v[248:249], v[108:109], v[22:23] op_sel:[1,0,0] op_sel_hi:[1,1,1]
	v_pk_fma_f32 v[16:17], v[250:251], v[108:109], v[16:17] op_sel_hi:[0,1,1]
	v_pk_fma_f32 v[4:5], v[250:251], v[246:247], v[4:5] op_sel:[1,0,0] op_sel_hi:[1,1,1]
	v_pk_fma_f32 v[30:31], v[248:249], v[246:247], v[30:31] op_sel_hi:[0,1,1]
	v_pk_fma_f32 v[20:21], v[248:249], v[246:247], v[20:21] op_sel:[1,0,0] op_sel_hi:[1,1,1]
	v_pk_fma_f32 v[12:13], v[250:251], v[246:247], v[12:13] op_sel_hi:[0,1,1]
	v_pk_fma_f32 v[2:3], v[250:251], v[94:95], v[2:3] op_sel:[1,0,0] op_sel_hi:[1,1,1]
	v_pk_fma_f32 v[26:27], v[248:249], v[94:95], v[26:27] op_sel_hi:[0,1,1]
	v_pk_fma_f32 v[18:19], v[248:249], v[94:95], v[18:19] op_sel:[1,0,0] op_sel_hi:[1,1,1]
	v_pk_fma_f32 v[10:11], v[250:251], v[94:95], v[10:11] op_sel_hi:[0,1,1]
	v_pk_fma_f32 v[0:1], v[250:251], v[96:97], v[0:1] op_sel:[1,0,0] op_sel_hi:[1,1,1]
	v_pk_fma_f32 v[24:25], v[248:249], v[96:97], v[24:25] op_sel_hi:[0,1,1]
	v_pk_fma_f32 v[14:15], v[248:249], v[96:97], v[14:15] op_sel:[1,0,0] op_sel_hi:[1,1,1]
	v_pk_fma_f32 v[6:7], v[250:251], v[96:97], v[6:7] op_sel_hi:[0,1,1]
	s_waitcnt vmcnt(0)
	v_lshlrev_b32_e32 v108, 16, v98
	v_and_b32_e32 v109, 0xffff0000, v98
	v_lshlrev_b32_e32 v246, 16, v99
	v_and_b32_e32 v247, 0xffff0000, v99
	v_lshlrev_b32_e32 v98, 16, v100
	v_and_b32_e32 v99, 0xffff0000, v100
	v_lshlrev_b32_e32 v100, 16, v101
	v_and_b32_e32 v101, 0xffff0000, v101
	s_waitcnt lgkmcnt(0)
	v_pk_fma_f32 v[8:9], v[254:255], v[108:109], v[8:9] op_sel:[1,0,0] op_sel_hi:[1,1,1]
	v_pk_fma_f32 v[32:33], v[252:253], v[108:109], v[32:33] op_sel_hi:[0,1,1]
	v_pk_fma_f32 v[22:23], v[252:253], v[108:109], v[22:23] op_sel:[1,0,0] op_sel_hi:[1,1,1]
	v_pk_fma_f32 v[16:17], v[254:255], v[108:109], v[16:17] op_sel_hi:[0,1,1]
	v_pk_fma_f32 v[4:5], v[254:255], v[246:247], v[4:5] op_sel:[1,0,0] op_sel_hi:[1,1,1]
	v_pk_fma_f32 v[30:31], v[252:253], v[246:247], v[30:31] op_sel_hi:[0,1,1]
	v_pk_fma_f32 v[20:21], v[252:253], v[246:247], v[20:21] op_sel:[1,0,0] op_sel_hi:[1,1,1]
	v_pk_fma_f32 v[12:13], v[254:255], v[246:247], v[12:13] op_sel_hi:[0,1,1]
	v_pk_fma_f32 v[2:3], v[254:255], v[98:99], v[2:3] op_sel:[1,0,0] op_sel_hi:[1,1,1]
	v_pk_fma_f32 v[26:27], v[252:253], v[98:99], v[26:27] op_sel_hi:[0,1,1]
	v_pk_fma_f32 v[18:19], v[252:253], v[98:99], v[18:19] op_sel:[1,0,0] op_sel_hi:[1,1,1]
	v_pk_fma_f32 v[10:11], v[254:255], v[98:99], v[10:11] op_sel_hi:[0,1,1]
	v_pk_fma_f32 v[0:1], v[254:255], v[100:101], v[0:1] op_sel:[1,0,0] op_sel_hi:[1,1,1]
	v_pk_fma_f32 v[24:25], v[252:253], v[100:101], v[24:25] op_sel_hi:[0,1,1]
	v_pk_fma_f32 v[14:15], v[252:253], v[100:101], v[14:15] op_sel:[1,0,0] op_sel_hi:[1,1,1]
	v_pk_fma_f32 v[6:7], v[254:255], v[100:101], v[6:7] op_sel_hi:[0,1,1]
	s_branch .LBB0_1536
